# GEMM K loops: pre-barrier vmcnt/lgkmcnt waits merged into one instruction, redundant post-barrier lgkmcnt(0) dropped
# speedup vs baseline: 1.0031x; 1.0031x over previous
; #define STAGE(bufoff, gbase, voff) do { _Pragma("unroll") for (int _i = 0; _i < 2; ++_i) \
;     __builtin_amdgcn_global_load_lds((const unsigned*)((const char*)(gbase) + (voff)[_i]), (LAS unsigned*)(lds + (bufoff) + ldsw + _i * 8192), 16, 0, 0); } while (0)
; #define LDA(dst, b, h) do { _Pragma("unroll") for (int m = 0; m < 4; ++m) _Pragma("unroll") for (int k = 0; k < 2; ++k) dst[m][k] = *(const LAS half8*)(lds + SA(b, h) + aoff + m * 2048 + k * 1024); } while (0)
; #define LDB(dst, b, h) do { _Pragma("unroll") for (int n = 0; n < 2; ++n) _Pragma("unroll") for (int k = 0; k < 2; ++k) dst[n][k] = *(const LAS half8*)(lds + SB(b, h) + boff + n * 2048 + k * 1024); } while (0)
; #define WAIT_V(n) asm volatile("s_waitcnt vmcnt(" #n ")" ::: "memory")
; #define WAIT_L(n) asm volatile("s_waitcnt lgkmcnt(" #n ")" ::: "memory")
; #define BAR __builtin_amdgcn_s_barrier()
; #define SCHED __builtin_amdgcn_sched_barrier(0)
; template <int EPI>
; DI void gemm_phase(const int wid_s, const h16* __restrict__ A, const h16* __restrict__ Bt, const int N, const int K, const EpiArgs ea) {
;     ...
;     int nbrow = brow, nbcol = bcol;
;     if (has_next) TILE_RC(Ln, nbrow, nbcol);
;     const char* nA = (const char*)A + (size_t)nbrow * K * 2;
;     const char* nB = (const char*)Bt + (size_t)nbcol * K * 2;
;     for (int t = 0; t < nt; t += 2) {
;       const bool last = (t == nt - 2);
;       const char* a1 = cA + (size_t)(t + 1) * kstep;
;       const char* a2 = last ? nA : cA + (size_t)(t + 2) * kstep; const char* b2 = last ? nB : cB + (size_t)(t + 2) * kstep;
;       const char* a3 = a2 + kstep; const char* b3 = b2 + kstep;
;       LDB(B0, 0, 0); LDB(B1, 0, 1); SCHED; LDA(At, 0, 0); STAGE(SA(1, 1), a1 + hstep, voffA);
;       WAIT_V(8); WAIT_L(0); BAR; MMA(0, 0, At, B0); MMA(0, 1, At, B1); BAR; SCHED;
;       LDA(At, 0, 1); STAGE(SB(0, 0), b2, voffB); STAGE(SB(0, 1), b2 + hstep, voffB); STAGE(SA(0, 0), a2, voffA);
;       WAIT_V(8); WAIT_L(0); BAR; MMA(1, 0, At, B0); MMA(1, 1, At, B1); BAR; SCHED;
;       LDB(B0, 1, 0); LDB(B1, 1, 1); SCHED; LDA(At, 1, 0); STAGE(SA(0, 1), a2 + hstep, voffA);
;       WAIT_V(8); WAIT_L(0); BAR; MMA(0, 0, At, B0); MMA(0, 1, At, B1); BAR; SCHED;
;       LDA(At, 1, 1); STAGE(SB(1, 0), b3, voffB); STAGE(SB(1, 1), b3 + hstep, voffB); STAGE(SA(1, 0), a3, voffA);
;       WAIT_V(8); WAIT_L(0); BAR; MMA(1, 0, At, B0); MMA(1, 1, At, B1); BAR; SCHED;
.LBB0_121:
	s_mul_i32 s8, s31, 0x1600
	s_mul_hi_i32 s9, s31, 0x1600
	s_add_u32 s8, s28, s8
	s_addc_u32 s9, s29, s9
	s_mul_i32 s10, s38, 0x1600
	v_readlane_b32 s16, v250, 58
	s_mul_hi_i32 s11, s38, 0x1600
	s_add_u32 s41, s16, s10
	v_readlane_b32 s16, v250, 61
	s_addc_u32 s42, s16, s11
	v_readlane_b32 s16, v249, 21
	s_add_u32 s43, s16, s14
	v_readlane_b32 s14, v249, 22
	v_mov_b32_e32 v6, 0
	s_addc_u32 s44, s14, s15
	s_mov_b32 s45, -2
	s_add_u32 s14, s12, 0x100
	s_addc_u32 s15, s13, 0
	s_add_i32 s46, 0, 0x10000
	s_cmp_eq_u32 s45, 40
	s_cselect_b32 s19, s9, s15
	s_cselect_b32 s18, s8, s14
	v_add_u32_e32 v177, s46, v148
	s_cselect_b32 s17, s42, s44
	s_cselect_b32 s16, s41, s43
	s_add_i32 s47, 0, 0x14000
	ds_read_b128 v[144:147], v177
	ds_read_b128 v[152:155], v177 offset:1024
	ds_read_b128 v[178:181], v177 offset:2048
	ds_read_b128 v[182:185], v177 offset:3072
	v_add_u32_e32 v177, s47, v148
	ds_read_b128 v[186:189], v177
	ds_read_b128 v[190:193], v177 offset:1024
	ds_read_b128 v[194:197], v177 offset:2048
	ds_read_b128 v[198:201], v177 offset:3072
	v_lshl_add_u64 v[234:235], s[12:13], 0, v[142:143]
	s_add_i32 m0, s22, 0xc000
	ds_read_b128 v[202:205], v151
	ds_read_b128 v[206:209], v151 offset:1024
	ds_read_b128 v[210:213], v151 offset:2048
	ds_read_b128 v[214:217], v151 offset:3072
	ds_read_b128 v[218:221], v151 offset:4096
	ds_read_b128 v[222:225], v151 offset:5120
	ds_read_b128 v[226:229], v151 offset:6144
	ds_read_b128 v[230:233], v151 offset:7168
	global_load_lds_dwordx4 v[234:235], off
	v_lshl_add_u64 v[234:235], s[12:13], 0, v[140:141]
	s_add_i32 m0, s22, 0xe000
	s_nop 0
	global_load_lds_dwordx4 v[234:235], off
	s_waitcnt vmcnt(8) lgkmcnt(0)
	s_barrier
	v_mfma_f32_16x16x32_f16 v[130:133], v[144:147], v[202:205], 0
	v_mfma_f32_16x16x32_f16 v[126:129], v[178:181], v[202:205], 0
	v_mfma_f32_16x16x32_f16 v[114:117], v[144:147], v[210:213], 0
	v_mfma_f32_16x16x32_f16 v[110:113], v[178:181], v[210:213], 0
	v_mfma_f32_16x16x32_f16 v[98:101], v[144:147], v[218:221], 0
	v_mfma_f32_16x16x32_f16 v[94:97], v[178:181], v[218:221], 0
	v_mfma_f32_16x16x32_f16 v[82:85], v[144:147], v[226:229], 0
	v_mfma_f32_16x16x32_f16 v[78:81], v[178:181], v[226:229], 0
	v_mfma_f32_16x16x32_f16 v[130:133], v[152:155], v[206:209], v[130:133]
	v_mfma_f32_16x16x32_f16 v[126:129], v[182:185], v[206:209], v[126:129]
	v_mfma_f32_16x16x32_f16 v[114:117], v[152:155], v[214:217], v[114:117]
	v_mfma_f32_16x16x32_f16 v[110:113], v[182:185], v[214:217], v[110:113]
	v_mfma_f32_16x16x32_f16 v[98:101], v[152:155], v[222:225], v[98:101]
	v_mfma_f32_16x16x32_f16 v[94:97], v[182:185], v[222:225], v[94:97]
	v_mfma_f32_16x16x32_f16 v[82:85], v[152:155], v[230:233], v[82:85]
	v_mfma_f32_16x16x32_f16 v[78:81], v[182:185], v[230:233], v[78:81]
	v_mfma_f32_16x16x32_f16 v[122:125], v[186:189], v[202:205], 0
	v_mfma_f32_16x16x32_f16 v[118:121], v[194:197], v[202:205], 0
	v_mfma_f32_16x16x32_f16 v[106:109], v[186:189], v[210:213], 0
	v_mfma_f32_16x16x32_f16 v[102:105], v[194:197], v[210:213], 0
	v_mfma_f32_16x16x32_f16 v[90:93], v[186:189], v[218:221], 0
	v_mfma_f32_16x16x32_f16 v[86:89], v[194:197], v[218:221], 0
	v_mfma_f32_16x16x32_f16 v[74:77], v[186:189], v[226:229], 0
	v_mfma_f32_16x16x32_f16 v[70:73], v[194:197], v[226:229], 0
	v_mfma_f32_16x16x32_f16 v[122:125], v[190:193], v[206:209], v[122:125]
	v_mfma_f32_16x16x32_f16 v[118:121], v[198:201], v[206:209], v[118:121]
	v_mfma_f32_16x16x32_f16 v[106:109], v[190:193], v[214:217], v[106:109]
	v_mfma_f32_16x16x32_f16 v[102:105], v[198:201], v[214:217], v[102:105]
	v_mfma_f32_16x16x32_f16 v[90:93], v[190:193], v[222:225], v[90:93]
	v_mfma_f32_16x16x32_f16 v[86:89], v[198:201], v[222:225], v[86:89]
	v_mfma_f32_16x16x32_f16 v[74:77], v[190:193], v[230:233], v[74:77]
	v_mfma_f32_16x16x32_f16 v[70:73], v[198:201], v[230:233], v[70:73]
	s_barrier
	s_add_i32 s12, s46, s21
	v_lshl_add_u64 v[234:235], s[16:17], 0, v[0:1]
	s_mov_b32 m0, s12
	ds_read_b128 v[202:205], v151 offset:16384
	ds_read_b128 v[206:209], v151 offset:17408
	ds_read_b128 v[210:213], v151 offset:18432
	ds_read_b128 v[214:217], v151 offset:19456
	ds_read_b128 v[218:221], v151 offset:20480
	ds_read_b128 v[222:225], v151 offset:21504
	ds_read_b128 v[226:229], v151 offset:22528
	ds_read_b128 v[230:233], v151 offset:23552
	global_load_lds_dwordx4 v[234:235], off
	s_add_i32 m0, s12, 0x2000
	s_add_u32 s12, s16, 0xb0000
	v_lshl_add_u64 v[236:237], s[16:17], 0, v[138:139]
	s_addc_u32 s13, s17, 0
	s_add_i32 s46, s47, s21
	global_load_lds_dwordx4 v[236:237], off
	v_lshl_add_u64 v[238:239], s[12:13], 0, v[0:1]
	s_mov_b32 m0, s46
	v_lshl_add_u64 v[240:241], s[18:19], 0, v[134:135]
	global_load_lds_dwordx4 v[238:239], off
	v_lshl_add_u64 v[238:239], s[12:13], 0, v[138:139]
	s_add_i32 m0, s46, 0x2000
	s_nop 0
	global_load_lds_dwordx4 v[238:239], off
	v_lshl_add_u64 v[238:239], s[18:19], 0, v[2:3]
	s_mov_b32 m0, s22
	s_nop 0
	global_load_lds_dwordx4 v[238:239], off
	s_mov_b32 m0, s23
	s_nop 0
	global_load_lds_dwordx4 v[240:241], off
	s_waitcnt vmcnt(8) lgkmcnt(0)
	s_barrier
; #define STAGE(bufoff, gbase, voff) do { _Pragma("unroll") for (int _i = 0; _i < 2; ++_i) \
;     __builtin_amdgcn_global_load_lds((const unsigned*)((const char*)(gbase) + (voff)[_i]), (LAS unsigned*)(lds + (bufoff) + ldsw + _i * 8192), 16, 0, 0); } while (0)
; #define LDA(dst, b, h) do { _Pragma("unroll") for (int m = 0; m < 4; ++m) _Pragma("unroll") for (int k = 0; k < 2; ++k) dst[m][k] = *(const LAS half8*)(lds + SA(b, h) + aoff + m * 2048 + k * 1024); } while (0)
; #define LDB(dst, b, h) do { _Pragma("unroll") for (int n = 0; n < 2; ++n) _Pragma("unroll") for (int k = 0; k < 2; ++k) dst[n][k] = *(const LAS half8*)(lds + SB(b, h) + boff + n * 2048 + k * 1024); } while (0)
; #define MMA(ai, bj, At_, Bt_) do { __builtin_amdgcn_s_setprio(1); \
;     _Pragma("unroll") for (int m = 0; m < 4; ++m) _Pragma("unroll") for (int n = 0; n < 2; ++n) _Pragma("unroll") for (int k = 0; k < 2; ++k) \
;       acc[ai][bj][m][n] = MFMA16(Bt_[n][k], At_[m][k], acc[ai][bj][m][n]); \
;     __builtin_amdgcn_s_setprio(0); } while (0)
; #define WAIT_V(n) asm volatile("s_waitcnt vmcnt(" #n ")" ::: "memory")
; #define WAIT_L(n) asm volatile("s_waitcnt lgkmcnt(" #n ")" ::: "memory")
; #define BAR __builtin_amdgcn_s_barrier()
; #define SCHED __builtin_amdgcn_sched_barrier(0)
; template <int EPI>
; DI void gemm_phase(const int wid_s, const h16* __restrict__ A, const h16* __restrict__ Bt, const int N, const int K, const EpiArgs ea) {
;     ...
;       LDB(B0, 0, 0); LDB(B1, 0, 1); SCHED; LDA(At, 0, 0); STAGE(SA(1, 1), a1 + hstep, voffA);
;       WAIT_V(8); WAIT_L(0); BAR; MMA(0, 0, At, B0); MMA(0, 1, At, B1); BAR; SCHED;
;       LDA(At, 0, 1); STAGE(SB(0, 0), b2, voffB); STAGE(SB(0, 1), b2 + hstep, voffB); STAGE(SA(0, 0), a2, voffA);
;       WAIT_V(8); WAIT_L(0); BAR; MMA(1, 0, At, B0); MMA(1, 1, At, B1); BAR; SCHED;
;       LDB(B0, 1, 0); LDB(B1, 1, 1); SCHED; LDA(At, 1, 0); STAGE(SA(0, 1), a2 + hstep, voffA);
;       WAIT_V(8); WAIT_L(0); BAR; MMA(0, 0, At, B0); MMA(0, 1, At, B1); BAR; SCHED;
;       LDA(At, 1, 1); STAGE(SB(1, 0), b3, voffB); STAGE(SB(1, 1), b3 + hstep, voffB); STAGE(SA(1, 0), a3, voffA);
;       WAIT_V(8); WAIT_L(0); BAR; MMA(1, 0, At, B0); MMA(1, 1, At, B1); BAR; SCHED;
	v_mfma_f32_16x16x32_f16 v[66:69], v[144:147], v[202:205], 0
	v_mfma_f32_16x16x32_f16 v[62:65], v[178:181], v[202:205], 0
	v_mfma_f32_16x16x32_f16 v[50:53], v[144:147], v[210:213], 0
	v_mfma_f32_16x16x32_f16 v[46:49], v[178:181], v[210:213], 0
	v_mfma_f32_16x16x32_f16 v[34:37], v[144:147], v[218:221], 0
	v_mfma_f32_16x16x32_f16 v[30:33], v[178:181], v[218:221], 0
	v_mfma_f32_16x16x32_f16 v[18:21], v[144:147], v[226:229], 0
	v_mfma_f32_16x16x32_f16 v[14:17], v[178:181], v[226:229], 0
	v_mfma_f32_16x16x32_f16 v[66:69], v[152:155], v[206:209], v[66:69]
	v_mfma_f32_16x16x32_f16 v[62:65], v[182:185], v[206:209], v[62:65]
	v_mfma_f32_16x16x32_f16 v[50:53], v[152:155], v[214:217], v[50:53]
	v_mfma_f32_16x16x32_f16 v[46:49], v[182:185], v[214:217], v[46:49]
	v_mfma_f32_16x16x32_f16 v[34:37], v[152:155], v[222:225], v[34:37]
	v_mfma_f32_16x16x32_f16 v[30:33], v[182:185], v[222:225], v[30:33]
	v_mfma_f32_16x16x32_f16 v[18:21], v[152:155], v[230:233], v[18:21]
	v_mfma_f32_16x16x32_f16 v[14:17], v[182:185], v[230:233], v[14:17]
	v_mfma_f32_16x16x32_f16 v[58:61], v[186:189], v[202:205], 0
	v_mfma_f32_16x16x32_f16 v[54:57], v[194:197], v[202:205], 0
	v_mfma_f32_16x16x32_f16 v[42:45], v[186:189], v[210:213], 0
	v_mfma_f32_16x16x32_f16 v[38:41], v[194:197], v[210:213], 0
	v_mfma_f32_16x16x32_f16 v[26:29], v[186:189], v[218:221], 0
	v_mfma_f32_16x16x32_f16 v[22:25], v[194:197], v[218:221], 0
	v_mfma_f32_16x16x32_f16 v[10:13], v[186:189], v[226:229], 0
	v_mfma_f32_16x16x32_f16 v[6:9], v[194:197], v[226:229], 0
	v_mfma_f32_16x16x32_f16 v[58:61], v[190:193], v[206:209], v[58:61]
	v_mfma_f32_16x16x32_f16 v[54:57], v[198:201], v[206:209], v[54:57]
	v_mfma_f32_16x16x32_f16 v[42:45], v[190:193], v[214:217], v[42:45]
	v_mfma_f32_16x16x32_f16 v[38:41], v[198:201], v[214:217], v[38:41]
	v_mfma_f32_16x16x32_f16 v[26:29], v[190:193], v[222:225], v[26:29]
	v_mfma_f32_16x16x32_f16 v[22:25], v[198:201], v[222:225], v[22:25]
	v_mfma_f32_16x16x32_f16 v[10:13], v[190:193], v[230:233], v[10:13]
	v_mfma_f32_16x16x32_f16 v[6:9], v[198:201], v[230:233], v[6:9]
	s_barrier
	s_add_i32 s46, 0, 0x18000
	v_add_u32_e32 v177, s46, v148
	s_add_i32 s47, 0, 0x1c000
	ds_read_b128 v[144:147], v177
	ds_read_b128 v[152:155], v177 offset:1024
	ds_read_b128 v[178:181], v177 offset:2048
	ds_read_b128 v[182:185], v177 offset:3072
	v_add_u32_e32 v177, s47, v148
	ds_read_b128 v[186:189], v177
	ds_read_b128 v[190:193], v177 offset:1024
	ds_read_b128 v[194:197], v177 offset:2048
	ds_read_b128 v[198:201], v177 offset:3072
	s_add_u32 s12, s18, 0xb0000
	s_addc_u32 s13, s19, 0
	s_mov_b32 m0, s24
	v_lshl_add_u64 v[242:243], s[12:13], 0, v[2:3]
	ds_read_b128 v[202:205], v151 offset:32768
	ds_read_b128 v[206:209], v151 offset:33792
	ds_read_b128 v[210:213], v151 offset:34816
	ds_read_b128 v[214:217], v151 offset:35840
	ds_read_b128 v[218:221], v151 offset:36864
	ds_read_b128 v[222:225], v151 offset:37888
	ds_read_b128 v[226:229], v151 offset:38912
	ds_read_b128 v[230:233], v151 offset:39936
	global_load_lds_dwordx4 v[242:243], off
	v_lshl_add_u64 v[242:243], s[12:13], 0, v[134:135]
	s_mov_b32 m0, s26
	s_nop 0
	global_load_lds_dwordx4 v[242:243], off
	s_waitcnt vmcnt(8) lgkmcnt(0)
	s_barrier
	v_mfma_f32_16x16x32_f16 v[130:133], v[144:147], v[202:205], v[130:133]
	v_mfma_f32_16x16x32_f16 v[126:129], v[178:181], v[202:205], v[126:129]
	v_mfma_f32_16x16x32_f16 v[114:117], v[144:147], v[210:213], v[114:117]
	v_mfma_f32_16x16x32_f16 v[110:113], v[178:181], v[210:213], v[110:113]
	v_mfma_f32_16x16x32_f16 v[98:101], v[144:147], v[218:221], v[98:101]
	v_mfma_f32_16x16x32_f16 v[94:97], v[178:181], v[218:221], v[94:97]
	v_mfma_f32_16x16x32_f16 v[82:85], v[144:147], v[226:229], v[82:85]
	v_mfma_f32_16x16x32_f16 v[78:81], v[178:181], v[226:229], v[78:81]
	v_mfma_f32_16x16x32_f16 v[130:133], v[152:155], v[206:209], v[130:133]
	v_mfma_f32_16x16x32_f16 v[126:129], v[182:185], v[206:209], v[126:129]
	v_mfma_f32_16x16x32_f16 v[114:117], v[152:155], v[214:217], v[114:117]
	v_mfma_f32_16x16x32_f16 v[110:113], v[182:185], v[214:217], v[110:113]
	v_mfma_f32_16x16x32_f16 v[98:101], v[152:155], v[222:225], v[98:101]
	v_mfma_f32_16x16x32_f16 v[94:97], v[182:185], v[222:225], v[94:97]
	v_mfma_f32_16x16x32_f16 v[82:85], v[152:155], v[230:233], v[82:85]
	v_mfma_f32_16x16x32_f16 v[78:81], v[182:185], v[230:233], v[78:81]
	v_mfma_f32_16x16x32_f16 v[122:125], v[186:189], v[202:205], v[122:125]
	v_mfma_f32_16x16x32_f16 v[118:121], v[194:197], v[202:205], v[118:121]
	v_mfma_f32_16x16x32_f16 v[106:109], v[186:189], v[210:213], v[106:109]
	v_mfma_f32_16x16x32_f16 v[102:105], v[194:197], v[210:213], v[102:105]
	v_mfma_f32_16x16x32_f16 v[90:93], v[186:189], v[218:221], v[90:93]
	v_mfma_f32_16x16x32_f16 v[86:89], v[194:197], v[218:221], v[86:89]
	v_mfma_f32_16x16x32_f16 v[74:77], v[186:189], v[226:229], v[74:77]
	v_mfma_f32_16x16x32_f16 v[70:73], v[194:197], v[226:229], v[70:73]
	v_mfma_f32_16x16x32_f16 v[122:125], v[190:193], v[206:209], v[122:125]
	v_mfma_f32_16x16x32_f16 v[118:121], v[198:201], v[206:209], v[118:121]
	v_mfma_f32_16x16x32_f16 v[106:109], v[190:193], v[214:217], v[106:109]
	v_mfma_f32_16x16x32_f16 v[102:105], v[198:201], v[214:217], v[102:105]
	v_mfma_f32_16x16x32_f16 v[90:93], v[190:193], v[222:225], v[90:93]
	v_mfma_f32_16x16x32_f16 v[86:89], v[198:201], v[222:225], v[86:89]
	v_mfma_f32_16x16x32_f16 v[74:77], v[190:193], v[230:233], v[74:77]
	v_mfma_f32_16x16x32_f16 v[70:73], v[198:201], v[230:233], v[70:73]
	s_barrier
; #define STAGE(bufoff, gbase, voff) do { _Pragma("unroll") for (int _i = 0; _i < 2; ++_i) \
;     __builtin_amdgcn_global_load_lds((const unsigned*)((const char*)(gbase) + (voff)[_i]), (LAS unsigned*)(lds + (bufoff) + ldsw + _i * 8192), 16, 0, 0); } while (0)
; #define LDA(dst, b, h) do { _Pragma("unroll") for (int m = 0; m < 4; ++m) _Pragma("unroll") for (int k = 0; k < 2; ++k) dst[m][k] = *(const LAS half8*)(lds + SA(b, h) + aoff + m * 2048 + k * 1024); } while (0)
; #define LDB(dst, b, h) do { _Pragma("unroll") for (int n = 0; n < 2; ++n) _Pragma("unroll") for (int k = 0; k < 2; ++k) dst[n][k] = *(const LAS half8*)(lds + SB(b, h) + boff + n * 2048 + k * 1024); } while (0)
; #define MMA(ai, bj, At_, Bt_) do { __builtin_amdgcn_s_setprio(1); \
;     _Pragma("unroll") for (int m = 0; m < 4; ++m) _Pragma("unroll") for (int n = 0; n < 2; ++n) _Pragma("unroll") for (int k = 0; k < 2; ++k) \
;       acc[ai][bj][m][n] = MFMA16(Bt_[n][k], At_[m][k], acc[ai][bj][m][n]); \
;     __builtin_amdgcn_s_setprio(0); } while (0)
; #define WAIT_V(n) asm volatile("s_waitcnt vmcnt(" #n ")" ::: "memory")
; #define BAR __builtin_amdgcn_s_barrier()
; template <int EPI>
; DI void gemm_phase(const int wid_s, const h16* __restrict__ A, const h16* __restrict__ Bt, const int N, const int K, const EpiArgs ea) {
;     ...
;     for (int t = 0; t < nt; t += 2) {
;       const bool last = (t == nt - 2);
;       const char* a1 = cA + (size_t)(t + 1) * kstep;
;       const char* a2 = last ? nA : cA + (size_t)(t + 2) * kstep; const char* b2 = last ? nB : cB + (size_t)(t + 2) * kstep;
;       const char* a3 = a2 + kstep; const char* b3 = b2 + kstep;
;       LDB(B0, 0, 0); LDB(B1, 0, 1); SCHED; LDA(At, 0, 0); STAGE(SA(1, 1), a1 + hstep, voffA);
;       WAIT_V(8); WAIT_L(0); BAR; MMA(0, 0, At, B0); MMA(0, 1, At, B1); BAR; SCHED;
;       LDA(At, 0, 1); STAGE(SB(0, 0), b2, voffB); STAGE(SB(0, 1), b2 + hstep, voffB); STAGE(SA(0, 0), a2, voffA);
;       WAIT_V(8); WAIT_L(0); BAR; MMA(1, 0, At, B0); MMA(1, 1, At, B1); BAR; SCHED;
;       LDB(B0, 1, 0); LDB(B1, 1, 1); SCHED; LDA(At, 1, 0); STAGE(SA(0, 1), a2 + hstep, voffA);
;       WAIT_V(8); WAIT_L(0); BAR; MMA(0, 0, At, B0); MMA(0, 1, At, B1); BAR; SCHED;
;       LDA(At, 1, 1); STAGE(SB(1, 0), b3, voffB); STAGE(SB(1, 1), b3 + hstep, voffB); STAGE(SA(1, 0), a3, voffA);
;       WAIT_V(8); WAIT_L(0); BAR; MMA(1, 0, At, B0); MMA(1, 1, At, B1); BAR; SCHED;
	s_add_i32 s12, s46, s21
	v_lshl_add_u64 v[234:235], v[234:235], 0, s[36:37]
	s_mov_b32 m0, s12
	ds_read_b128 v[202:205], v151 offset:49152
	ds_read_b128 v[206:209], v151 offset:50176
	ds_read_b128 v[210:213], v151 offset:51200
	ds_read_b128 v[214:217], v151 offset:52224
	ds_read_b128 v[218:221], v151 offset:53248
	ds_read_b128 v[222:225], v151 offset:54272
	ds_read_b128 v[226:229], v151 offset:55296
	ds_read_b128 v[230:233], v151 offset:56320
	global_load_lds_dwordx4 v[234:235], off
	s_add_i32 m0, s12, 0x2000
	s_add_u32 s12, s16, 0xb0080
	v_lshl_add_u64 v[234:235], v[236:237], 0, s[36:37]
	s_addc_u32 s13, s17, 0
	s_add_i32 s16, s47, s21
	global_load_lds_dwordx4 v[234:235], off
	v_lshl_add_u64 v[234:235], s[12:13], 0, v[0:1]
	s_mov_b32 m0, s16
	s_nop 0
	global_load_lds_dwordx4 v[234:235], off
	v_lshl_add_u64 v[234:235], s[12:13], 0, v[138:139]
	s_add_i32 m0, s16, 0x2000
	s_nop 0
	global_load_lds_dwordx4 v[234:235], off
	v_lshl_add_u64 v[234:235], v[238:239], 0, s[36:37]
	s_mov_b32 m0, s27
	s_nop 0
	global_load_lds_dwordx4 v[234:235], off
	v_lshl_add_u64 v[234:235], v[240:241], 0, s[36:37]
	s_mov_b32 m0, s30
	s_nop 0
	global_load_lds_dwordx4 v[234:235], off
	s_waitcnt vmcnt(8) lgkmcnt(0)
	s_barrier
	v_mfma_f32_16x16x32_f16 v[66:69], v[144:147], v[202:205], v[66:69]
	v_mfma_f32_16x16x32_f16 v[62:65], v[178:181], v[202:205], v[62:65]
	v_mfma_f32_16x16x32_f16 v[50:53], v[144:147], v[210:213], v[50:53]
	v_mfma_f32_16x16x32_f16 v[46:49], v[178:181], v[210:213], v[46:49]
	v_mfma_f32_16x16x32_f16 v[34:37], v[144:147], v[218:221], v[34:37]
	v_mfma_f32_16x16x32_f16 v[30:33], v[178:181], v[218:221], v[30:33]
	v_mfma_f32_16x16x32_f16 v[18:21], v[144:147], v[226:229], v[18:21]
	v_mfma_f32_16x16x32_f16 v[14:17], v[178:181], v[226:229], v[14:17]
	v_mfma_f32_16x16x32_f16 v[66:69], v[152:155], v[206:209], v[66:69]
	v_mfma_f32_16x16x32_f16 v[62:65], v[182:185], v[206:209], v[62:65]
	v_mfma_f32_16x16x32_f16 v[50:53], v[152:155], v[214:217], v[50:53]
	v_mfma_f32_16x16x32_f16 v[46:49], v[182:185], v[214:217], v[46:49]
	v_mfma_f32_16x16x32_f16 v[34:37], v[152:155], v[222:225], v[34:37]
	v_mfma_f32_16x16x32_f16 v[30:33], v[182:185], v[222:225], v[30:33]
	v_mfma_f32_16x16x32_f16 v[18:21], v[152:155], v[230:233], v[18:21]
	v_mfma_f32_16x16x32_f16 v[14:17], v[182:185], v[230:233], v[14:17]
	v_mfma_f32_16x16x32_f16 v[58:61], v[186:189], v[202:205], v[58:61]
	v_mfma_f32_16x16x32_f16 v[54:57], v[194:197], v[202:205], v[54:57]
	v_mfma_f32_16x16x32_f16 v[42:45], v[186:189], v[210:213], v[42:45]
	v_mfma_f32_16x16x32_f16 v[38:41], v[194:197], v[210:213], v[38:41]
	v_mfma_f32_16x16x32_f16 v[26:29], v[186:189], v[218:221], v[26:29]
	v_mfma_f32_16x16x32_f16 v[22:25], v[194:197], v[218:221], v[22:25]
	v_mfma_f32_16x16x32_f16 v[10:13], v[186:189], v[226:229], v[10:13]
	v_mfma_f32_16x16x32_f16 v[6:9], v[194:197], v[226:229], v[6:9]
	v_mfma_f32_16x16x32_f16 v[58:61], v[190:193], v[206:209], v[58:61]
	v_mfma_f32_16x16x32_f16 v[54:57], v[198:201], v[206:209], v[54:57]
	v_mfma_f32_16x16x32_f16 v[42:45], v[190:193], v[214:217], v[42:45]
	v_mfma_f32_16x16x32_f16 v[38:41], v[198:201], v[214:217], v[38:41]
	v_mfma_f32_16x16x32_f16 v[26:29], v[190:193], v[222:225], v[26:29]
	v_mfma_f32_16x16x32_f16 v[22:25], v[198:201], v[222:225], v[22:25]
	v_mfma_f32_16x16x32_f16 v[10:13], v[190:193], v[230:233], v[10:13]
	v_mfma_f32_16x16x32_f16 v[6:9], v[198:201], v[230:233], v[6:9]
	s_barrier
	s_add_i32 s45, s45, 2
	s_add_u32 s43, s43, 0x100
	s_addc_u32 s44, s44, 0
	s_cmp_gt_u32 s45, 41
	s_mov_b64 s[12:13], s[14:15]
.LBB0_122:
	s_add_u32 s14, s12, 0x100
	s_addc_u32 s15, s13, 0
	s_add_i32 s46, 0, 0x10000
	s_cmp_eq_u32 s45, 40
	s_cselect_b32 s19, s9, s15
	s_cselect_b32 s18, s8, s14
	v_add_u32_e32 v177, s46, v148
	s_cselect_b32 s17, s42, s44
	s_cselect_b32 s16, s41, s43
	s_add_i32 s47, 0, 0x14000
	ds_read_b128 v[144:147], v177
	ds_read_b128 v[152:155], v177 offset:1024
	ds_read_b128 v[178:181], v177 offset:2048
	ds_read_b128 v[182:185], v177 offset:3072
	v_add_u32_e32 v177, s47, v148
	ds_read_b128 v[186:189], v177
	ds_read_b128 v[190:193], v177 offset:1024
	ds_read_b128 v[194:197], v177 offset:2048
	ds_read_b128 v[198:201], v177 offset:3072
	v_lshl_add_u64 v[234:235], s[12:13], 0, v[142:143]
	s_add_i32 m0, s22, 0xc000
	ds_read_b128 v[202:205], v151
	ds_read_b128 v[206:209], v151 offset:1024
	ds_read_b128 v[210:213], v151 offset:2048
	ds_read_b128 v[214:217], v151 offset:3072
	ds_read_b128 v[218:221], v151 offset:4096
	ds_read_b128 v[222:225], v151 offset:5120
	ds_read_b128 v[226:229], v151 offset:6144
	ds_read_b128 v[230:233], v151 offset:7168
	global_load_lds_dwordx4 v[234:235], off
	v_lshl_add_u64 v[234:235], s[12:13], 0, v[140:141]
	s_add_i32 m0, s22, 0xe000
	s_nop 0
	global_load_lds_dwordx4 v[234:235], off
	s_waitcnt vmcnt(8) lgkmcnt(0)
	s_barrier
; #define STAGE(bufoff, gbase, voff) do { _Pragma("unroll") for (int _i = 0; _i < 2; ++_i) \
;     __builtin_amdgcn_global_load_lds((const unsigned*)((const char*)(gbase) + (voff)[_i]), (LAS unsigned*)(lds + (bufoff) + ldsw + _i * 8192), 16, 0, 0); } while (0)
; #define LDA(dst, b, h) do { _Pragma("unroll") for (int m = 0; m < 4; ++m) _Pragma("unroll") for (int k = 0; k < 2; ++k) dst[m][k] = *(const LAS half8*)(lds + SA(b, h) + aoff + m * 2048 + k * 1024); } while (0)
; #define LDB(dst, b, h) do { _Pragma("unroll") for (int n = 0; n < 2; ++n) _Pragma("unroll") for (int k = 0; k < 2; ++k) dst[n][k] = *(const LAS half8*)(lds + SB(b, h) + boff + n * 2048 + k * 1024); } while (0)
; #define MMA(ai, bj, At_, Bt_) do { __builtin_amdgcn_s_setprio(1); \
;     _Pragma("unroll") for (int m = 0; m < 4; ++m) _Pragma("unroll") for (int n = 0; n < 2; ++n) _Pragma("unroll") for (int k = 0; k < 2; ++k) \
;       acc[ai][bj][m][n] = MFMA16(Bt_[n][k], At_[m][k], acc[ai][bj][m][n]); \
;     __builtin_amdgcn_s_setprio(0); } while (0)
; #define WAIT_V(n) asm volatile("s_waitcnt vmcnt(" #n ")" ::: "memory")
; #define WAIT_L(n) asm volatile("s_waitcnt lgkmcnt(" #n ")" ::: "memory")
; #define BAR __builtin_amdgcn_s_barrier()
; #define SCHED __builtin_amdgcn_sched_barrier(0)
; template <int EPI>
; DI void gemm_phase(const int wid_s, const h16* __restrict__ A, const h16* __restrict__ Bt, const int N, const int K, const EpiArgs ea) {
;     ...
;       LDB(B0, 0, 0); LDB(B1, 0, 1); SCHED; LDA(At, 0, 0); STAGE(SA(1, 1), a1 + hstep, voffA);
;       WAIT_V(8); WAIT_L(0); BAR; MMA(0, 0, At, B0); MMA(0, 1, At, B1); BAR; SCHED;
;       LDA(At, 0, 1); STAGE(SB(0, 0), b2, voffB); STAGE(SB(0, 1), b2 + hstep, voffB); STAGE(SA(0, 0), a2, voffA);
;       WAIT_V(8); WAIT_L(0); BAR; MMA(1, 0, At, B0); MMA(1, 1, At, B1); BAR; SCHED;
;       LDB(B0, 1, 0); LDB(B1, 1, 1); SCHED; LDA(At, 1, 0); STAGE(SA(0, 1), a2 + hstep, voffA);
;       WAIT_V(8); WAIT_L(0); BAR; MMA(0, 0, At, B0); MMA(0, 1, At, B1); BAR; SCHED;
;       LDA(At, 1, 1); STAGE(SB(1, 0), b3, voffB); STAGE(SB(1, 1), b3 + hstep, voffB); STAGE(SA(1, 0), a3, voffA);
;       WAIT_V(8); WAIT_L(0); BAR; MMA(1, 0, At, B0); MMA(1, 1, At, B1); BAR; SCHED;
	v_mfma_f32_16x16x32_f16 v[130:133], v[144:147], v[202:205], v[130:133]
	v_mfma_f32_16x16x32_f16 v[126:129], v[178:181], v[202:205], v[126:129]
	v_mfma_f32_16x16x32_f16 v[114:117], v[144:147], v[210:213], v[114:117]
	v_mfma_f32_16x16x32_f16 v[110:113], v[178:181], v[210:213], v[110:113]
	v_mfma_f32_16x16x32_f16 v[98:101], v[144:147], v[218:221], v[98:101]
	v_mfma_f32_16x16x32_f16 v[94:97], v[178:181], v[218:221], v[94:97]
	v_mfma_f32_16x16x32_f16 v[82:85], v[144:147], v[226:229], v[82:85]
	v_mfma_f32_16x16x32_f16 v[78:81], v[178:181], v[226:229], v[78:81]
	v_mfma_f32_16x16x32_f16 v[130:133], v[152:155], v[206:209], v[130:133]
	v_mfma_f32_16x16x32_f16 v[126:129], v[182:185], v[206:209], v[126:129]
	v_mfma_f32_16x16x32_f16 v[114:117], v[152:155], v[214:217], v[114:117]
	v_mfma_f32_16x16x32_f16 v[110:113], v[182:185], v[214:217], v[110:113]
	v_mfma_f32_16x16x32_f16 v[98:101], v[152:155], v[222:225], v[98:101]
	v_mfma_f32_16x16x32_f16 v[94:97], v[182:185], v[222:225], v[94:97]
	v_mfma_f32_16x16x32_f16 v[82:85], v[152:155], v[230:233], v[82:85]
	v_mfma_f32_16x16x32_f16 v[78:81], v[182:185], v[230:233], v[78:81]
	v_mfma_f32_16x16x32_f16 v[122:125], v[186:189], v[202:205], v[122:125]
	v_mfma_f32_16x16x32_f16 v[118:121], v[194:197], v[202:205], v[118:121]
	v_mfma_f32_16x16x32_f16 v[106:109], v[186:189], v[210:213], v[106:109]
	v_mfma_f32_16x16x32_f16 v[102:105], v[194:197], v[210:213], v[102:105]
	v_mfma_f32_16x16x32_f16 v[90:93], v[186:189], v[218:221], v[90:93]
	v_mfma_f32_16x16x32_f16 v[86:89], v[194:197], v[218:221], v[86:89]
	v_mfma_f32_16x16x32_f16 v[74:77], v[186:189], v[226:229], v[74:77]
	v_mfma_f32_16x16x32_f16 v[70:73], v[194:197], v[226:229], v[70:73]
	v_mfma_f32_16x16x32_f16 v[122:125], v[190:193], v[206:209], v[122:125]
	v_mfma_f32_16x16x32_f16 v[118:121], v[198:201], v[206:209], v[118:121]
	v_mfma_f32_16x16x32_f16 v[106:109], v[190:193], v[214:217], v[106:109]
	v_mfma_f32_16x16x32_f16 v[102:105], v[198:201], v[214:217], v[102:105]
	v_mfma_f32_16x16x32_f16 v[90:93], v[190:193], v[222:225], v[90:93]
	v_mfma_f32_16x16x32_f16 v[86:89], v[198:201], v[222:225], v[86:89]
	v_mfma_f32_16x16x32_f16 v[74:77], v[190:193], v[230:233], v[74:77]
	v_mfma_f32_16x16x32_f16 v[70:73], v[198:201], v[230:233], v[70:73]
	s_barrier
	s_add_i32 s12, s46, s21
	v_lshl_add_u64 v[234:235], s[16:17], 0, v[0:1]
	s_mov_b32 m0, s12
	ds_read_b128 v[202:205], v151 offset:16384
	ds_read_b128 v[206:209], v151 offset:17408
	ds_read_b128 v[210:213], v151 offset:18432
	ds_read_b128 v[214:217], v151 offset:19456
	ds_read_b128 v[218:221], v151 offset:20480
	ds_read_b128 v[222:225], v151 offset:21504
	ds_read_b128 v[226:229], v151 offset:22528
	ds_read_b128 v[230:233], v151 offset:23552
	global_load_lds_dwordx4 v[234:235], off
	s_add_i32 m0, s12, 0x2000
	s_add_u32 s12, s16, 0xb0000
	v_lshl_add_u64 v[236:237], s[16:17], 0, v[138:139]
	s_addc_u32 s13, s17, 0
	s_add_i32 s46, s47, s21
	global_load_lds_dwordx4 v[236:237], off
	v_lshl_add_u64 v[238:239], s[12:13], 0, v[0:1]
	s_mov_b32 m0, s46
	v_lshl_add_u64 v[240:241], s[18:19], 0, v[134:135]
	global_load_lds_dwordx4 v[238:239], off
	v_lshl_add_u64 v[238:239], s[12:13], 0, v[138:139]
	s_add_i32 m0, s46, 0x2000
	s_nop 0
	global_load_lds_dwordx4 v[238:239], off
	v_lshl_add_u64 v[238:239], s[18:19], 0, v[2:3]
	s_mov_b32 m0, s22
	s_nop 0
	global_load_lds_dwordx4 v[238:239], off
	s_mov_b32 m0, s23
	s_nop 0
	global_load_lds_dwordx4 v[240:241], off
	s_waitcnt vmcnt(8) lgkmcnt(0)
	s_barrier
	v_mfma_f32_16x16x32_f16 v[66:69], v[144:147], v[202:205], v[66:69]
	v_mfma_f32_16x16x32_f16 v[62:65], v[178:181], v[202:205], v[62:65]
	v_mfma_f32_16x16x32_f16 v[50:53], v[144:147], v[210:213], v[50:53]
	v_mfma_f32_16x16x32_f16 v[46:49], v[178:181], v[210:213], v[46:49]
	v_mfma_f32_16x16x32_f16 v[34:37], v[144:147], v[218:221], v[34:37]
	v_mfma_f32_16x16x32_f16 v[30:33], v[178:181], v[218:221], v[30:33]
	v_mfma_f32_16x16x32_f16 v[18:21], v[144:147], v[226:229], v[18:21]
	v_mfma_f32_16x16x32_f16 v[14:17], v[178:181], v[226:229], v[14:17]
	v_mfma_f32_16x16x32_f16 v[66:69], v[152:155], v[206:209], v[66:69]
	v_mfma_f32_16x16x32_f16 v[62:65], v[182:185], v[206:209], v[62:65]
	v_mfma_f32_16x16x32_f16 v[50:53], v[152:155], v[214:217], v[50:53]
	v_mfma_f32_16x16x32_f16 v[46:49], v[182:185], v[214:217], v[46:49]
	v_mfma_f32_16x16x32_f16 v[34:37], v[152:155], v[222:225], v[34:37]
	v_mfma_f32_16x16x32_f16 v[30:33], v[182:185], v[222:225], v[30:33]
	v_mfma_f32_16x16x32_f16 v[18:21], v[152:155], v[230:233], v[18:21]
	v_mfma_f32_16x16x32_f16 v[14:17], v[182:185], v[230:233], v[14:17]
	v_mfma_f32_16x16x32_f16 v[58:61], v[186:189], v[202:205], v[58:61]
	v_mfma_f32_16x16x32_f16 v[54:57], v[194:197], v[202:205], v[54:57]
	v_mfma_f32_16x16x32_f16 v[42:45], v[186:189], v[210:213], v[42:45]
	v_mfma_f32_16x16x32_f16 v[38:41], v[194:197], v[210:213], v[38:41]
	v_mfma_f32_16x16x32_f16 v[26:29], v[186:189], v[218:221], v[26:29]
	v_mfma_f32_16x16x32_f16 v[22:25], v[194:197], v[218:221], v[22:25]
	v_mfma_f32_16x16x32_f16 v[10:13], v[186:189], v[226:229], v[10:13]
	v_mfma_f32_16x16x32_f16 v[6:9], v[194:197], v[226:229], v[6:9]
	v_mfma_f32_16x16x32_f16 v[58:61], v[190:193], v[206:209], v[58:61]
	v_mfma_f32_16x16x32_f16 v[54:57], v[198:201], v[206:209], v[54:57]
	v_mfma_f32_16x16x32_f16 v[42:45], v[190:193], v[214:217], v[42:45]
	v_mfma_f32_16x16x32_f16 v[38:41], v[198:201], v[214:217], v[38:41]
	v_mfma_f32_16x16x32_f16 v[26:29], v[190:193], v[222:225], v[26:29]
	v_mfma_f32_16x16x32_f16 v[22:25], v[198:201], v[222:225], v[22:25]
	v_mfma_f32_16x16x32_f16 v[10:13], v[190:193], v[230:233], v[10:13]
	v_mfma_f32_16x16x32_f16 v[6:9], v[198:201], v[230:233], v[6:9]
	s_barrier
; #define STAGE(bufoff, gbase, voff) do { _Pragma("unroll") for (int _i = 0; _i < 2; ++_i) \
;     __builtin_amdgcn_global_load_lds((const unsigned*)((const char*)(gbase) + (voff)[_i]), (LAS unsigned*)(lds + (bufoff) + ldsw + _i * 8192), 16, 0, 0); } while (0)
; #define LDA(dst, b, h) do { _Pragma("unroll") for (int m = 0; m < 4; ++m) _Pragma("unroll") for (int k = 0; k < 2; ++k) dst[m][k] = *(const LAS half8*)(lds + SA(b, h) + aoff + m * 2048 + k * 1024); } while (0)
; #define LDB(dst, b, h) do { _Pragma("unroll") for (int n = 0; n < 2; ++n) _Pragma("unroll") for (int k = 0; k < 2; ++k) dst[n][k] = *(const LAS half8*)(lds + SB(b, h) + boff + n * 2048 + k * 1024); } while (0)
; #define MMA(ai, bj, At_, Bt_) do { __builtin_amdgcn_s_setprio(1); \
;     _Pragma("unroll") for (int m = 0; m < 4; ++m) _Pragma("unroll") for (int n = 0; n < 2; ++n) _Pragma("unroll") for (int k = 0; k < 2; ++k) \
;       acc[ai][bj][m][n] = MFMA16(Bt_[n][k], At_[m][k], acc[ai][bj][m][n]); \
;     __builtin_amdgcn_s_setprio(0); } while (0)
; #define WAIT_V(n) asm volatile("s_waitcnt vmcnt(" #n ")" ::: "memory")
; template <int EPI>
; DI void gemm_phase(const int wid_s, const h16* __restrict__ A, const h16* __restrict__ Bt, const int N, const int K, const EpiArgs ea) {
;     ...
;     for (int t = 0; t < nt; t += 2) {
;       const bool last = (t == nt - 2);
;       const char* a1 = cA + (size_t)(t + 1) * kstep;
;       const char* a2 = last ? nA : cA + (size_t)(t + 2) * kstep; const char* b2 = last ? nB : cB + (size_t)(t + 2) * kstep;
;       const char* a3 = a2 + kstep; const char* b3 = b2 + kstep;
;       LDB(B0, 0, 0); LDB(B1, 0, 1); SCHED; LDA(At, 0, 0); STAGE(SA(1, 1), a1 + hstep, voffA);
;       WAIT_V(8); WAIT_L(0); BAR; MMA(0, 0, At, B0); MMA(0, 1, At, B1); BAR; SCHED;
;       LDA(At, 0, 1); STAGE(SB(0, 0), b2, voffB); STAGE(SB(0, 1), b2 + hstep, voffB); STAGE(SA(0, 0), a2, voffA);
;       WAIT_V(8); WAIT_L(0); BAR; MMA(1, 0, At, B0); MMA(1, 1, At, B1); BAR; SCHED;
;       LDB(B0, 1, 0); LDB(B1, 1, 1); SCHED; LDA(At, 1, 0); STAGE(SA(0, 1), a2 + hstep, voffA);
;       WAIT_V(8); WAIT_L(0); BAR; MMA(0, 0, At, B0); MMA(0, 1, At, B1); BAR; SCHED;
;       LDA(At, 1, 1); STAGE(SB(1, 0), b3, voffB); STAGE(SB(1, 1), b3 + hstep, voffB); STAGE(SA(1, 0), a3, voffA);
;       WAIT_V(8); WAIT_L(0); BAR; MMA(1, 0, At, B0); MMA(1, 1, At, B1); BAR; SCHED;
;     }
;     if (wr == 0) BAR;
	s_add_i32 s46, 0, 0x18000
	v_add_u32_e32 v177, s46, v148
	s_add_i32 s47, 0, 0x1c000
	ds_read_b128 v[144:147], v177
	ds_read_b128 v[152:155], v177 offset:1024
	ds_read_b128 v[178:181], v177 offset:2048
	ds_read_b128 v[182:185], v177 offset:3072
	v_add_u32_e32 v177, s47, v148
	ds_read_b128 v[186:189], v177
	ds_read_b128 v[190:193], v177 offset:1024
	ds_read_b128 v[194:197], v177 offset:2048
	ds_read_b128 v[198:201], v177 offset:3072
	s_add_u32 s12, s18, 0xb0000
	s_addc_u32 s13, s19, 0
	s_mov_b32 m0, s24
	v_lshl_add_u64 v[242:243], s[12:13], 0, v[2:3]
	ds_read_b128 v[202:205], v151 offset:32768
	ds_read_b128 v[206:209], v151 offset:33792
	ds_read_b128 v[210:213], v151 offset:34816
	ds_read_b128 v[214:217], v151 offset:35840
	ds_read_b128 v[218:221], v151 offset:36864
	ds_read_b128 v[222:225], v151 offset:37888
	ds_read_b128 v[226:229], v151 offset:38912
	ds_read_b128 v[230:233], v151 offset:39936
	global_load_lds_dwordx4 v[242:243], off
	v_lshl_add_u64 v[242:243], s[12:13], 0, v[134:135]
	s_mov_b32 m0, s26
	s_nop 0
	global_load_lds_dwordx4 v[242:243], off
	s_waitcnt vmcnt(8) lgkmcnt(0)
	s_barrier
	v_mfma_f32_16x16x32_f16 v[130:133], v[144:147], v[202:205], v[130:133]
	v_mfma_f32_16x16x32_f16 v[126:129], v[178:181], v[202:205], v[126:129]
	v_mfma_f32_16x16x32_f16 v[114:117], v[144:147], v[210:213], v[114:117]
	v_mfma_f32_16x16x32_f16 v[110:113], v[178:181], v[210:213], v[110:113]
	v_mfma_f32_16x16x32_f16 v[98:101], v[144:147], v[218:221], v[98:101]
	v_mfma_f32_16x16x32_f16 v[94:97], v[178:181], v[218:221], v[94:97]
	v_mfma_f32_16x16x32_f16 v[82:85], v[144:147], v[226:229], v[82:85]
	v_mfma_f32_16x16x32_f16 v[78:81], v[178:181], v[226:229], v[78:81]
	v_mfma_f32_16x16x32_f16 v[130:133], v[152:155], v[206:209], v[130:133]
	v_mfma_f32_16x16x32_f16 v[126:129], v[182:185], v[206:209], v[126:129]
	v_mfma_f32_16x16x32_f16 v[114:117], v[152:155], v[214:217], v[114:117]
	v_mfma_f32_16x16x32_f16 v[110:113], v[182:185], v[214:217], v[110:113]
	v_mfma_f32_16x16x32_f16 v[98:101], v[152:155], v[222:225], v[98:101]
	v_mfma_f32_16x16x32_f16 v[94:97], v[182:185], v[222:225], v[94:97]
	v_mfma_f32_16x16x32_f16 v[82:85], v[152:155], v[230:233], v[82:85]
	v_mfma_f32_16x16x32_f16 v[78:81], v[182:185], v[230:233], v[78:81]
	v_mfma_f32_16x16x32_f16 v[122:125], v[186:189], v[202:205], v[122:125]
	v_mfma_f32_16x16x32_f16 v[118:121], v[194:197], v[202:205], v[118:121]
	v_mfma_f32_16x16x32_f16 v[106:109], v[186:189], v[210:213], v[106:109]
	v_mfma_f32_16x16x32_f16 v[102:105], v[194:197], v[210:213], v[102:105]
	v_mfma_f32_16x16x32_f16 v[90:93], v[186:189], v[218:221], v[90:93]
	v_mfma_f32_16x16x32_f16 v[86:89], v[194:197], v[218:221], v[86:89]
	v_mfma_f32_16x16x32_f16 v[74:77], v[186:189], v[226:229], v[74:77]
	v_mfma_f32_16x16x32_f16 v[70:73], v[194:197], v[226:229], v[70:73]
	v_mfma_f32_16x16x32_f16 v[122:125], v[190:193], v[206:209], v[122:125]
	v_mfma_f32_16x16x32_f16 v[118:121], v[198:201], v[206:209], v[118:121]
	v_mfma_f32_16x16x32_f16 v[106:109], v[190:193], v[214:217], v[106:109]
	v_mfma_f32_16x16x32_f16 v[102:105], v[198:201], v[214:217], v[102:105]
	v_mfma_f32_16x16x32_f16 v[90:93], v[190:193], v[222:225], v[90:93]
	v_mfma_f32_16x16x32_f16 v[86:89], v[198:201], v[222:225], v[86:89]
	v_mfma_f32_16x16x32_f16 v[74:77], v[190:193], v[230:233], v[74:77]
	v_mfma_f32_16x16x32_f16 v[70:73], v[198:201], v[230:233], v[70:73]
	s_barrier
	s_add_i32 s12, s46, s21
	v_lshl_add_u64 v[234:235], v[234:235], 0, s[36:37]
	s_mov_b32 m0, s12
	ds_read_b128 v[202:205], v151 offset:49152
	ds_read_b128 v[206:209], v151 offset:50176
	ds_read_b128 v[210:213], v151 offset:51200
	ds_read_b128 v[214:217], v151 offset:52224
	ds_read_b128 v[218:221], v151 offset:53248
	ds_read_b128 v[222:225], v151 offset:54272
	ds_read_b128 v[226:229], v151 offset:55296
	ds_read_b128 v[230:233], v151 offset:56320
	global_load_lds_dwordx4 v[234:235], off
	s_add_i32 m0, s12, 0x2000
	s_add_u32 s12, s16, 0xb0080
	v_lshl_add_u64 v[234:235], v[236:237], 0, s[36:37]
	s_addc_u32 s13, s17, 0
	s_add_i32 s16, s47, s21
	global_load_lds_dwordx4 v[234:235], off
	v_lshl_add_u64 v[234:235], s[12:13], 0, v[0:1]
	s_mov_b32 m0, s16
	s_nop 0
	global_load_lds_dwordx4 v[234:235], off
	v_lshl_add_u64 v[234:235], s[12:13], 0, v[138:139]
	s_add_i32 m0, s16, 0x2000
	s_nop 0
	global_load_lds_dwordx4 v[234:235], off
	v_lshl_add_u64 v[234:235], v[238:239], 0, s[36:37]
	s_mov_b32 m0, s27
	s_nop 0
	global_load_lds_dwordx4 v[234:235], off
	v_lshl_add_u64 v[234:235], v[240:241], 0, s[36:37]
	s_mov_b32 m0, s30
	s_nop 0
	global_load_lds_dwordx4 v[234:235], off
	s_waitcnt vmcnt(8) lgkmcnt(0)
	s_barrier
	v_mfma_f32_16x16x32_f16 v[66:69], v[144:147], v[202:205], v[66:69]
	v_mfma_f32_16x16x32_f16 v[62:65], v[178:181], v[202:205], v[62:65]
	v_mfma_f32_16x16x32_f16 v[50:53], v[144:147], v[210:213], v[50:53]
	v_mfma_f32_16x16x32_f16 v[46:49], v[178:181], v[210:213], v[46:49]
	v_mfma_f32_16x16x32_f16 v[34:37], v[144:147], v[218:221], v[34:37]
	v_mfma_f32_16x16x32_f16 v[30:33], v[178:181], v[218:221], v[30:33]
	v_mfma_f32_16x16x32_f16 v[18:21], v[144:147], v[226:229], v[18:21]
	v_mfma_f32_16x16x32_f16 v[14:17], v[178:181], v[226:229], v[14:17]
	v_mfma_f32_16x16x32_f16 v[66:69], v[152:155], v[206:209], v[66:69]
	v_mfma_f32_16x16x32_f16 v[62:65], v[182:185], v[206:209], v[62:65]
	v_mfma_f32_16x16x32_f16 v[50:53], v[152:155], v[214:217], v[50:53]
	v_mfma_f32_16x16x32_f16 v[46:49], v[182:185], v[214:217], v[46:49]
	v_mfma_f32_16x16x32_f16 v[34:37], v[152:155], v[222:225], v[34:37]
	v_mfma_f32_16x16x32_f16 v[30:33], v[182:185], v[222:225], v[30:33]
	v_mfma_f32_16x16x32_f16 v[18:21], v[152:155], v[230:233], v[18:21]
	v_mfma_f32_16x16x32_f16 v[14:17], v[182:185], v[230:233], v[14:17]
	v_mfma_f32_16x16x32_f16 v[58:61], v[186:189], v[202:205], v[58:61]
	v_mfma_f32_16x16x32_f16 v[54:57], v[194:197], v[202:205], v[54:57]
	v_mfma_f32_16x16x32_f16 v[42:45], v[186:189], v[210:213], v[42:45]
	v_mfma_f32_16x16x32_f16 v[38:41], v[194:197], v[210:213], v[38:41]
	v_mfma_f32_16x16x32_f16 v[26:29], v[186:189], v[218:221], v[26:29]
	v_mfma_f32_16x16x32_f16 v[22:25], v[194:197], v[218:221], v[22:25]
	v_mfma_f32_16x16x32_f16 v[10:13], v[186:189], v[226:229], v[10:13]
	v_mfma_f32_16x16x32_f16 v[6:9], v[194:197], v[226:229], v[6:9]
	v_mfma_f32_16x16x32_f16 v[58:61], v[190:193], v[206:209], v[58:61]
	v_mfma_f32_16x16x32_f16 v[54:57], v[198:201], v[206:209], v[54:57]
	v_mfma_f32_16x16x32_f16 v[42:45], v[190:193], v[214:217], v[42:45]
	v_mfma_f32_16x16x32_f16 v[38:41], v[198:201], v[214:217], v[38:41]
	v_mfma_f32_16x16x32_f16 v[26:29], v[190:193], v[222:225], v[26:29]
	v_mfma_f32_16x16x32_f16 v[22:25], v[198:201], v[222:225], v[22:25]
	v_mfma_f32_16x16x32_f16 v[10:13], v[190:193], v[230:233], v[10:13]
	v_mfma_f32_16x16x32_f16 v[6:9], v[198:201], v[230:233], v[6:9]
	s_barrier
	s_add_i32 s45, s45, 2
	s_add_u32 s43, s43, 0x100
	s_addc_u32 s44, s44, 0
	s_cmp_gt_u32 s45, 41
	s_mov_b64 s[12:13], s[14:15]
	s_cbranch_scc0 .LBB0_122
	s_and_b64 vcc, exec, s[4:5]
	s_cbranch_vccz .LBB0_125
	s_barrier

; #define STAGE(bufoff, gbase, voff) do { _Pragma("unroll") for (int _i = 0; _i < 2; ++_i) \
;     __builtin_amdgcn_global_load_lds((const unsigned*)((const char*)(gbase) + (voff)[_i]), (LAS unsigned*)(lds + (bufoff) + ldsw + _i * 8192), 16, 0, 0); } while (0)
; #define LDA(dst, b, h) do { _Pragma("unroll") for (int m = 0; m < 4; ++m) _Pragma("unroll") for (int k = 0; k < 2; ++k) dst[m][k] = *(const LAS half8*)(lds + SA(b, h) + aoff + m * 2048 + k * 1024); } while (0)
; #define LDB(dst, b, h) do { _Pragma("unroll") for (int n = 0; n < 2; ++n) _Pragma("unroll") for (int k = 0; k < 2; ++k) dst[n][k] = *(const LAS half8*)(lds + SB(b, h) + boff + n * 2048 + k * 1024); } while (0)
; #define WAIT_V(n) asm volatile("s_waitcnt vmcnt(" #n ")" ::: "memory")
; #define WAIT_L(n) asm volatile("s_waitcnt lgkmcnt(" #n ")" ::: "memory")
; #define BAR __builtin_amdgcn_s_barrier()
; #define SCHED __builtin_amdgcn_sched_barrier(0)
; template <int EPI>
; DI void gemm_phase(const int wid_s, const h16* __restrict__ A, const h16* __restrict__ Bt, const int N, const int K, const EpiArgs ea) {
;     ...
;     int nbrow = brow, nbcol = bcol;
;     if (has_next) TILE_RC(Ln, nbrow, nbcol);
;     const char* nA = (const char*)A + (size_t)nbrow * K * 2;
;     const char* nB = (const char*)Bt + (size_t)nbcol * K * 2;
;     for (int t = 0; t < nt; t += 2) {
;       const bool last = (t == nt - 2);
;       const char* a1 = cA + (size_t)(t + 1) * kstep;
;       const char* a2 = last ? nA : cA + (size_t)(t + 2) * kstep; const char* b2 = last ? nB : cB + (size_t)(t + 2) * kstep;
;       const char* a3 = a2 + kstep; const char* b3 = b2 + kstep;
;       LDB(B0, 0, 0); LDB(B1, 0, 1); SCHED; LDA(At, 0, 0); STAGE(SA(1, 1), a1 + hstep, voffA);
;       WAIT_V(8); WAIT_L(0); BAR; MMA(0, 0, At, B0); MMA(0, 1, At, B1); BAR; SCHED;
;       LDA(At, 0, 1); STAGE(SB(0, 0), b2, voffB); STAGE(SB(0, 1), b2 + hstep, voffB); STAGE(SA(0, 0), a2, voffA);
;       WAIT_V(8); WAIT_L(0); BAR; MMA(1, 0, At, B0); MMA(1, 1, At, B1); BAR; SCHED;
;       LDB(B0, 1, 0); LDB(B1, 1, 1); SCHED; LDA(At, 1, 0); STAGE(SA(0, 1), a2 + hstep, voffA);
;       WAIT_V(8); WAIT_L(0); BAR; MMA(0, 0, At, B0); MMA(0, 1, At, B1); BAR; SCHED;
;       LDA(At, 1, 1); STAGE(SB(1, 0), b3, voffB); STAGE(SB(1, 1), b3 + hstep, voffB); STAGE(SA(1, 0), a3, voffA);
;       WAIT_V(8); WAIT_L(0); BAR; MMA(1, 0, At, B0); MMA(1, 1, At, B1); BAR; SCHED;
.LBB0_140:
	s_ashr_i32 s9, s8, 31
	s_lshl_b64 s[12:13], s[8:9], 11
	s_add_u32 s9, s92, s12
	s_addc_u32 s42, s93, s13
	s_ashr_i32 s11, s10, 31
	s_lshl_b64 s[14:15], s[10:11], 11
	v_readlane_b32 s11, v250, 62
	s_add_u32 s11, s11, s14
	v_readlane_b32 s26, v249, 1
	s_addc_u32 s43, s26, s15
	v_readlane_b32 s26, v249, 23
	s_add_u32 s44, s26, s22
	v_readlane_b32 s22, v249, 24
	s_addc_u32 s45, s22, s23
	s_add_u32 s46, s86, s20
	v_mov_b32_e32 v6, 0
	v_lshl_add_u64 v[144:145], v[140:141], 0, s[20:21]
	v_lshl_add_u64 v[146:147], v[142:143], 0, s[20:21]
	s_addc_u32 s47, s87, s21
	s_mov_b32 s48, -2
	s_mov_b64 s[20:21], 0
	s_add_u32 s22, s46, s20
	s_addc_u32 s23, s47, s21
	s_add_u32 s22, s22, 0x520e100
	s_addc_u32 s23, s23, 0
	s_add_u32 s49, s44, s20
	s_addc_u32 s50, s45, s21
	s_add_i32 s51, 0, 0x10000
	s_cmpk_eq_i32 s20, 0x700
	s_cselect_b32 s27, s42, s23
	s_cselect_b32 s26, s9, s22
	v_add_u32_e32 v177, s51, v148
	s_cselect_b32 s23, s43, s50
	s_cselect_b32 s22, s11, s49
	s_add_i32 s49, 0, 0x14000
	ds_read_b128 v[152:155], v177
	ds_read_b128 v[178:181], v177 offset:1024
	ds_read_b128 v[182:185], v177 offset:2048
	ds_read_b128 v[186:189], v177 offset:3072
	v_add_u32_e32 v177, s49, v148
	ds_read_b128 v[190:193], v177
	ds_read_b128 v[194:197], v177 offset:1024
	ds_read_b128 v[198:201], v177 offset:2048
	ds_read_b128 v[202:205], v177 offset:3072
	v_lshl_add_u64 v[238:239], v[146:147], 0, s[20:21]
	s_add_i32 m0, s17, 0xc000
	ds_read_b128 v[206:209], v151
	ds_read_b128 v[210:213], v151 offset:1024
	ds_read_b128 v[214:217], v151 offset:2048
	ds_read_b128 v[218:221], v151 offset:3072
	ds_read_b128 v[222:225], v151 offset:4096
	ds_read_b128 v[226:229], v151 offset:5120
	ds_read_b128 v[230:233], v151 offset:6144
	ds_read_b128 v[234:237], v151 offset:7168
	global_load_lds_dwordx4 v[238:239], off
	v_lshl_add_u64 v[238:239], v[144:145], 0, s[20:21]
	s_add_i32 m0, s17, 0xe000
	s_nop 0
	global_load_lds_dwordx4 v[238:239], off
	s_waitcnt vmcnt(8) lgkmcnt(0)
	s_barrier
	v_mfma_f32_16x16x32_f16 v[130:133], v[152:155], v[206:209], 0
	v_mfma_f32_16x16x32_f16 v[126:129], v[182:185], v[206:209], 0
	v_mfma_f32_16x16x32_f16 v[114:117], v[152:155], v[214:217], 0
	v_mfma_f32_16x16x32_f16 v[110:113], v[182:185], v[214:217], 0
	v_mfma_f32_16x16x32_f16 v[98:101], v[152:155], v[222:225], 0
	v_mfma_f32_16x16x32_f16 v[94:97], v[182:185], v[222:225], 0
	v_mfma_f32_16x16x32_f16 v[82:85], v[152:155], v[230:233], 0
	v_mfma_f32_16x16x32_f16 v[78:81], v[182:185], v[230:233], 0
	v_mfma_f32_16x16x32_f16 v[130:133], v[178:181], v[210:213], v[130:133]
	v_mfma_f32_16x16x32_f16 v[126:129], v[186:189], v[210:213], v[126:129]
	v_mfma_f32_16x16x32_f16 v[114:117], v[178:181], v[218:221], v[114:117]
	v_mfma_f32_16x16x32_f16 v[110:113], v[186:189], v[218:221], v[110:113]
	v_mfma_f32_16x16x32_f16 v[98:101], v[178:181], v[226:229], v[98:101]
	v_mfma_f32_16x16x32_f16 v[94:97], v[186:189], v[226:229], v[94:97]
	v_mfma_f32_16x16x32_f16 v[82:85], v[178:181], v[234:237], v[82:85]
	v_mfma_f32_16x16x32_f16 v[78:81], v[186:189], v[234:237], v[78:81]
	v_mfma_f32_16x16x32_f16 v[122:125], v[190:193], v[206:209], 0
	v_mfma_f32_16x16x32_f16 v[118:121], v[198:201], v[206:209], 0
	v_mfma_f32_16x16x32_f16 v[106:109], v[190:193], v[214:217], 0
	v_mfma_f32_16x16x32_f16 v[102:105], v[198:201], v[214:217], 0
	v_mfma_f32_16x16x32_f16 v[90:93], v[190:193], v[222:225], 0
	v_mfma_f32_16x16x32_f16 v[86:89], v[198:201], v[222:225], 0
	v_mfma_f32_16x16x32_f16 v[74:77], v[190:193], v[230:233], 0
	v_mfma_f32_16x16x32_f16 v[70:73], v[198:201], v[230:233], 0
	v_mfma_f32_16x16x32_f16 v[122:125], v[194:197], v[210:213], v[122:125]
	v_mfma_f32_16x16x32_f16 v[118:121], v[202:205], v[210:213], v[118:121]
	v_mfma_f32_16x16x32_f16 v[106:109], v[194:197], v[218:221], v[106:109]
	v_mfma_f32_16x16x32_f16 v[102:105], v[202:205], v[218:221], v[102:105]
	v_mfma_f32_16x16x32_f16 v[90:93], v[194:197], v[226:229], v[90:93]
	v_mfma_f32_16x16x32_f16 v[86:89], v[202:205], v[226:229], v[86:89]
	v_mfma_f32_16x16x32_f16 v[74:77], v[194:197], v[234:237], v[74:77]
	v_mfma_f32_16x16x32_f16 v[70:73], v[202:205], v[234:237], v[70:73]
	s_barrier
	s_add_i32 s50, s51, s30
	v_lshl_add_u64 v[238:239], s[22:23], 0, v[0:1]
	s_mov_b32 m0, s50
	ds_read_b128 v[206:209], v151 offset:16384
	ds_read_b128 v[210:213], v151 offset:17408
	ds_read_b128 v[214:217], v151 offset:18432
	ds_read_b128 v[218:221], v151 offset:19456
	ds_read_b128 v[222:225], v151 offset:20480
	ds_read_b128 v[226:229], v151 offset:21504
	ds_read_b128 v[230:233], v151 offset:22528
	ds_read_b128 v[234:237], v151 offset:23552
	global_load_lds_dwordx4 v[238:239], off
	s_add_i32 m0, s50, 0x2000
	s_add_u32 s50, s22, 0x40000
	v_lshl_add_u64 v[240:241], s[22:23], 0, v[2:3]
	s_addc_u32 s51, s23, 0
	s_add_i32 s49, s49, s30
	global_load_lds_dwordx4 v[240:241], off
	v_lshl_add_u64 v[242:243], s[50:51], 0, v[0:1]
	s_mov_b32 m0, s49
	v_lshl_add_u64 v[244:245], s[26:27], 0, v[134:135]
	global_load_lds_dwordx4 v[242:243], off
	v_lshl_add_u64 v[242:243], s[50:51], 0, v[2:3]
	s_add_i32 m0, s49, 0x2000
	s_nop 0
	global_load_lds_dwordx4 v[242:243], off
	v_lshl_add_u64 v[242:243], s[26:27], 0, v[138:139]
	s_mov_b32 m0, s17
	s_nop 0
	global_load_lds_dwordx4 v[242:243], off
	s_mov_b32 m0, s19
	s_nop 0
	global_load_lds_dwordx4 v[244:245], off
	s_waitcnt vmcnt(8) lgkmcnt(0)
	s_barrier
; #define STAGE(bufoff, gbase, voff) do { _Pragma("unroll") for (int _i = 0; _i < 2; ++_i) \
;     __builtin_amdgcn_global_load_lds((const unsigned*)((const char*)(gbase) + (voff)[_i]), (LAS unsigned*)(lds + (bufoff) + ldsw + _i * 8192), 16, 0, 0); } while (0)
; #define LDA(dst, b, h) do { _Pragma("unroll") for (int m = 0; m < 4; ++m) _Pragma("unroll") for (int k = 0; k < 2; ++k) dst[m][k] = *(const LAS half8*)(lds + SA(b, h) + aoff + m * 2048 + k * 1024); } while (0)
; #define LDB(dst, b, h) do { _Pragma("unroll") for (int n = 0; n < 2; ++n) _Pragma("unroll") for (int k = 0; k < 2; ++k) dst[n][k] = *(const LAS half8*)(lds + SB(b, h) + boff + n * 2048 + k * 1024); } while (0)
; #define MMA(ai, bj, At_, Bt_) do { __builtin_amdgcn_s_setprio(1); \
;     _Pragma("unroll") for (int m = 0; m < 4; ++m) _Pragma("unroll") for (int n = 0; n < 2; ++n) _Pragma("unroll") for (int k = 0; k < 2; ++k) \
;       acc[ai][bj][m][n] = MFMA16(Bt_[n][k], At_[m][k], acc[ai][bj][m][n]); \
;     __builtin_amdgcn_s_setprio(0); } while (0)
; #define WAIT_V(n) asm volatile("s_waitcnt vmcnt(" #n ")" ::: "memory")
; #define WAIT_L(n) asm volatile("s_waitcnt lgkmcnt(" #n ")" ::: "memory")
; #define BAR __builtin_amdgcn_s_barrier()
; #define SCHED __builtin_amdgcn_sched_barrier(0)
; template <int EPI>
; DI void gemm_phase(const int wid_s, const h16* __restrict__ A, const h16* __restrict__ Bt, const int N, const int K, const EpiArgs ea) {
;     ...
;       LDB(B0, 0, 0); LDB(B1, 0, 1); SCHED; LDA(At, 0, 0); STAGE(SA(1, 1), a1 + hstep, voffA);
;       WAIT_V(8); WAIT_L(0); BAR; MMA(0, 0, At, B0); MMA(0, 1, At, B1); BAR; SCHED;
;       LDA(At, 0, 1); STAGE(SB(0, 0), b2, voffB); STAGE(SB(0, 1), b2 + hstep, voffB); STAGE(SA(0, 0), a2, voffA);
;       WAIT_V(8); WAIT_L(0); BAR; MMA(1, 0, At, B0); MMA(1, 1, At, B1); BAR; SCHED;
;       LDB(B0, 1, 0); LDB(B1, 1, 1); SCHED; LDA(At, 1, 0); STAGE(SA(0, 1), a2 + hstep, voffA);
;       WAIT_V(8); WAIT_L(0); BAR; MMA(0, 0, At, B0); MMA(0, 1, At, B1); BAR; SCHED;
;       LDA(At, 1, 1); STAGE(SB(1, 0), b3, voffB); STAGE(SB(1, 1), b3 + hstep, voffB); STAGE(SA(1, 0), a3, voffA);
;       WAIT_V(8); WAIT_L(0); BAR; MMA(1, 0, At, B0); MMA(1, 1, At, B1); BAR; SCHED;
	v_mfma_f32_16x16x32_f16 v[66:69], v[152:155], v[206:209], 0
	v_mfma_f32_16x16x32_f16 v[62:65], v[182:185], v[206:209], 0
	v_mfma_f32_16x16x32_f16 v[50:53], v[152:155], v[214:217], 0
	v_mfma_f32_16x16x32_f16 v[46:49], v[182:185], v[214:217], 0
	v_mfma_f32_16x16x32_f16 v[34:37], v[152:155], v[222:225], 0
	v_mfma_f32_16x16x32_f16 v[30:33], v[182:185], v[222:225], 0
	v_mfma_f32_16x16x32_f16 v[18:21], v[152:155], v[230:233], 0
	v_mfma_f32_16x16x32_f16 v[14:17], v[182:185], v[230:233], 0
	v_mfma_f32_16x16x32_f16 v[66:69], v[178:181], v[210:213], v[66:69]
	v_mfma_f32_16x16x32_f16 v[62:65], v[186:189], v[210:213], v[62:65]
	v_mfma_f32_16x16x32_f16 v[50:53], v[178:181], v[218:221], v[50:53]
	v_mfma_f32_16x16x32_f16 v[46:49], v[186:189], v[218:221], v[46:49]
	v_mfma_f32_16x16x32_f16 v[34:37], v[178:181], v[226:229], v[34:37]
	v_mfma_f32_16x16x32_f16 v[30:33], v[186:189], v[226:229], v[30:33]
	v_mfma_f32_16x16x32_f16 v[18:21], v[178:181], v[234:237], v[18:21]
	v_mfma_f32_16x16x32_f16 v[14:17], v[186:189], v[234:237], v[14:17]
	v_mfma_f32_16x16x32_f16 v[58:61], v[190:193], v[206:209], 0
	v_mfma_f32_16x16x32_f16 v[54:57], v[198:201], v[206:209], 0
	v_mfma_f32_16x16x32_f16 v[42:45], v[190:193], v[214:217], 0
	v_mfma_f32_16x16x32_f16 v[38:41], v[198:201], v[214:217], 0
	v_mfma_f32_16x16x32_f16 v[26:29], v[190:193], v[222:225], 0
	v_mfma_f32_16x16x32_f16 v[22:25], v[198:201], v[222:225], 0
	v_mfma_f32_16x16x32_f16 v[10:13], v[190:193], v[230:233], 0
	v_mfma_f32_16x16x32_f16 v[6:9], v[198:201], v[230:233], 0
	v_mfma_f32_16x16x32_f16 v[58:61], v[194:197], v[210:213], v[58:61]
	v_mfma_f32_16x16x32_f16 v[54:57], v[202:205], v[210:213], v[54:57]
	v_mfma_f32_16x16x32_f16 v[42:45], v[194:197], v[218:221], v[42:45]
	v_mfma_f32_16x16x32_f16 v[38:41], v[202:205], v[218:221], v[38:41]
	v_mfma_f32_16x16x32_f16 v[26:29], v[194:197], v[226:229], v[26:29]
	v_mfma_f32_16x16x32_f16 v[22:25], v[202:205], v[226:229], v[22:25]
	v_mfma_f32_16x16x32_f16 v[10:13], v[194:197], v[234:237], v[10:13]
	v_mfma_f32_16x16x32_f16 v[6:9], v[202:205], v[234:237], v[6:9]
	s_barrier
	s_add_i32 s49, 0, 0x18000
	v_add_u32_e32 v177, s49, v148
	s_add_i32 s50, 0, 0x1c000
	ds_read_b128 v[152:155], v177
	ds_read_b128 v[178:181], v177 offset:1024
	ds_read_b128 v[182:185], v177 offset:2048
	ds_read_b128 v[186:189], v177 offset:3072
	v_add_u32_e32 v177, s50, v148
	ds_read_b128 v[190:193], v177
	ds_read_b128 v[194:197], v177 offset:1024
	ds_read_b128 v[198:201], v177 offset:2048
	ds_read_b128 v[202:205], v177 offset:3072
	s_add_u32 s26, s26, 0x40000
	s_addc_u32 s27, s27, 0
	s_mov_b32 m0, s31
	v_lshl_add_u64 v[246:247], s[26:27], 0, v[138:139]
	ds_read_b128 v[206:209], v151 offset:32768
	ds_read_b128 v[210:213], v151 offset:33792
	ds_read_b128 v[214:217], v151 offset:34816
	ds_read_b128 v[218:221], v151 offset:35840
	ds_read_b128 v[222:225], v151 offset:36864
	ds_read_b128 v[226:229], v151 offset:37888
	ds_read_b128 v[230:233], v151 offset:38912
	ds_read_b128 v[234:237], v151 offset:39936
	global_load_lds_dwordx4 v[246:247], off
	v_lshl_add_u64 v[246:247], s[26:27], 0, v[134:135]
	s_mov_b32 m0, s38
	s_nop 0
	global_load_lds_dwordx4 v[246:247], off
	s_waitcnt vmcnt(8) lgkmcnt(0)
	s_barrier
	v_mfma_f32_16x16x32_f16 v[130:133], v[152:155], v[206:209], v[130:133]
	v_mfma_f32_16x16x32_f16 v[126:129], v[182:185], v[206:209], v[126:129]
	v_mfma_f32_16x16x32_f16 v[114:117], v[152:155], v[214:217], v[114:117]
	v_mfma_f32_16x16x32_f16 v[110:113], v[182:185], v[214:217], v[110:113]
	v_mfma_f32_16x16x32_f16 v[98:101], v[152:155], v[222:225], v[98:101]
	v_mfma_f32_16x16x32_f16 v[94:97], v[182:185], v[222:225], v[94:97]
	v_mfma_f32_16x16x32_f16 v[82:85], v[152:155], v[230:233], v[82:85]
	v_mfma_f32_16x16x32_f16 v[78:81], v[182:185], v[230:233], v[78:81]
	v_mfma_f32_16x16x32_f16 v[130:133], v[178:181], v[210:213], v[130:133]
	v_mfma_f32_16x16x32_f16 v[126:129], v[186:189], v[210:213], v[126:129]
	v_mfma_f32_16x16x32_f16 v[114:117], v[178:181], v[218:221], v[114:117]
	v_mfma_f32_16x16x32_f16 v[110:113], v[186:189], v[218:221], v[110:113]
	v_mfma_f32_16x16x32_f16 v[98:101], v[178:181], v[226:229], v[98:101]
	v_mfma_f32_16x16x32_f16 v[94:97], v[186:189], v[226:229], v[94:97]
	v_mfma_f32_16x16x32_f16 v[82:85], v[178:181], v[234:237], v[82:85]
	v_mfma_f32_16x16x32_f16 v[78:81], v[186:189], v[234:237], v[78:81]
	v_mfma_f32_16x16x32_f16 v[122:125], v[190:193], v[206:209], v[122:125]
	v_mfma_f32_16x16x32_f16 v[118:121], v[198:201], v[206:209], v[118:121]
	v_mfma_f32_16x16x32_f16 v[106:109], v[190:193], v[214:217], v[106:109]
	v_mfma_f32_16x16x32_f16 v[102:105], v[198:201], v[214:217], v[102:105]
	v_mfma_f32_16x16x32_f16 v[90:93], v[190:193], v[222:225], v[90:93]
	v_mfma_f32_16x16x32_f16 v[86:89], v[198:201], v[222:225], v[86:89]
	v_mfma_f32_16x16x32_f16 v[74:77], v[190:193], v[230:233], v[74:77]
	v_mfma_f32_16x16x32_f16 v[70:73], v[198:201], v[230:233], v[70:73]
	v_mfma_f32_16x16x32_f16 v[122:125], v[194:197], v[210:213], v[122:125]
	v_mfma_f32_16x16x32_f16 v[118:121], v[202:205], v[210:213], v[118:121]
	v_mfma_f32_16x16x32_f16 v[106:109], v[194:197], v[218:221], v[106:109]
	v_mfma_f32_16x16x32_f16 v[102:105], v[202:205], v[218:221], v[102:105]
	v_mfma_f32_16x16x32_f16 v[90:93], v[194:197], v[226:229], v[90:93]
	v_mfma_f32_16x16x32_f16 v[86:89], v[202:205], v[226:229], v[86:89]
	v_mfma_f32_16x16x32_f16 v[74:77], v[194:197], v[234:237], v[74:77]
	v_mfma_f32_16x16x32_f16 v[70:73], v[202:205], v[234:237], v[70:73]
	s_barrier
; #define STAGE(bufoff, gbase, voff) do { _Pragma("unroll") for (int _i = 0; _i < 2; ++_i) \
;     __builtin_amdgcn_global_load_lds((const unsigned*)((const char*)(gbase) + (voff)[_i]), (LAS unsigned*)(lds + (bufoff) + ldsw + _i * 8192), 16, 0, 0); } while (0)
; #define LDA(dst, b, h) do { _Pragma("unroll") for (int m = 0; m < 4; ++m) _Pragma("unroll") for (int k = 0; k < 2; ++k) dst[m][k] = *(const LAS half8*)(lds + SA(b, h) + aoff + m * 2048 + k * 1024); } while (0)
; #define LDB(dst, b, h) do { _Pragma("unroll") for (int n = 0; n < 2; ++n) _Pragma("unroll") for (int k = 0; k < 2; ++k) dst[n][k] = *(const LAS half8*)(lds + SB(b, h) + boff + n * 2048 + k * 1024); } while (0)
; #define MMA(ai, bj, At_, Bt_) do { __builtin_amdgcn_s_setprio(1); \
;     _Pragma("unroll") for (int m = 0; m < 4; ++m) _Pragma("unroll") for (int n = 0; n < 2; ++n) _Pragma("unroll") for (int k = 0; k < 2; ++k) \
;       acc[ai][bj][m][n] = MFMA16(Bt_[n][k], At_[m][k], acc[ai][bj][m][n]); \
;     __builtin_amdgcn_s_setprio(0); } while (0)
; #define WAIT_V(n) asm volatile("s_waitcnt vmcnt(" #n ")" ::: "memory")
; #define BAR __builtin_amdgcn_s_barrier()
; template <int EPI>
; DI void gemm_phase(const int wid_s, const h16* __restrict__ A, const h16* __restrict__ Bt, const int N, const int K, const EpiArgs ea) {
;     ...
;     for (int t = 0; t < nt; t += 2) {
;       const bool last = (t == nt - 2);
;       const char* a1 = cA + (size_t)(t + 1) * kstep;
;       const char* a2 = last ? nA : cA + (size_t)(t + 2) * kstep; const char* b2 = last ? nB : cB + (size_t)(t + 2) * kstep;
;       const char* a3 = a2 + kstep; const char* b3 = b2 + kstep;
;       LDB(B0, 0, 0); LDB(B1, 0, 1); SCHED; LDA(At, 0, 0); STAGE(SA(1, 1), a1 + hstep, voffA);
;       WAIT_V(8); WAIT_L(0); BAR; MMA(0, 0, At, B0); MMA(0, 1, At, B1); BAR; SCHED;
;       LDA(At, 0, 1); STAGE(SB(0, 0), b2, voffB); STAGE(SB(0, 1), b2 + hstep, voffB); STAGE(SA(0, 0), a2, voffA);
;       WAIT_V(8); WAIT_L(0); BAR; MMA(1, 0, At, B0); MMA(1, 1, At, B1); BAR; SCHED;
;       LDB(B0, 1, 0); LDB(B1, 1, 1); SCHED; LDA(At, 1, 0); STAGE(SA(0, 1), a2 + hstep, voffA);
;       WAIT_V(8); WAIT_L(0); BAR; MMA(0, 0, At, B0); MMA(0, 1, At, B1); BAR; SCHED;
;       LDA(At, 1, 1); STAGE(SB(1, 0), b3, voffB); STAGE(SB(1, 1), b3 + hstep, voffB); STAGE(SA(1, 0), a3, voffA);
;       WAIT_V(8); WAIT_L(0); BAR; MMA(1, 0, At, B0); MMA(1, 1, At, B1); BAR; SCHED;
	s_add_i32 s26, s49, s30
	v_lshl_add_u64 v[238:239], v[238:239], 0, s[36:37]
	s_mov_b32 m0, s26
	ds_read_b128 v[206:209], v151 offset:49152
	ds_read_b128 v[210:213], v151 offset:50176
	ds_read_b128 v[214:217], v151 offset:51200
	ds_read_b128 v[218:221], v151 offset:52224
	ds_read_b128 v[222:225], v151 offset:53248
	ds_read_b128 v[226:229], v151 offset:54272
	ds_read_b128 v[230:233], v151 offset:55296
	ds_read_b128 v[234:237], v151 offset:56320
	global_load_lds_dwordx4 v[238:239], off
	s_add_i32 m0, s26, 0x2000
	s_add_u32 s22, s22, 0x40080
	v_lshl_add_u64 v[238:239], v[240:241], 0, s[36:37]
	s_addc_u32 s23, s23, 0
	s_add_i32 s26, s50, s30
	global_load_lds_dwordx4 v[238:239], off
	v_lshl_add_u64 v[238:239], s[22:23], 0, v[0:1]
	s_mov_b32 m0, s26
	s_nop 0
	global_load_lds_dwordx4 v[238:239], off
	v_lshl_add_u64 v[238:239], s[22:23], 0, v[2:3]
	s_add_i32 m0, s26, 0x2000
	s_nop 0
	global_load_lds_dwordx4 v[238:239], off
	v_lshl_add_u64 v[238:239], v[242:243], 0, s[36:37]
	s_mov_b32 m0, s40
	s_nop 0
	global_load_lds_dwordx4 v[238:239], off
	v_lshl_add_u64 v[238:239], v[244:245], 0, s[36:37]
	s_mov_b32 m0, s41
	s_nop 0
	global_load_lds_dwordx4 v[238:239], off
	s_waitcnt vmcnt(8) lgkmcnt(0)
	s_barrier
	v_mfma_f32_16x16x32_f16 v[66:69], v[152:155], v[206:209], v[66:69]
	v_mfma_f32_16x16x32_f16 v[62:65], v[182:185], v[206:209], v[62:65]
	v_mfma_f32_16x16x32_f16 v[50:53], v[152:155], v[214:217], v[50:53]
	v_mfma_f32_16x16x32_f16 v[46:49], v[182:185], v[214:217], v[46:49]
	v_mfma_f32_16x16x32_f16 v[34:37], v[152:155], v[222:225], v[34:37]
	v_mfma_f32_16x16x32_f16 v[30:33], v[182:185], v[222:225], v[30:33]
	v_mfma_f32_16x16x32_f16 v[18:21], v[152:155], v[230:233], v[18:21]
	v_mfma_f32_16x16x32_f16 v[14:17], v[182:185], v[230:233], v[14:17]
	v_mfma_f32_16x16x32_f16 v[66:69], v[178:181], v[210:213], v[66:69]
	v_mfma_f32_16x16x32_f16 v[62:65], v[186:189], v[210:213], v[62:65]
	v_mfma_f32_16x16x32_f16 v[50:53], v[178:181], v[218:221], v[50:53]
	v_mfma_f32_16x16x32_f16 v[46:49], v[186:189], v[218:221], v[46:49]
	v_mfma_f32_16x16x32_f16 v[34:37], v[178:181], v[226:229], v[34:37]
	v_mfma_f32_16x16x32_f16 v[30:33], v[186:189], v[226:229], v[30:33]
	v_mfma_f32_16x16x32_f16 v[18:21], v[178:181], v[234:237], v[18:21]
	v_mfma_f32_16x16x32_f16 v[14:17], v[186:189], v[234:237], v[14:17]
	v_mfma_f32_16x16x32_f16 v[58:61], v[190:193], v[206:209], v[58:61]
	v_mfma_f32_16x16x32_f16 v[54:57], v[198:201], v[206:209], v[54:57]
	v_mfma_f32_16x16x32_f16 v[42:45], v[190:193], v[214:217], v[42:45]
	v_mfma_f32_16x16x32_f16 v[38:41], v[198:201], v[214:217], v[38:41]
	v_mfma_f32_16x16x32_f16 v[26:29], v[190:193], v[222:225], v[26:29]
	v_mfma_f32_16x16x32_f16 v[22:25], v[198:201], v[222:225], v[22:25]
	v_mfma_f32_16x16x32_f16 v[10:13], v[190:193], v[230:233], v[10:13]
	v_mfma_f32_16x16x32_f16 v[6:9], v[198:201], v[230:233], v[6:9]
	v_mfma_f32_16x16x32_f16 v[58:61], v[194:197], v[210:213], v[58:61]
	v_mfma_f32_16x16x32_f16 v[54:57], v[202:205], v[210:213], v[54:57]
	v_mfma_f32_16x16x32_f16 v[42:45], v[194:197], v[218:221], v[42:45]
	v_mfma_f32_16x16x32_f16 v[38:41], v[202:205], v[218:221], v[38:41]
	v_mfma_f32_16x16x32_f16 v[26:29], v[194:197], v[226:229], v[26:29]
	v_mfma_f32_16x16x32_f16 v[22:25], v[202:205], v[226:229], v[22:25]
	v_mfma_f32_16x16x32_f16 v[10:13], v[194:197], v[234:237], v[10:13]
	v_mfma_f32_16x16x32_f16 v[6:9], v[202:205], v[234:237], v[6:9]
	s_barrier
	s_add_i32 s48, s48, 2
	s_add_u32 s20, s20, 0x100
	s_addc_u32 s21, s21, 0
	s_cmp_gt_u32 s48, 13
.LBB0_141:
	s_add_u32 s22, s46, s20
	s_addc_u32 s23, s47, s21
	s_add_u32 s22, s22, 0x520e100
	s_addc_u32 s23, s23, 0
	s_add_u32 s49, s44, s20
	s_addc_u32 s50, s45, s21
	s_add_i32 s51, 0, 0x10000
	s_cmpk_eq_i32 s20, 0x700
	s_cselect_b32 s27, s42, s23
	s_cselect_b32 s26, s9, s22
	v_add_u32_e32 v177, s51, v148
	s_cselect_b32 s23, s43, s50
	s_cselect_b32 s22, s11, s49
	s_add_i32 s49, 0, 0x14000
	ds_read_b128 v[152:155], v177
	ds_read_b128 v[178:181], v177 offset:1024
	ds_read_b128 v[182:185], v177 offset:2048
	ds_read_b128 v[186:189], v177 offset:3072
	v_add_u32_e32 v177, s49, v148
	ds_read_b128 v[190:193], v177
	ds_read_b128 v[194:197], v177 offset:1024
	ds_read_b128 v[198:201], v177 offset:2048
	ds_read_b128 v[202:205], v177 offset:3072
	v_lshl_add_u64 v[238:239], v[146:147], 0, s[20:21]
	s_add_i32 m0, s17, 0xc000
	ds_read_b128 v[206:209], v151
	ds_read_b128 v[210:213], v151 offset:1024
	ds_read_b128 v[214:217], v151 offset:2048
	ds_read_b128 v[218:221], v151 offset:3072
	ds_read_b128 v[222:225], v151 offset:4096
	ds_read_b128 v[226:229], v151 offset:5120
	ds_read_b128 v[230:233], v151 offset:6144
	ds_read_b128 v[234:237], v151 offset:7168
	global_load_lds_dwordx4 v[238:239], off
	v_lshl_add_u64 v[238:239], v[144:145], 0, s[20:21]
	s_add_i32 m0, s17, 0xe000
	s_nop 0
	global_load_lds_dwordx4 v[238:239], off
	s_waitcnt vmcnt(8) lgkmcnt(0)
	s_barrier
; #define STAGE(bufoff, gbase, voff) do { _Pragma("unroll") for (int _i = 0; _i < 2; ++_i) \
;     __builtin_amdgcn_global_load_lds((const unsigned*)((const char*)(gbase) + (voff)[_i]), (LAS unsigned*)(lds + (bufoff) + ldsw + _i * 8192), 16, 0, 0); } while (0)
; #define LDA(dst, b, h) do { _Pragma("unroll") for (int m = 0; m < 4; ++m) _Pragma("unroll") for (int k = 0; k < 2; ++k) dst[m][k] = *(const LAS half8*)(lds + SA(b, h) + aoff + m * 2048 + k * 1024); } while (0)
; #define LDB(dst, b, h) do { _Pragma("unroll") for (int n = 0; n < 2; ++n) _Pragma("unroll") for (int k = 0; k < 2; ++k) dst[n][k] = *(const LAS half8*)(lds + SB(b, h) + boff + n * 2048 + k * 1024); } while (0)
; #define MMA(ai, bj, At_, Bt_) do { __builtin_amdgcn_s_setprio(1); \
;     _Pragma("unroll") for (int m = 0; m < 4; ++m) _Pragma("unroll") for (int n = 0; n < 2; ++n) _Pragma("unroll") for (int k = 0; k < 2; ++k) \
;       acc[ai][bj][m][n] = MFMA16(Bt_[n][k], At_[m][k], acc[ai][bj][m][n]); \
;     __builtin_amdgcn_s_setprio(0); } while (0)
; #define WAIT_V(n) asm volatile("s_waitcnt vmcnt(" #n ")" ::: "memory")
; #define WAIT_L(n) asm volatile("s_waitcnt lgkmcnt(" #n ")" ::: "memory")
; #define BAR __builtin_amdgcn_s_barrier()
; #define SCHED __builtin_amdgcn_sched_barrier(0)
; template <int EPI>
; DI void gemm_phase(const int wid_s, const h16* __restrict__ A, const h16* __restrict__ Bt, const int N, const int K, const EpiArgs ea) {
;     ...
;       LDB(B0, 0, 0); LDB(B1, 0, 1); SCHED; LDA(At, 0, 0); STAGE(SA(1, 1), a1 + hstep, voffA);
;       WAIT_V(8); WAIT_L(0); BAR; MMA(0, 0, At, B0); MMA(0, 1, At, B1); BAR; SCHED;
;       LDA(At, 0, 1); STAGE(SB(0, 0), b2, voffB); STAGE(SB(0, 1), b2 + hstep, voffB); STAGE(SA(0, 0), a2, voffA);
;       WAIT_V(8); WAIT_L(0); BAR; MMA(1, 0, At, B0); MMA(1, 1, At, B1); BAR; SCHED;
;       LDB(B0, 1, 0); LDB(B1, 1, 1); SCHED; LDA(At, 1, 0); STAGE(SA(0, 1), a2 + hstep, voffA);
;       WAIT_V(8); WAIT_L(0); BAR; MMA(0, 0, At, B0); MMA(0, 1, At, B1); BAR; SCHED;
;       LDA(At, 1, 1); STAGE(SB(1, 0), b3, voffB); STAGE(SB(1, 1), b3 + hstep, voffB); STAGE(SA(1, 0), a3, voffA);
;       WAIT_V(8); WAIT_L(0); BAR; MMA(1, 0, At, B0); MMA(1, 1, At, B1); BAR; SCHED;
	v_mfma_f32_16x16x32_f16 v[130:133], v[152:155], v[206:209], v[130:133]
	v_mfma_f32_16x16x32_f16 v[126:129], v[182:185], v[206:209], v[126:129]
	v_mfma_f32_16x16x32_f16 v[114:117], v[152:155], v[214:217], v[114:117]
	v_mfma_f32_16x16x32_f16 v[110:113], v[182:185], v[214:217], v[110:113]
	v_mfma_f32_16x16x32_f16 v[98:101], v[152:155], v[222:225], v[98:101]
	v_mfma_f32_16x16x32_f16 v[94:97], v[182:185], v[222:225], v[94:97]
	v_mfma_f32_16x16x32_f16 v[82:85], v[152:155], v[230:233], v[82:85]
	v_mfma_f32_16x16x32_f16 v[78:81], v[182:185], v[230:233], v[78:81]
	v_mfma_f32_16x16x32_f16 v[130:133], v[178:181], v[210:213], v[130:133]
	v_mfma_f32_16x16x32_f16 v[126:129], v[186:189], v[210:213], v[126:129]
	v_mfma_f32_16x16x32_f16 v[114:117], v[178:181], v[218:221], v[114:117]
	v_mfma_f32_16x16x32_f16 v[110:113], v[186:189], v[218:221], v[110:113]
	v_mfma_f32_16x16x32_f16 v[98:101], v[178:181], v[226:229], v[98:101]
	v_mfma_f32_16x16x32_f16 v[94:97], v[186:189], v[226:229], v[94:97]
	v_mfma_f32_16x16x32_f16 v[82:85], v[178:181], v[234:237], v[82:85]
	v_mfma_f32_16x16x32_f16 v[78:81], v[186:189], v[234:237], v[78:81]
	v_mfma_f32_16x16x32_f16 v[122:125], v[190:193], v[206:209], v[122:125]
	v_mfma_f32_16x16x32_f16 v[118:121], v[198:201], v[206:209], v[118:121]
	v_mfma_f32_16x16x32_f16 v[106:109], v[190:193], v[214:217], v[106:109]
	v_mfma_f32_16x16x32_f16 v[102:105], v[198:201], v[214:217], v[102:105]
	v_mfma_f32_16x16x32_f16 v[90:93], v[190:193], v[222:225], v[90:93]
	v_mfma_f32_16x16x32_f16 v[86:89], v[198:201], v[222:225], v[86:89]
	v_mfma_f32_16x16x32_f16 v[74:77], v[190:193], v[230:233], v[74:77]
	v_mfma_f32_16x16x32_f16 v[70:73], v[198:201], v[230:233], v[70:73]
	v_mfma_f32_16x16x32_f16 v[122:125], v[194:197], v[210:213], v[122:125]
	v_mfma_f32_16x16x32_f16 v[118:121], v[202:205], v[210:213], v[118:121]
	v_mfma_f32_16x16x32_f16 v[106:109], v[194:197], v[218:221], v[106:109]
	v_mfma_f32_16x16x32_f16 v[102:105], v[202:205], v[218:221], v[102:105]
	v_mfma_f32_16x16x32_f16 v[90:93], v[194:197], v[226:229], v[90:93]
	v_mfma_f32_16x16x32_f16 v[86:89], v[202:205], v[226:229], v[86:89]
	v_mfma_f32_16x16x32_f16 v[74:77], v[194:197], v[234:237], v[74:77]
	v_mfma_f32_16x16x32_f16 v[70:73], v[202:205], v[234:237], v[70:73]
	s_barrier
	s_add_i32 s50, s51, s30
	v_lshl_add_u64 v[238:239], s[22:23], 0, v[0:1]
	s_mov_b32 m0, s50
	ds_read_b128 v[206:209], v151 offset:16384
	ds_read_b128 v[210:213], v151 offset:17408
	ds_read_b128 v[214:217], v151 offset:18432
	ds_read_b128 v[218:221], v151 offset:19456
	ds_read_b128 v[222:225], v151 offset:20480
	ds_read_b128 v[226:229], v151 offset:21504
	ds_read_b128 v[230:233], v151 offset:22528
	ds_read_b128 v[234:237], v151 offset:23552
	global_load_lds_dwordx4 v[238:239], off
	s_add_i32 m0, s50, 0x2000
	s_add_u32 s50, s22, 0x40000
	v_lshl_add_u64 v[240:241], s[22:23], 0, v[2:3]
	s_addc_u32 s51, s23, 0
	s_add_i32 s49, s49, s30
	global_load_lds_dwordx4 v[240:241], off
	v_lshl_add_u64 v[242:243], s[50:51], 0, v[0:1]
	s_mov_b32 m0, s49
	v_lshl_add_u64 v[244:245], s[26:27], 0, v[134:135]
	global_load_lds_dwordx4 v[242:243], off
	v_lshl_add_u64 v[242:243], s[50:51], 0, v[2:3]
	s_add_i32 m0, s49, 0x2000
	s_nop 0
	global_load_lds_dwordx4 v[242:243], off
	v_lshl_add_u64 v[242:243], s[26:27], 0, v[138:139]
	s_mov_b32 m0, s17
	s_nop 0
	global_load_lds_dwordx4 v[242:243], off
	s_mov_b32 m0, s19
	s_nop 0
	global_load_lds_dwordx4 v[244:245], off
	s_waitcnt vmcnt(8) lgkmcnt(0)
	s_barrier
	v_mfma_f32_16x16x32_f16 v[66:69], v[152:155], v[206:209], v[66:69]
	v_mfma_f32_16x16x32_f16 v[62:65], v[182:185], v[206:209], v[62:65]
	v_mfma_f32_16x16x32_f16 v[50:53], v[152:155], v[214:217], v[50:53]
	v_mfma_f32_16x16x32_f16 v[46:49], v[182:185], v[214:217], v[46:49]
	v_mfma_f32_16x16x32_f16 v[34:37], v[152:155], v[222:225], v[34:37]
	v_mfma_f32_16x16x32_f16 v[30:33], v[182:185], v[222:225], v[30:33]
	v_mfma_f32_16x16x32_f16 v[18:21], v[152:155], v[230:233], v[18:21]
	v_mfma_f32_16x16x32_f16 v[14:17], v[182:185], v[230:233], v[14:17]
	v_mfma_f32_16x16x32_f16 v[66:69], v[178:181], v[210:213], v[66:69]
	v_mfma_f32_16x16x32_f16 v[62:65], v[186:189], v[210:213], v[62:65]
	v_mfma_f32_16x16x32_f16 v[50:53], v[178:181], v[218:221], v[50:53]
	v_mfma_f32_16x16x32_f16 v[46:49], v[186:189], v[218:221], v[46:49]
	v_mfma_f32_16x16x32_f16 v[34:37], v[178:181], v[226:229], v[34:37]
	v_mfma_f32_16x16x32_f16 v[30:33], v[186:189], v[226:229], v[30:33]
	v_mfma_f32_16x16x32_f16 v[18:21], v[178:181], v[234:237], v[18:21]
	v_mfma_f32_16x16x32_f16 v[14:17], v[186:189], v[234:237], v[14:17]
	v_mfma_f32_16x16x32_f16 v[58:61], v[190:193], v[206:209], v[58:61]
	v_mfma_f32_16x16x32_f16 v[54:57], v[198:201], v[206:209], v[54:57]
	v_mfma_f32_16x16x32_f16 v[42:45], v[190:193], v[214:217], v[42:45]
	v_mfma_f32_16x16x32_f16 v[38:41], v[198:201], v[214:217], v[38:41]
	v_mfma_f32_16x16x32_f16 v[26:29], v[190:193], v[222:225], v[26:29]
	v_mfma_f32_16x16x32_f16 v[22:25], v[198:201], v[222:225], v[22:25]
	v_mfma_f32_16x16x32_f16 v[10:13], v[190:193], v[230:233], v[10:13]
	v_mfma_f32_16x16x32_f16 v[6:9], v[198:201], v[230:233], v[6:9]
	v_mfma_f32_16x16x32_f16 v[58:61], v[194:197], v[210:213], v[58:61]
	v_mfma_f32_16x16x32_f16 v[54:57], v[202:205], v[210:213], v[54:57]
	v_mfma_f32_16x16x32_f16 v[42:45], v[194:197], v[218:221], v[42:45]
	v_mfma_f32_16x16x32_f16 v[38:41], v[202:205], v[218:221], v[38:41]
	v_mfma_f32_16x16x32_f16 v[26:29], v[194:197], v[226:229], v[26:29]
	v_mfma_f32_16x16x32_f16 v[22:25], v[202:205], v[226:229], v[22:25]
	v_mfma_f32_16x16x32_f16 v[10:13], v[194:197], v[234:237], v[10:13]
	v_mfma_f32_16x16x32_f16 v[6:9], v[202:205], v[234:237], v[6:9]
	s_barrier
; #define STAGE(bufoff, gbase, voff) do { _Pragma("unroll") for (int _i = 0; _i < 2; ++_i) \
;     __builtin_amdgcn_global_load_lds((const unsigned*)((const char*)(gbase) + (voff)[_i]), (LAS unsigned*)(lds + (bufoff) + ldsw + _i * 8192), 16, 0, 0); } while (0)
; #define LDA(dst, b, h) do { _Pragma("unroll") for (int m = 0; m < 4; ++m) _Pragma("unroll") for (int k = 0; k < 2; ++k) dst[m][k] = *(const LAS half8*)(lds + SA(b, h) + aoff + m * 2048 + k * 1024); } while (0)
; #define LDB(dst, b, h) do { _Pragma("unroll") for (int n = 0; n < 2; ++n) _Pragma("unroll") for (int k = 0; k < 2; ++k) dst[n][k] = *(const LAS half8*)(lds + SB(b, h) + boff + n * 2048 + k * 1024); } while (0)
; #define MMA(ai, bj, At_, Bt_) do { __builtin_amdgcn_s_setprio(1); \
;     _Pragma("unroll") for (int m = 0; m < 4; ++m) _Pragma("unroll") for (int n = 0; n < 2; ++n) _Pragma("unroll") for (int k = 0; k < 2; ++k) \
;       acc[ai][bj][m][n] = MFMA16(Bt_[n][k], At_[m][k], acc[ai][bj][m][n]); \
;     __builtin_amdgcn_s_setprio(0); } while (0)
; #define WAIT_V(n) asm volatile("s_waitcnt vmcnt(" #n ")" ::: "memory")
; template <int EPI>
; DI void gemm_phase(const int wid_s, const h16* __restrict__ A, const h16* __restrict__ Bt, const int N, const int K, const EpiArgs ea) {
;     ...
;     for (int t = 0; t < nt; t += 2) {
;       const bool last = (t == nt - 2);
;       const char* a1 = cA + (size_t)(t + 1) * kstep;
;       const char* a2 = last ? nA : cA + (size_t)(t + 2) * kstep; const char* b2 = last ? nB : cB + (size_t)(t + 2) * kstep;
;       const char* a3 = a2 + kstep; const char* b3 = b2 + kstep;
;       LDB(B0, 0, 0); LDB(B1, 0, 1); SCHED; LDA(At, 0, 0); STAGE(SA(1, 1), a1 + hstep, voffA);
;       WAIT_V(8); WAIT_L(0); BAR; MMA(0, 0, At, B0); MMA(0, 1, At, B1); BAR; SCHED;
;       LDA(At, 0, 1); STAGE(SB(0, 0), b2, voffB); STAGE(SB(0, 1), b2 + hstep, voffB); STAGE(SA(0, 0), a2, voffA);
;       WAIT_V(8); WAIT_L(0); BAR; MMA(1, 0, At, B0); MMA(1, 1, At, B1); BAR; SCHED;
;       LDB(B0, 1, 0); LDB(B1, 1, 1); SCHED; LDA(At, 1, 0); STAGE(SA(0, 1), a2 + hstep, voffA);
;       WAIT_V(8); WAIT_L(0); BAR; MMA(0, 0, At, B0); MMA(0, 1, At, B1); BAR; SCHED;
;       LDA(At, 1, 1); STAGE(SB(1, 0), b3, voffB); STAGE(SB(1, 1), b3 + hstep, voffB); STAGE(SA(1, 0), a3, voffA);
;       WAIT_V(8); WAIT_L(0); BAR; MMA(1, 0, At, B0); MMA(1, 1, At, B1); BAR; SCHED;
;     }
;     if (wr == 0) BAR;
	s_add_i32 s49, 0, 0x18000
	v_add_u32_e32 v177, s49, v148
	s_add_i32 s50, 0, 0x1c000
	ds_read_b128 v[152:155], v177
	ds_read_b128 v[178:181], v177 offset:1024
	ds_read_b128 v[182:185], v177 offset:2048
	ds_read_b128 v[186:189], v177 offset:3072
	v_add_u32_e32 v177, s50, v148
	ds_read_b128 v[190:193], v177
	ds_read_b128 v[194:197], v177 offset:1024
	ds_read_b128 v[198:201], v177 offset:2048
	ds_read_b128 v[202:205], v177 offset:3072
	s_add_u32 s26, s26, 0x40000
	s_addc_u32 s27, s27, 0
	s_mov_b32 m0, s31
	v_lshl_add_u64 v[246:247], s[26:27], 0, v[138:139]
	ds_read_b128 v[206:209], v151 offset:32768
	ds_read_b128 v[210:213], v151 offset:33792
	ds_read_b128 v[214:217], v151 offset:34816
	ds_read_b128 v[218:221], v151 offset:35840
	ds_read_b128 v[222:225], v151 offset:36864
	ds_read_b128 v[226:229], v151 offset:37888
	ds_read_b128 v[230:233], v151 offset:38912
	ds_read_b128 v[234:237], v151 offset:39936
	global_load_lds_dwordx4 v[246:247], off
	v_lshl_add_u64 v[246:247], s[26:27], 0, v[134:135]
	s_mov_b32 m0, s38
	s_nop 0
	global_load_lds_dwordx4 v[246:247], off
	s_waitcnt vmcnt(8) lgkmcnt(0)
	s_barrier
	v_mfma_f32_16x16x32_f16 v[130:133], v[152:155], v[206:209], v[130:133]
	v_mfma_f32_16x16x32_f16 v[126:129], v[182:185], v[206:209], v[126:129]
	v_mfma_f32_16x16x32_f16 v[114:117], v[152:155], v[214:217], v[114:117]
	v_mfma_f32_16x16x32_f16 v[110:113], v[182:185], v[214:217], v[110:113]
	v_mfma_f32_16x16x32_f16 v[98:101], v[152:155], v[222:225], v[98:101]
	v_mfma_f32_16x16x32_f16 v[94:97], v[182:185], v[222:225], v[94:97]
	v_mfma_f32_16x16x32_f16 v[82:85], v[152:155], v[230:233], v[82:85]
	v_mfma_f32_16x16x32_f16 v[78:81], v[182:185], v[230:233], v[78:81]
	v_mfma_f32_16x16x32_f16 v[130:133], v[178:181], v[210:213], v[130:133]
	v_mfma_f32_16x16x32_f16 v[126:129], v[186:189], v[210:213], v[126:129]
	v_mfma_f32_16x16x32_f16 v[114:117], v[178:181], v[218:221], v[114:117]
	v_mfma_f32_16x16x32_f16 v[110:113], v[186:189], v[218:221], v[110:113]
	v_mfma_f32_16x16x32_f16 v[98:101], v[178:181], v[226:229], v[98:101]
	v_mfma_f32_16x16x32_f16 v[94:97], v[186:189], v[226:229], v[94:97]
	v_mfma_f32_16x16x32_f16 v[82:85], v[178:181], v[234:237], v[82:85]
	v_mfma_f32_16x16x32_f16 v[78:81], v[186:189], v[234:237], v[78:81]
	v_mfma_f32_16x16x32_f16 v[122:125], v[190:193], v[206:209], v[122:125]
	v_mfma_f32_16x16x32_f16 v[118:121], v[198:201], v[206:209], v[118:121]
	v_mfma_f32_16x16x32_f16 v[106:109], v[190:193], v[214:217], v[106:109]
	v_mfma_f32_16x16x32_f16 v[102:105], v[198:201], v[214:217], v[102:105]
	v_mfma_f32_16x16x32_f16 v[90:93], v[190:193], v[222:225], v[90:93]
	v_mfma_f32_16x16x32_f16 v[86:89], v[198:201], v[222:225], v[86:89]
	v_mfma_f32_16x16x32_f16 v[74:77], v[190:193], v[230:233], v[74:77]
	v_mfma_f32_16x16x32_f16 v[70:73], v[198:201], v[230:233], v[70:73]
	v_mfma_f32_16x16x32_f16 v[122:125], v[194:197], v[210:213], v[122:125]
	v_mfma_f32_16x16x32_f16 v[118:121], v[202:205], v[210:213], v[118:121]
	v_mfma_f32_16x16x32_f16 v[106:109], v[194:197], v[218:221], v[106:109]
	v_mfma_f32_16x16x32_f16 v[102:105], v[202:205], v[218:221], v[102:105]
	v_mfma_f32_16x16x32_f16 v[90:93], v[194:197], v[226:229], v[90:93]
	v_mfma_f32_16x16x32_f16 v[86:89], v[202:205], v[226:229], v[86:89]
	v_mfma_f32_16x16x32_f16 v[74:77], v[194:197], v[234:237], v[74:77]
	v_mfma_f32_16x16x32_f16 v[70:73], v[202:205], v[234:237], v[70:73]
	s_barrier
	s_add_i32 s26, s49, s30
	v_lshl_add_u64 v[238:239], v[238:239], 0, s[36:37]
	s_mov_b32 m0, s26
	ds_read_b128 v[206:209], v151 offset:49152
	ds_read_b128 v[210:213], v151 offset:50176
	ds_read_b128 v[214:217], v151 offset:51200
	ds_read_b128 v[218:221], v151 offset:52224
	ds_read_b128 v[222:225], v151 offset:53248
	ds_read_b128 v[226:229], v151 offset:54272
	ds_read_b128 v[230:233], v151 offset:55296
	ds_read_b128 v[234:237], v151 offset:56320
	global_load_lds_dwordx4 v[238:239], off
	s_add_i32 m0, s26, 0x2000
	s_add_u32 s22, s22, 0x40080
	v_lshl_add_u64 v[238:239], v[240:241], 0, s[36:37]
	s_addc_u32 s23, s23, 0
	s_add_i32 s26, s50, s30
	global_load_lds_dwordx4 v[238:239], off
	v_lshl_add_u64 v[238:239], s[22:23], 0, v[0:1]
	s_mov_b32 m0, s26
	s_nop 0
	global_load_lds_dwordx4 v[238:239], off
	v_lshl_add_u64 v[238:239], s[22:23], 0, v[2:3]
	s_add_i32 m0, s26, 0x2000
	s_nop 0
	global_load_lds_dwordx4 v[238:239], off
	v_lshl_add_u64 v[238:239], v[242:243], 0, s[36:37]
	s_mov_b32 m0, s40
	s_nop 0
	global_load_lds_dwordx4 v[238:239], off
	v_lshl_add_u64 v[238:239], v[244:245], 0, s[36:37]
	s_mov_b32 m0, s41
	s_nop 0
	global_load_lds_dwordx4 v[238:239], off
	s_waitcnt vmcnt(8) lgkmcnt(0)
	s_barrier
	v_mfma_f32_16x16x32_f16 v[66:69], v[152:155], v[206:209], v[66:69]
	v_mfma_f32_16x16x32_f16 v[62:65], v[182:185], v[206:209], v[62:65]
	v_mfma_f32_16x16x32_f16 v[50:53], v[152:155], v[214:217], v[50:53]
	v_mfma_f32_16x16x32_f16 v[46:49], v[182:185], v[214:217], v[46:49]
	v_mfma_f32_16x16x32_f16 v[34:37], v[152:155], v[222:225], v[34:37]
	v_mfma_f32_16x16x32_f16 v[30:33], v[182:185], v[222:225], v[30:33]
	v_mfma_f32_16x16x32_f16 v[18:21], v[152:155], v[230:233], v[18:21]
	v_mfma_f32_16x16x32_f16 v[14:17], v[182:185], v[230:233], v[14:17]
	v_mfma_f32_16x16x32_f16 v[66:69], v[178:181], v[210:213], v[66:69]
	v_mfma_f32_16x16x32_f16 v[62:65], v[186:189], v[210:213], v[62:65]
	v_mfma_f32_16x16x32_f16 v[50:53], v[178:181], v[218:221], v[50:53]
	v_mfma_f32_16x16x32_f16 v[46:49], v[186:189], v[218:221], v[46:49]
	v_mfma_f32_16x16x32_f16 v[34:37], v[178:181], v[226:229], v[34:37]
	v_mfma_f32_16x16x32_f16 v[30:33], v[186:189], v[226:229], v[30:33]
	v_mfma_f32_16x16x32_f16 v[18:21], v[178:181], v[234:237], v[18:21]
	v_mfma_f32_16x16x32_f16 v[14:17], v[186:189], v[234:237], v[14:17]
	v_mfma_f32_16x16x32_f16 v[58:61], v[190:193], v[206:209], v[58:61]
	v_mfma_f32_16x16x32_f16 v[54:57], v[198:201], v[206:209], v[54:57]
	v_mfma_f32_16x16x32_f16 v[42:45], v[190:193], v[214:217], v[42:45]
	v_mfma_f32_16x16x32_f16 v[38:41], v[198:201], v[214:217], v[38:41]
	v_mfma_f32_16x16x32_f16 v[26:29], v[190:193], v[222:225], v[26:29]
	v_mfma_f32_16x16x32_f16 v[22:25], v[198:201], v[222:225], v[22:25]
	v_mfma_f32_16x16x32_f16 v[10:13], v[190:193], v[230:233], v[10:13]
	v_mfma_f32_16x16x32_f16 v[6:9], v[198:201], v[230:233], v[6:9]
	v_mfma_f32_16x16x32_f16 v[58:61], v[194:197], v[210:213], v[58:61]
	v_mfma_f32_16x16x32_f16 v[54:57], v[202:205], v[210:213], v[54:57]
	v_mfma_f32_16x16x32_f16 v[42:45], v[194:197], v[218:221], v[42:45]
	v_mfma_f32_16x16x32_f16 v[38:41], v[202:205], v[218:221], v[38:41]
	v_mfma_f32_16x16x32_f16 v[26:29], v[194:197], v[226:229], v[26:29]
	v_mfma_f32_16x16x32_f16 v[22:25], v[202:205], v[226:229], v[22:25]
	v_mfma_f32_16x16x32_f16 v[10:13], v[194:197], v[234:237], v[10:13]
	v_mfma_f32_16x16x32_f16 v[6:9], v[202:205], v[234:237], v[6:9]
	s_barrier
	s_add_i32 s48, s48, 2
	s_add_u32 s20, s20, 0x100
	s_addc_u32 s21, s21, 0
	s_cmp_gt_u32 s48, 13
	s_cbranch_scc0 .LBB0_141
	s_and_b64 vcc, exec, s[4:5]
	s_cbranch_vccz .LBB0_144
	s_barrier

; #define STAGE(bufoff, gbase, voff) do { _Pragma("unroll") for (int _i = 0; _i < 2; ++_i) \
;     __builtin_amdgcn_global_load_lds((const unsigned*)((const char*)(gbase) + (voff)[_i]), (LAS unsigned*)(lds + (bufoff) + ldsw + _i * 8192), 16, 0, 0); } while (0)
; #define LDA(dst, b, h) do { _Pragma("unroll") for (int m = 0; m < 4; ++m) _Pragma("unroll") for (int k = 0; k < 2; ++k) dst[m][k] = *(const LAS half8*)(lds + SA(b, h) + aoff + m * 2048 + k * 1024); } while (0)
; #define LDB(dst, b, h) do { _Pragma("unroll") for (int n = 0; n < 2; ++n) _Pragma("unroll") for (int k = 0; k < 2; ++k) dst[n][k] = *(const LAS half8*)(lds + SB(b, h) + boff + n * 2048 + k * 1024); } while (0)
; #define WAIT_V(n) asm volatile("s_waitcnt vmcnt(" #n ")" ::: "memory")
; #define WAIT_L(n) asm volatile("s_waitcnt lgkmcnt(" #n ")" ::: "memory")
; #define BAR __builtin_amdgcn_s_barrier()
; #define SCHED __builtin_amdgcn_sched_barrier(0)
; template <int EPI>
; DI void gemm_phase(const int wid_s, const h16* __restrict__ A, const h16* __restrict__ Bt, const int N, const int K, const EpiArgs ea) {
;     ...
;     int nbrow = brow, nbcol = bcol;
;     if (has_next) TILE_RC(Ln, nbrow, nbcol);
;     const char* nA = (const char*)A + (size_t)nbrow * K * 2;
;     const char* nB = (const char*)Bt + (size_t)nbcol * K * 2;
;     for (int t = 0; t < nt; t += 2) {
;       const bool last = (t == nt - 2);
;       const char* a1 = cA + (size_t)(t + 1) * kstep;
;       const char* a2 = last ? nA : cA + (size_t)(t + 2) * kstep; const char* b2 = last ? nB : cB + (size_t)(t + 2) * kstep;
;       const char* a3 = a2 + kstep; const char* b3 = b2 + kstep;
;       LDB(B0, 0, 0); LDB(B1, 0, 1); SCHED; LDA(At, 0, 0); STAGE(SA(1, 1), a1 + hstep, voffA);
;       WAIT_V(8); WAIT_L(0); BAR; MMA(0, 0, At, B0); MMA(0, 1, At, B1); BAR; SCHED;
;       LDA(At, 0, 1); STAGE(SB(0, 0), b2, voffB); STAGE(SB(0, 1), b2 + hstep, voffB); STAGE(SA(0, 0), a2, voffA);
;       WAIT_V(8); WAIT_L(0); BAR; MMA(1, 0, At, B0); MMA(1, 1, At, B1); BAR; SCHED;
;       LDB(B0, 1, 0); LDB(B1, 1, 1); SCHED; LDA(At, 1, 0); STAGE(SA(0, 1), a2 + hstep, voffA);
;       WAIT_V(8); WAIT_L(0); BAR; MMA(0, 0, At, B0); MMA(0, 1, At, B1); BAR; SCHED;
;       LDA(At, 1, 1); STAGE(SB(1, 0), b3, voffB); STAGE(SB(1, 1), b3 + hstep, voffB); STAGE(SA(1, 0), a3, voffA);
;       WAIT_V(8); WAIT_L(0); BAR; MMA(1, 0, At, B0); MMA(1, 1, At, B1); BAR; SCHED;
.LBB0_174:
	s_ashr_i32 s9, s8, 31
	s_lshl_b64 s[12:13], s[8:9], 11
	v_readlane_b32 s14, v250, 46
	v_readlane_b32 s15, v250, 47
	s_add_u32 s12, s14, s12
	s_addc_u32 s13, s15, s13
	s_ashr_i32 s11, s10, 31
	s_lshl_b64 s[14:15], s[10:11], 11
	v_readlane_b32 s9, v249, 6
	s_add_u32 s9, s9, s14
	v_readlane_b32 s11, v249, 7
	s_addc_u32 s11, s11, s15
	v_readlane_b32 s26, v249, 27
	s_add_u32 s41, s26, s20
	v_readlane_b32 s20, v249, 28
	s_addc_u32 s42, s20, s21
	s_add_u32 s20, s22, 0x40080
	v_mov_b32_e32 v6, 0
	s_addc_u32 s21, s23, 0
	s_mov_b32 s43, -2
	s_add_u32 s22, s20, 0xfffc0080
	s_addc_u32 s23, s21, -1
	s_add_i32 s44, 0, 0x10000
	s_cmp_eq_u32 s43, 12
	s_cselect_b32 s27, s13, s23
	s_cselect_b32 s26, s12, s22
	v_add_u32_e32 v177, s44, v148
	s_cselect_b32 s23, s11, s42
	s_cselect_b32 s22, s9, s41
	s_add_i32 s46, 0, 0x14000
	ds_read_b128 v[144:147], v177
	ds_read_b128 v[152:155], v177 offset:1024
	ds_read_b128 v[178:181], v177 offset:2048
	ds_read_b128 v[182:185], v177 offset:3072
	v_add_u32_e32 v177, s46, v148
	ds_read_b128 v[186:189], v177
	ds_read_b128 v[190:193], v177 offset:1024
	ds_read_b128 v[194:197], v177 offset:2048
	ds_read_b128 v[198:201], v177 offset:3072
	v_lshl_add_u64 v[234:235], s[20:21], 0, v[142:143]
	s_add_i32 m0, s17, 0xc000
	ds_read_b128 v[202:205], v151
	ds_read_b128 v[206:209], v151 offset:1024
	ds_read_b128 v[210:213], v151 offset:2048
	ds_read_b128 v[214:217], v151 offset:3072
	ds_read_b128 v[218:221], v151 offset:4096
	ds_read_b128 v[222:225], v151 offset:5120
	ds_read_b128 v[226:229], v151 offset:6144
	ds_read_b128 v[230:233], v151 offset:7168
	global_load_lds_dwordx4 v[234:235], off
	v_lshl_add_u64 v[234:235], s[20:21], 0, v[140:141]
	s_add_i32 m0, s17, 0xe000
	s_nop 0
	global_load_lds_dwordx4 v[234:235], off
	s_waitcnt vmcnt(8) lgkmcnt(0)
	s_barrier
	v_mfma_f32_16x16x32_f16 v[130:133], v[144:147], v[202:205], 0
	v_mfma_f32_16x16x32_f16 v[126:129], v[178:181], v[202:205], 0
	v_mfma_f32_16x16x32_f16 v[114:117], v[144:147], v[210:213], 0
	v_mfma_f32_16x16x32_f16 v[110:113], v[178:181], v[210:213], 0
	v_mfma_f32_16x16x32_f16 v[98:101], v[144:147], v[218:221], 0
	v_mfma_f32_16x16x32_f16 v[94:97], v[178:181], v[218:221], 0
	v_mfma_f32_16x16x32_f16 v[82:85], v[144:147], v[226:229], 0
	v_mfma_f32_16x16x32_f16 v[78:81], v[178:181], v[226:229], 0
	v_mfma_f32_16x16x32_f16 v[130:133], v[152:155], v[206:209], v[130:133]
	v_mfma_f32_16x16x32_f16 v[126:129], v[182:185], v[206:209], v[126:129]
	v_mfma_f32_16x16x32_f16 v[114:117], v[152:155], v[214:217], v[114:117]
	v_mfma_f32_16x16x32_f16 v[110:113], v[182:185], v[214:217], v[110:113]
	v_mfma_f32_16x16x32_f16 v[98:101], v[152:155], v[222:225], v[98:101]
	v_mfma_f32_16x16x32_f16 v[94:97], v[182:185], v[222:225], v[94:97]
	v_mfma_f32_16x16x32_f16 v[82:85], v[152:155], v[230:233], v[82:85]
	v_mfma_f32_16x16x32_f16 v[78:81], v[182:185], v[230:233], v[78:81]
	v_mfma_f32_16x16x32_f16 v[122:125], v[186:189], v[202:205], 0
	v_mfma_f32_16x16x32_f16 v[118:121], v[194:197], v[202:205], 0
	v_mfma_f32_16x16x32_f16 v[106:109], v[186:189], v[210:213], 0
	v_mfma_f32_16x16x32_f16 v[102:105], v[194:197], v[210:213], 0
	v_mfma_f32_16x16x32_f16 v[90:93], v[186:189], v[218:221], 0
	v_mfma_f32_16x16x32_f16 v[86:89], v[194:197], v[218:221], 0
	v_mfma_f32_16x16x32_f16 v[74:77], v[186:189], v[226:229], 0
	v_mfma_f32_16x16x32_f16 v[70:73], v[194:197], v[226:229], 0
	v_mfma_f32_16x16x32_f16 v[122:125], v[190:193], v[206:209], v[122:125]
	v_mfma_f32_16x16x32_f16 v[118:121], v[198:201], v[206:209], v[118:121]
	v_mfma_f32_16x16x32_f16 v[106:109], v[190:193], v[214:217], v[106:109]
	v_mfma_f32_16x16x32_f16 v[102:105], v[198:201], v[214:217], v[102:105]
	v_mfma_f32_16x16x32_f16 v[90:93], v[190:193], v[222:225], v[90:93]
	v_mfma_f32_16x16x32_f16 v[86:89], v[198:201], v[222:225], v[86:89]
	v_mfma_f32_16x16x32_f16 v[74:77], v[190:193], v[230:233], v[74:77]
	v_mfma_f32_16x16x32_f16 v[70:73], v[198:201], v[230:233], v[70:73]
	s_barrier
	s_add_i32 s44, s44, s30
	v_lshl_add_u64 v[234:235], s[22:23], 0, v[0:1]
	s_mov_b32 m0, s44
	ds_read_b128 v[202:205], v151 offset:16384
	ds_read_b128 v[206:209], v151 offset:17408
	ds_read_b128 v[210:213], v151 offset:18432
	ds_read_b128 v[214:217], v151 offset:19456
	ds_read_b128 v[218:221], v151 offset:20480
	ds_read_b128 v[222:225], v151 offset:21504
	ds_read_b128 v[226:229], v151 offset:22528
	ds_read_b128 v[230:233], v151 offset:23552
	global_load_lds_dwordx4 v[234:235], off
	s_add_i32 m0, s44, 0x2000
	s_add_u32 s44, s22, 0x40000
	v_lshl_add_u64 v[236:237], s[22:23], 0, v[138:139]
	s_addc_u32 s45, s23, 0
	s_add_i32 s46, s46, s30
	global_load_lds_dwordx4 v[236:237], off
	v_lshl_add_u64 v[238:239], s[44:45], 0, v[0:1]
	s_mov_b32 m0, s46
	v_lshl_add_u64 v[240:241], s[26:27], 0, v[134:135]
	global_load_lds_dwordx4 v[238:239], off
	v_lshl_add_u64 v[238:239], s[44:45], 0, v[138:139]
	s_add_i32 m0, s46, 0x2000
	s_nop 0
	global_load_lds_dwordx4 v[238:239], off
	v_lshl_add_u64 v[238:239], s[26:27], 0, v[2:3]
	s_mov_b32 m0, s17
	s_nop 0
	global_load_lds_dwordx4 v[238:239], off
	s_mov_b32 m0, s19
	s_nop 0
	global_load_lds_dwordx4 v[240:241], off
	s_waitcnt vmcnt(8) lgkmcnt(0)
	s_barrier
; #define STAGE(bufoff, gbase, voff) do { _Pragma("unroll") for (int _i = 0; _i < 2; ++_i) \
;     __builtin_amdgcn_global_load_lds((const unsigned*)((const char*)(gbase) + (voff)[_i]), (LAS unsigned*)(lds + (bufoff) + ldsw + _i * 8192), 16, 0, 0); } while (0)
; #define LDA(dst, b, h) do { _Pragma("unroll") for (int m = 0; m < 4; ++m) _Pragma("unroll") for (int k = 0; k < 2; ++k) dst[m][k] = *(const LAS half8*)(lds + SA(b, h) + aoff + m * 2048 + k * 1024); } while (0)
; #define LDB(dst, b, h) do { _Pragma("unroll") for (int n = 0; n < 2; ++n) _Pragma("unroll") for (int k = 0; k < 2; ++k) dst[n][k] = *(const LAS half8*)(lds + SB(b, h) + boff + n * 2048 + k * 1024); } while (0)
; #define MMA(ai, bj, At_, Bt_) do { __builtin_amdgcn_s_setprio(1); \
;     _Pragma("unroll") for (int m = 0; m < 4; ++m) _Pragma("unroll") for (int n = 0; n < 2; ++n) _Pragma("unroll") for (int k = 0; k < 2; ++k) \
;       acc[ai][bj][m][n] = MFMA16(Bt_[n][k], At_[m][k], acc[ai][bj][m][n]); \
;     __builtin_amdgcn_s_setprio(0); } while (0)
; #define WAIT_V(n) asm volatile("s_waitcnt vmcnt(" #n ")" ::: "memory")
; #define WAIT_L(n) asm volatile("s_waitcnt lgkmcnt(" #n ")" ::: "memory")
; #define BAR __builtin_amdgcn_s_barrier()
; #define SCHED __builtin_amdgcn_sched_barrier(0)
; template <int EPI>
; DI void gemm_phase(const int wid_s, const h16* __restrict__ A, const h16* __restrict__ Bt, const int N, const int K, const EpiArgs ea) {
;     ...
;       LDB(B0, 0, 0); LDB(B1, 0, 1); SCHED; LDA(At, 0, 0); STAGE(SA(1, 1), a1 + hstep, voffA);
;       WAIT_V(8); WAIT_L(0); BAR; MMA(0, 0, At, B0); MMA(0, 1, At, B1); BAR; SCHED;
;       LDA(At, 0, 1); STAGE(SB(0, 0), b2, voffB); STAGE(SB(0, 1), b2 + hstep, voffB); STAGE(SA(0, 0), a2, voffA);
;       WAIT_V(8); WAIT_L(0); BAR; MMA(1, 0, At, B0); MMA(1, 1, At, B1); BAR; SCHED;
;       LDB(B0, 1, 0); LDB(B1, 1, 1); SCHED; LDA(At, 1, 0); STAGE(SA(0, 1), a2 + hstep, voffA);
;       WAIT_V(8); WAIT_L(0); BAR; MMA(0, 0, At, B0); MMA(0, 1, At, B1); BAR; SCHED;
;       LDA(At, 1, 1); STAGE(SB(1, 0), b3, voffB); STAGE(SB(1, 1), b3 + hstep, voffB); STAGE(SA(1, 0), a3, voffA);
;       WAIT_V(8); WAIT_L(0); BAR; MMA(1, 0, At, B0); MMA(1, 1, At, B1); BAR; SCHED;
	v_mfma_f32_16x16x32_f16 v[66:69], v[144:147], v[202:205], 0
	v_mfma_f32_16x16x32_f16 v[62:65], v[178:181], v[202:205], 0
	v_mfma_f32_16x16x32_f16 v[50:53], v[144:147], v[210:213], 0
	v_mfma_f32_16x16x32_f16 v[46:49], v[178:181], v[210:213], 0
	v_mfma_f32_16x16x32_f16 v[34:37], v[144:147], v[218:221], 0
	v_mfma_f32_16x16x32_f16 v[30:33], v[178:181], v[218:221], 0
	v_mfma_f32_16x16x32_f16 v[18:21], v[144:147], v[226:229], 0
	v_mfma_f32_16x16x32_f16 v[14:17], v[178:181], v[226:229], 0
	v_mfma_f32_16x16x32_f16 v[66:69], v[152:155], v[206:209], v[66:69]
	v_mfma_f32_16x16x32_f16 v[62:65], v[182:185], v[206:209], v[62:65]
	v_mfma_f32_16x16x32_f16 v[50:53], v[152:155], v[214:217], v[50:53]
	v_mfma_f32_16x16x32_f16 v[46:49], v[182:185], v[214:217], v[46:49]
	v_mfma_f32_16x16x32_f16 v[34:37], v[152:155], v[222:225], v[34:37]
	v_mfma_f32_16x16x32_f16 v[30:33], v[182:185], v[222:225], v[30:33]
	v_mfma_f32_16x16x32_f16 v[18:21], v[152:155], v[230:233], v[18:21]
	v_mfma_f32_16x16x32_f16 v[14:17], v[182:185], v[230:233], v[14:17]
	v_mfma_f32_16x16x32_f16 v[58:61], v[186:189], v[202:205], 0
	v_mfma_f32_16x16x32_f16 v[54:57], v[194:197], v[202:205], 0
	v_mfma_f32_16x16x32_f16 v[42:45], v[186:189], v[210:213], 0
	v_mfma_f32_16x16x32_f16 v[38:41], v[194:197], v[210:213], 0
	v_mfma_f32_16x16x32_f16 v[26:29], v[186:189], v[218:221], 0
	v_mfma_f32_16x16x32_f16 v[22:25], v[194:197], v[218:221], 0
	v_mfma_f32_16x16x32_f16 v[10:13], v[186:189], v[226:229], 0
	v_mfma_f32_16x16x32_f16 v[6:9], v[194:197], v[226:229], 0
	v_mfma_f32_16x16x32_f16 v[58:61], v[190:193], v[206:209], v[58:61]
	v_mfma_f32_16x16x32_f16 v[54:57], v[198:201], v[206:209], v[54:57]
	v_mfma_f32_16x16x32_f16 v[42:45], v[190:193], v[214:217], v[42:45]
	v_mfma_f32_16x16x32_f16 v[38:41], v[198:201], v[214:217], v[38:41]
	v_mfma_f32_16x16x32_f16 v[26:29], v[190:193], v[222:225], v[26:29]
	v_mfma_f32_16x16x32_f16 v[22:25], v[198:201], v[222:225], v[22:25]
	v_mfma_f32_16x16x32_f16 v[10:13], v[190:193], v[230:233], v[10:13]
	v_mfma_f32_16x16x32_f16 v[6:9], v[198:201], v[230:233], v[6:9]
	s_barrier
	s_add_i32 s44, 0, 0x18000
	v_add_u32_e32 v177, s44, v148
	s_add_i32 s45, 0, 0x1c000
	ds_read_b128 v[144:147], v177
	ds_read_b128 v[152:155], v177 offset:1024
	ds_read_b128 v[178:181], v177 offset:2048
	ds_read_b128 v[182:185], v177 offset:3072
	v_add_u32_e32 v177, s45, v148
	ds_read_b128 v[186:189], v177
	ds_read_b128 v[190:193], v177 offset:1024
	ds_read_b128 v[194:197], v177 offset:2048
	ds_read_b128 v[198:201], v177 offset:3072
	s_add_u32 s26, s26, 0x40000
	s_addc_u32 s27, s27, 0
	s_mov_b32 m0, s31
	v_lshl_add_u64 v[242:243], s[26:27], 0, v[2:3]
	ds_read_b128 v[202:205], v151 offset:32768
	ds_read_b128 v[206:209], v151 offset:33792
	ds_read_b128 v[210:213], v151 offset:34816
	ds_read_b128 v[214:217], v151 offset:35840
	ds_read_b128 v[218:221], v151 offset:36864
	ds_read_b128 v[222:225], v151 offset:37888
	ds_read_b128 v[226:229], v151 offset:38912
	ds_read_b128 v[230:233], v151 offset:39936
	global_load_lds_dwordx4 v[242:243], off
	v_lshl_add_u64 v[242:243], s[26:27], 0, v[134:135]
	s_mov_b32 m0, s38
	s_nop 0
	global_load_lds_dwordx4 v[242:243], off
	s_waitcnt vmcnt(8) lgkmcnt(0)
	s_barrier
	v_mfma_f32_16x16x32_f16 v[130:133], v[144:147], v[202:205], v[130:133]
	v_mfma_f32_16x16x32_f16 v[126:129], v[178:181], v[202:205], v[126:129]
	v_mfma_f32_16x16x32_f16 v[114:117], v[144:147], v[210:213], v[114:117]
	v_mfma_f32_16x16x32_f16 v[110:113], v[178:181], v[210:213], v[110:113]
	v_mfma_f32_16x16x32_f16 v[98:101], v[144:147], v[218:221], v[98:101]
	v_mfma_f32_16x16x32_f16 v[94:97], v[178:181], v[218:221], v[94:97]
	v_mfma_f32_16x16x32_f16 v[82:85], v[144:147], v[226:229], v[82:85]
	v_mfma_f32_16x16x32_f16 v[78:81], v[178:181], v[226:229], v[78:81]
	v_mfma_f32_16x16x32_f16 v[130:133], v[152:155], v[206:209], v[130:133]
	v_mfma_f32_16x16x32_f16 v[126:129], v[182:185], v[206:209], v[126:129]
	v_mfma_f32_16x16x32_f16 v[114:117], v[152:155], v[214:217], v[114:117]
	v_mfma_f32_16x16x32_f16 v[110:113], v[182:185], v[214:217], v[110:113]
	v_mfma_f32_16x16x32_f16 v[98:101], v[152:155], v[222:225], v[98:101]
	v_mfma_f32_16x16x32_f16 v[94:97], v[182:185], v[222:225], v[94:97]
	v_mfma_f32_16x16x32_f16 v[82:85], v[152:155], v[230:233], v[82:85]
	v_mfma_f32_16x16x32_f16 v[78:81], v[182:185], v[230:233], v[78:81]
	v_mfma_f32_16x16x32_f16 v[122:125], v[186:189], v[202:205], v[122:125]
	v_mfma_f32_16x16x32_f16 v[118:121], v[194:197], v[202:205], v[118:121]
	v_mfma_f32_16x16x32_f16 v[106:109], v[186:189], v[210:213], v[106:109]
	v_mfma_f32_16x16x32_f16 v[102:105], v[194:197], v[210:213], v[102:105]
	v_mfma_f32_16x16x32_f16 v[90:93], v[186:189], v[218:221], v[90:93]
	v_mfma_f32_16x16x32_f16 v[86:89], v[194:197], v[218:221], v[86:89]
	v_mfma_f32_16x16x32_f16 v[74:77], v[186:189], v[226:229], v[74:77]
	v_mfma_f32_16x16x32_f16 v[70:73], v[194:197], v[226:229], v[70:73]
	v_mfma_f32_16x16x32_f16 v[122:125], v[190:193], v[206:209], v[122:125]
	v_mfma_f32_16x16x32_f16 v[118:121], v[198:201], v[206:209], v[118:121]
	v_mfma_f32_16x16x32_f16 v[106:109], v[190:193], v[214:217], v[106:109]
	v_mfma_f32_16x16x32_f16 v[102:105], v[198:201], v[214:217], v[102:105]
	v_mfma_f32_16x16x32_f16 v[90:93], v[190:193], v[222:225], v[90:93]
	v_mfma_f32_16x16x32_f16 v[86:89], v[198:201], v[222:225], v[86:89]
	v_mfma_f32_16x16x32_f16 v[74:77], v[190:193], v[230:233], v[74:77]
	v_mfma_f32_16x16x32_f16 v[70:73], v[198:201], v[230:233], v[70:73]
	s_barrier
; #define STAGE(bufoff, gbase, voff) do { _Pragma("unroll") for (int _i = 0; _i < 2; ++_i) \
;     __builtin_amdgcn_global_load_lds((const unsigned*)((const char*)(gbase) + (voff)[_i]), (LAS unsigned*)(lds + (bufoff) + ldsw + _i * 8192), 16, 0, 0); } while (0)
; #define LDA(dst, b, h) do { _Pragma("unroll") for (int m = 0; m < 4; ++m) _Pragma("unroll") for (int k = 0; k < 2; ++k) dst[m][k] = *(const LAS half8*)(lds + SA(b, h) + aoff + m * 2048 + k * 1024); } while (0)
; #define LDB(dst, b, h) do { _Pragma("unroll") for (int n = 0; n < 2; ++n) _Pragma("unroll") for (int k = 0; k < 2; ++k) dst[n][k] = *(const LAS half8*)(lds + SB(b, h) + boff + n * 2048 + k * 1024); } while (0)
; #define MMA(ai, bj, At_, Bt_) do { __builtin_amdgcn_s_setprio(1); \
;     _Pragma("unroll") for (int m = 0; m < 4; ++m) _Pragma("unroll") for (int n = 0; n < 2; ++n) _Pragma("unroll") for (int k = 0; k < 2; ++k) \
;       acc[ai][bj][m][n] = MFMA16(Bt_[n][k], At_[m][k], acc[ai][bj][m][n]); \
;     __builtin_amdgcn_s_setprio(0); } while (0)
; #define WAIT_V(n) asm volatile("s_waitcnt vmcnt(" #n ")" ::: "memory")
; #define BAR __builtin_amdgcn_s_barrier()
; template <int EPI>
; DI void gemm_phase(const int wid_s, const h16* __restrict__ A, const h16* __restrict__ Bt, const int N, const int K, const EpiArgs ea) {
;     ...
;     for (int t = 0; t < nt; t += 2) {
;       const bool last = (t == nt - 2);
;       const char* a1 = cA + (size_t)(t + 1) * kstep;
;       const char* a2 = last ? nA : cA + (size_t)(t + 2) * kstep; const char* b2 = last ? nB : cB + (size_t)(t + 2) * kstep;
;       const char* a3 = a2 + kstep; const char* b3 = b2 + kstep;
;       LDB(B0, 0, 0); LDB(B1, 0, 1); SCHED; LDA(At, 0, 0); STAGE(SA(1, 1), a1 + hstep, voffA);
;       WAIT_V(8); WAIT_L(0); BAR; MMA(0, 0, At, B0); MMA(0, 1, At, B1); BAR; SCHED;
;       LDA(At, 0, 1); STAGE(SB(0, 0), b2, voffB); STAGE(SB(0, 1), b2 + hstep, voffB); STAGE(SA(0, 0), a2, voffA);
;       WAIT_V(8); WAIT_L(0); BAR; MMA(1, 0, At, B0); MMA(1, 1, At, B1); BAR; SCHED;
;       LDB(B0, 1, 0); LDB(B1, 1, 1); SCHED; LDA(At, 1, 0); STAGE(SA(0, 1), a2 + hstep, voffA);
;       WAIT_V(8); WAIT_L(0); BAR; MMA(0, 0, At, B0); MMA(0, 1, At, B1); BAR; SCHED;
;       LDA(At, 1, 1); STAGE(SB(1, 0), b3, voffB); STAGE(SB(1, 1), b3 + hstep, voffB); STAGE(SA(1, 0), a3, voffA);
;       WAIT_V(8); WAIT_L(0); BAR; MMA(1, 0, At, B0); MMA(1, 1, At, B1); BAR; SCHED;
	s_add_i32 s26, s44, s30
	v_lshl_add_u64 v[234:235], v[234:235], 0, s[36:37]
	s_mov_b32 m0, s26
	ds_read_b128 v[202:205], v151 offset:49152
	ds_read_b128 v[206:209], v151 offset:50176
	ds_read_b128 v[210:213], v151 offset:51200
	ds_read_b128 v[214:217], v151 offset:52224
	ds_read_b128 v[218:221], v151 offset:53248
	ds_read_b128 v[222:225], v151 offset:54272
	ds_read_b128 v[226:229], v151 offset:55296
	ds_read_b128 v[230:233], v151 offset:56320
	global_load_lds_dwordx4 v[234:235], off
	s_add_i32 m0, s26, 0x2000
	s_add_u32 s22, s22, 0x40080
	v_lshl_add_u64 v[234:235], v[236:237], 0, s[36:37]
	s_addc_u32 s23, s23, 0
	s_add_i32 s26, s45, s30
	global_load_lds_dwordx4 v[234:235], off
	v_lshl_add_u64 v[234:235], s[22:23], 0, v[0:1]
	s_mov_b32 m0, s26
	s_nop 0
	global_load_lds_dwordx4 v[234:235], off
	v_lshl_add_u64 v[234:235], s[22:23], 0, v[138:139]
	s_add_i32 m0, s26, 0x2000
	s_nop 0
	global_load_lds_dwordx4 v[234:235], off
	v_lshl_add_u64 v[234:235], v[238:239], 0, s[36:37]
	s_mov_b32 m0, s39
	s_nop 0
	global_load_lds_dwordx4 v[234:235], off
	v_lshl_add_u64 v[234:235], v[240:241], 0, s[36:37]
	s_mov_b32 m0, s40
	s_nop 0
	global_load_lds_dwordx4 v[234:235], off
	s_waitcnt vmcnt(8) lgkmcnt(0)
	s_barrier
	v_mfma_f32_16x16x32_f16 v[66:69], v[144:147], v[202:205], v[66:69]
	v_mfma_f32_16x16x32_f16 v[62:65], v[178:181], v[202:205], v[62:65]
	v_mfma_f32_16x16x32_f16 v[50:53], v[144:147], v[210:213], v[50:53]
	v_mfma_f32_16x16x32_f16 v[46:49], v[178:181], v[210:213], v[46:49]
	v_mfma_f32_16x16x32_f16 v[34:37], v[144:147], v[218:221], v[34:37]
	v_mfma_f32_16x16x32_f16 v[30:33], v[178:181], v[218:221], v[30:33]
	v_mfma_f32_16x16x32_f16 v[18:21], v[144:147], v[226:229], v[18:21]
	v_mfma_f32_16x16x32_f16 v[14:17], v[178:181], v[226:229], v[14:17]
	v_mfma_f32_16x16x32_f16 v[66:69], v[152:155], v[206:209], v[66:69]
	v_mfma_f32_16x16x32_f16 v[62:65], v[182:185], v[206:209], v[62:65]
	v_mfma_f32_16x16x32_f16 v[50:53], v[152:155], v[214:217], v[50:53]
	v_mfma_f32_16x16x32_f16 v[46:49], v[182:185], v[214:217], v[46:49]
	v_mfma_f32_16x16x32_f16 v[34:37], v[152:155], v[222:225], v[34:37]
	v_mfma_f32_16x16x32_f16 v[30:33], v[182:185], v[222:225], v[30:33]
	v_mfma_f32_16x16x32_f16 v[18:21], v[152:155], v[230:233], v[18:21]
	v_mfma_f32_16x16x32_f16 v[14:17], v[182:185], v[230:233], v[14:17]
	v_mfma_f32_16x16x32_f16 v[58:61], v[186:189], v[202:205], v[58:61]
	v_mfma_f32_16x16x32_f16 v[54:57], v[194:197], v[202:205], v[54:57]
	v_mfma_f32_16x16x32_f16 v[42:45], v[186:189], v[210:213], v[42:45]
	v_mfma_f32_16x16x32_f16 v[38:41], v[194:197], v[210:213], v[38:41]
	v_mfma_f32_16x16x32_f16 v[26:29], v[186:189], v[218:221], v[26:29]
	v_mfma_f32_16x16x32_f16 v[22:25], v[194:197], v[218:221], v[22:25]
	v_mfma_f32_16x16x32_f16 v[10:13], v[186:189], v[226:229], v[10:13]
	v_mfma_f32_16x16x32_f16 v[6:9], v[194:197], v[226:229], v[6:9]
	v_mfma_f32_16x16x32_f16 v[58:61], v[190:193], v[206:209], v[58:61]
	v_mfma_f32_16x16x32_f16 v[54:57], v[198:201], v[206:209], v[54:57]
	v_mfma_f32_16x16x32_f16 v[42:45], v[190:193], v[214:217], v[42:45]
	v_mfma_f32_16x16x32_f16 v[38:41], v[198:201], v[214:217], v[38:41]
	v_mfma_f32_16x16x32_f16 v[26:29], v[190:193], v[222:225], v[26:29]
	v_mfma_f32_16x16x32_f16 v[22:25], v[198:201], v[222:225], v[22:25]
	v_mfma_f32_16x16x32_f16 v[10:13], v[190:193], v[230:233], v[10:13]
	v_mfma_f32_16x16x32_f16 v[6:9], v[198:201], v[230:233], v[6:9]
	s_barrier
	s_add_i32 s43, s43, 2
	s_add_u32 s41, s41, 0x100
	s_addc_u32 s42, s42, 0
	s_add_u32 s20, s20, 0x100
	s_addc_u32 s21, s21, 0
	s_cmp_gt_u32 s43, 13
.LBB0_175:
	s_add_u32 s22, s20, 0xfffc0080
	s_addc_u32 s23, s21, -1
	s_add_i32 s44, 0, 0x10000
	s_cmp_eq_u32 s43, 12
	s_cselect_b32 s27, s13, s23
	s_cselect_b32 s26, s12, s22
	v_add_u32_e32 v177, s44, v148
	s_cselect_b32 s23, s11, s42
	s_cselect_b32 s22, s9, s41
	s_add_i32 s46, 0, 0x14000
	ds_read_b128 v[144:147], v177
	ds_read_b128 v[152:155], v177 offset:1024
	ds_read_b128 v[178:181], v177 offset:2048
	ds_read_b128 v[182:185], v177 offset:3072
	v_add_u32_e32 v177, s46, v148
	ds_read_b128 v[186:189], v177
	ds_read_b128 v[190:193], v177 offset:1024
	ds_read_b128 v[194:197], v177 offset:2048
	ds_read_b128 v[198:201], v177 offset:3072
	v_lshl_add_u64 v[234:235], s[20:21], 0, v[142:143]
	s_add_i32 m0, s17, 0xc000
	ds_read_b128 v[202:205], v151
	ds_read_b128 v[206:209], v151 offset:1024
	ds_read_b128 v[210:213], v151 offset:2048
	ds_read_b128 v[214:217], v151 offset:3072
	ds_read_b128 v[218:221], v151 offset:4096
	ds_read_b128 v[222:225], v151 offset:5120
	ds_read_b128 v[226:229], v151 offset:6144
	ds_read_b128 v[230:233], v151 offset:7168
	global_load_lds_dwordx4 v[234:235], off
	v_lshl_add_u64 v[234:235], s[20:21], 0, v[140:141]
	s_add_i32 m0, s17, 0xe000
	s_nop 0
	global_load_lds_dwordx4 v[234:235], off
	s_waitcnt vmcnt(8) lgkmcnt(0)
	s_barrier
; #define STAGE(bufoff, gbase, voff) do { _Pragma("unroll") for (int _i = 0; _i < 2; ++_i) \
;     __builtin_amdgcn_global_load_lds((const unsigned*)((const char*)(gbase) + (voff)[_i]), (LAS unsigned*)(lds + (bufoff) + ldsw + _i * 8192), 16, 0, 0); } while (0)
; #define LDA(dst, b, h) do { _Pragma("unroll") for (int m = 0; m < 4; ++m) _Pragma("unroll") for (int k = 0; k < 2; ++k) dst[m][k] = *(const LAS half8*)(lds + SA(b, h) + aoff + m * 2048 + k * 1024); } while (0)
; #define LDB(dst, b, h) do { _Pragma("unroll") for (int n = 0; n < 2; ++n) _Pragma("unroll") for (int k = 0; k < 2; ++k) dst[n][k] = *(const LAS half8*)(lds + SB(b, h) + boff + n * 2048 + k * 1024); } while (0)
; #define MMA(ai, bj, At_, Bt_) do { __builtin_amdgcn_s_setprio(1); \
;     _Pragma("unroll") for (int m = 0; m < 4; ++m) _Pragma("unroll") for (int n = 0; n < 2; ++n) _Pragma("unroll") for (int k = 0; k < 2; ++k) \
;       acc[ai][bj][m][n] = MFMA16(Bt_[n][k], At_[m][k], acc[ai][bj][m][n]); \
;     __builtin_amdgcn_s_setprio(0); } while (0)
; #define WAIT_V(n) asm volatile("s_waitcnt vmcnt(" #n ")" ::: "memory")
; #define WAIT_L(n) asm volatile("s_waitcnt lgkmcnt(" #n ")" ::: "memory")
; #define BAR __builtin_amdgcn_s_barrier()
; #define SCHED __builtin_amdgcn_sched_barrier(0)
; template <int EPI>
; DI void gemm_phase(const int wid_s, const h16* __restrict__ A, const h16* __restrict__ Bt, const int N, const int K, const EpiArgs ea) {
;     ...
;       LDB(B0, 0, 0); LDB(B1, 0, 1); SCHED; LDA(At, 0, 0); STAGE(SA(1, 1), a1 + hstep, voffA);
;       WAIT_V(8); WAIT_L(0); BAR; MMA(0, 0, At, B0); MMA(0, 1, At, B1); BAR; SCHED;
;       LDA(At, 0, 1); STAGE(SB(0, 0), b2, voffB); STAGE(SB(0, 1), b2 + hstep, voffB); STAGE(SA(0, 0), a2, voffA);
;       WAIT_V(8); WAIT_L(0); BAR; MMA(1, 0, At, B0); MMA(1, 1, At, B1); BAR; SCHED;
;       LDB(B0, 1, 0); LDB(B1, 1, 1); SCHED; LDA(At, 1, 0); STAGE(SA(0, 1), a2 + hstep, voffA);
;       WAIT_V(8); WAIT_L(0); BAR; MMA(0, 0, At, B0); MMA(0, 1, At, B1); BAR; SCHED;
;       LDA(At, 1, 1); STAGE(SB(1, 0), b3, voffB); STAGE(SB(1, 1), b3 + hstep, voffB); STAGE(SA(1, 0), a3, voffA);
;       WAIT_V(8); WAIT_L(0); BAR; MMA(1, 0, At, B0); MMA(1, 1, At, B1); BAR; SCHED;
	v_mfma_f32_16x16x32_f16 v[130:133], v[144:147], v[202:205], v[130:133]
	v_mfma_f32_16x16x32_f16 v[126:129], v[178:181], v[202:205], v[126:129]
	v_mfma_f32_16x16x32_f16 v[114:117], v[144:147], v[210:213], v[114:117]
	v_mfma_f32_16x16x32_f16 v[110:113], v[178:181], v[210:213], v[110:113]
	v_mfma_f32_16x16x32_f16 v[98:101], v[144:147], v[218:221], v[98:101]
	v_mfma_f32_16x16x32_f16 v[94:97], v[178:181], v[218:221], v[94:97]
	v_mfma_f32_16x16x32_f16 v[82:85], v[144:147], v[226:229], v[82:85]
	v_mfma_f32_16x16x32_f16 v[78:81], v[178:181], v[226:229], v[78:81]
	v_mfma_f32_16x16x32_f16 v[130:133], v[152:155], v[206:209], v[130:133]
	v_mfma_f32_16x16x32_f16 v[126:129], v[182:185], v[206:209], v[126:129]
	v_mfma_f32_16x16x32_f16 v[114:117], v[152:155], v[214:217], v[114:117]
	v_mfma_f32_16x16x32_f16 v[110:113], v[182:185], v[214:217], v[110:113]
	v_mfma_f32_16x16x32_f16 v[98:101], v[152:155], v[222:225], v[98:101]
	v_mfma_f32_16x16x32_f16 v[94:97], v[182:185], v[222:225], v[94:97]
	v_mfma_f32_16x16x32_f16 v[82:85], v[152:155], v[230:233], v[82:85]
	v_mfma_f32_16x16x32_f16 v[78:81], v[182:185], v[230:233], v[78:81]
	v_mfma_f32_16x16x32_f16 v[122:125], v[186:189], v[202:205], v[122:125]
	v_mfma_f32_16x16x32_f16 v[118:121], v[194:197], v[202:205], v[118:121]
	v_mfma_f32_16x16x32_f16 v[106:109], v[186:189], v[210:213], v[106:109]
	v_mfma_f32_16x16x32_f16 v[102:105], v[194:197], v[210:213], v[102:105]
	v_mfma_f32_16x16x32_f16 v[90:93], v[186:189], v[218:221], v[90:93]
	v_mfma_f32_16x16x32_f16 v[86:89], v[194:197], v[218:221], v[86:89]
	v_mfma_f32_16x16x32_f16 v[74:77], v[186:189], v[226:229], v[74:77]
	v_mfma_f32_16x16x32_f16 v[70:73], v[194:197], v[226:229], v[70:73]
	v_mfma_f32_16x16x32_f16 v[122:125], v[190:193], v[206:209], v[122:125]
	v_mfma_f32_16x16x32_f16 v[118:121], v[198:201], v[206:209], v[118:121]
	v_mfma_f32_16x16x32_f16 v[106:109], v[190:193], v[214:217], v[106:109]
	v_mfma_f32_16x16x32_f16 v[102:105], v[198:201], v[214:217], v[102:105]
	v_mfma_f32_16x16x32_f16 v[90:93], v[190:193], v[222:225], v[90:93]
	v_mfma_f32_16x16x32_f16 v[86:89], v[198:201], v[222:225], v[86:89]
	v_mfma_f32_16x16x32_f16 v[74:77], v[190:193], v[230:233], v[74:77]
	v_mfma_f32_16x16x32_f16 v[70:73], v[198:201], v[230:233], v[70:73]
	s_barrier
	s_add_i32 s44, s44, s30
	v_lshl_add_u64 v[234:235], s[22:23], 0, v[0:1]
	s_mov_b32 m0, s44
	ds_read_b128 v[202:205], v151 offset:16384
	ds_read_b128 v[206:209], v151 offset:17408
	ds_read_b128 v[210:213], v151 offset:18432
	ds_read_b128 v[214:217], v151 offset:19456
	ds_read_b128 v[218:221], v151 offset:20480
	ds_read_b128 v[222:225], v151 offset:21504
	ds_read_b128 v[226:229], v151 offset:22528
	ds_read_b128 v[230:233], v151 offset:23552
	global_load_lds_dwordx4 v[234:235], off
	s_add_i32 m0, s44, 0x2000
	s_add_u32 s44, s22, 0x40000
	v_lshl_add_u64 v[236:237], s[22:23], 0, v[138:139]
	s_addc_u32 s45, s23, 0
	s_add_i32 s46, s46, s30
	global_load_lds_dwordx4 v[236:237], off
	v_lshl_add_u64 v[238:239], s[44:45], 0, v[0:1]
	s_mov_b32 m0, s46
	v_lshl_add_u64 v[240:241], s[26:27], 0, v[134:135]
	global_load_lds_dwordx4 v[238:239], off
	v_lshl_add_u64 v[238:239], s[44:45], 0, v[138:139]
	s_add_i32 m0, s46, 0x2000
	s_nop 0
	global_load_lds_dwordx4 v[238:239], off
	v_lshl_add_u64 v[238:239], s[26:27], 0, v[2:3]
	s_mov_b32 m0, s17
	s_nop 0
	global_load_lds_dwordx4 v[238:239], off
	s_mov_b32 m0, s19
	s_nop 0
	global_load_lds_dwordx4 v[240:241], off
	s_waitcnt vmcnt(8) lgkmcnt(0)
	s_barrier
	v_mfma_f32_16x16x32_f16 v[66:69], v[144:147], v[202:205], v[66:69]
	v_mfma_f32_16x16x32_f16 v[62:65], v[178:181], v[202:205], v[62:65]
	v_mfma_f32_16x16x32_f16 v[50:53], v[144:147], v[210:213], v[50:53]
	v_mfma_f32_16x16x32_f16 v[46:49], v[178:181], v[210:213], v[46:49]
	v_mfma_f32_16x16x32_f16 v[34:37], v[144:147], v[218:221], v[34:37]
	v_mfma_f32_16x16x32_f16 v[30:33], v[178:181], v[218:221], v[30:33]
	v_mfma_f32_16x16x32_f16 v[18:21], v[144:147], v[226:229], v[18:21]
	v_mfma_f32_16x16x32_f16 v[14:17], v[178:181], v[226:229], v[14:17]
	v_mfma_f32_16x16x32_f16 v[66:69], v[152:155], v[206:209], v[66:69]
	v_mfma_f32_16x16x32_f16 v[62:65], v[182:185], v[206:209], v[62:65]
	v_mfma_f32_16x16x32_f16 v[50:53], v[152:155], v[214:217], v[50:53]
	v_mfma_f32_16x16x32_f16 v[46:49], v[182:185], v[214:217], v[46:49]
	v_mfma_f32_16x16x32_f16 v[34:37], v[152:155], v[222:225], v[34:37]
	v_mfma_f32_16x16x32_f16 v[30:33], v[182:185], v[222:225], v[30:33]
	v_mfma_f32_16x16x32_f16 v[18:21], v[152:155], v[230:233], v[18:21]
	v_mfma_f32_16x16x32_f16 v[14:17], v[182:185], v[230:233], v[14:17]
	v_mfma_f32_16x16x32_f16 v[58:61], v[186:189], v[202:205], v[58:61]
	v_mfma_f32_16x16x32_f16 v[54:57], v[194:197], v[202:205], v[54:57]
	v_mfma_f32_16x16x32_f16 v[42:45], v[186:189], v[210:213], v[42:45]
	v_mfma_f32_16x16x32_f16 v[38:41], v[194:197], v[210:213], v[38:41]
	v_mfma_f32_16x16x32_f16 v[26:29], v[186:189], v[218:221], v[26:29]
	v_mfma_f32_16x16x32_f16 v[22:25], v[194:197], v[218:221], v[22:25]
	v_mfma_f32_16x16x32_f16 v[10:13], v[186:189], v[226:229], v[10:13]
	v_mfma_f32_16x16x32_f16 v[6:9], v[194:197], v[226:229], v[6:9]
	v_mfma_f32_16x16x32_f16 v[58:61], v[190:193], v[206:209], v[58:61]
	v_mfma_f32_16x16x32_f16 v[54:57], v[198:201], v[206:209], v[54:57]
	v_mfma_f32_16x16x32_f16 v[42:45], v[190:193], v[214:217], v[42:45]
	v_mfma_f32_16x16x32_f16 v[38:41], v[198:201], v[214:217], v[38:41]
	v_mfma_f32_16x16x32_f16 v[26:29], v[190:193], v[222:225], v[26:29]
	v_mfma_f32_16x16x32_f16 v[22:25], v[198:201], v[222:225], v[22:25]
	v_mfma_f32_16x16x32_f16 v[10:13], v[190:193], v[230:233], v[10:13]
	v_mfma_f32_16x16x32_f16 v[6:9], v[198:201], v[230:233], v[6:9]
	s_barrier
; #define STAGE(bufoff, gbase, voff) do { _Pragma("unroll") for (int _i = 0; _i < 2; ++_i) \
;     __builtin_amdgcn_global_load_lds((const unsigned*)((const char*)(gbase) + (voff)[_i]), (LAS unsigned*)(lds + (bufoff) + ldsw + _i * 8192), 16, 0, 0); } while (0)
; #define LDA(dst, b, h) do { _Pragma("unroll") for (int m = 0; m < 4; ++m) _Pragma("unroll") for (int k = 0; k < 2; ++k) dst[m][k] = *(const LAS half8*)(lds + SA(b, h) + aoff + m * 2048 + k * 1024); } while (0)
; #define LDB(dst, b, h) do { _Pragma("unroll") for (int n = 0; n < 2; ++n) _Pragma("unroll") for (int k = 0; k < 2; ++k) dst[n][k] = *(const LAS half8*)(lds + SB(b, h) + boff + n * 2048 + k * 1024); } while (0)
; #define MMA(ai, bj, At_, Bt_) do { __builtin_amdgcn_s_setprio(1); \
;     _Pragma("unroll") for (int m = 0; m < 4; ++m) _Pragma("unroll") for (int n = 0; n < 2; ++n) _Pragma("unroll") for (int k = 0; k < 2; ++k) \
;       acc[ai][bj][m][n] = MFMA16(Bt_[n][k], At_[m][k], acc[ai][bj][m][n]); \
;     __builtin_amdgcn_s_setprio(0); } while (0)
; #define WAIT_V(n) asm volatile("s_waitcnt vmcnt(" #n ")" ::: "memory")
; #define WAIT_L(n) asm volatile("s_waitcnt lgkmcnt(" #n ")" ::: "memory")
; #define BAR __builtin_amdgcn_s_barrier()
; #define SCHED __builtin_amdgcn_sched_barrier(0)
; template <int EPI>
; DI void gemm_phase(const int wid_s, const h16* __restrict__ A, const h16* __restrict__ Bt, const int N, const int K, const EpiArgs ea) {
;     ...
;       LDB(B0, 1, 0); LDB(B1, 1, 1); SCHED; LDA(At, 1, 0); STAGE(SA(0, 1), a2 + hstep, voffA);
;       WAIT_V(8); WAIT_L(0); BAR; MMA(0, 0, At, B0); MMA(0, 1, At, B1); BAR; SCHED;
;       LDA(At, 1, 1); STAGE(SB(1, 0), b3, voffB); STAGE(SB(1, 1), b3 + hstep, voffB); STAGE(SA(1, 0), a3, voffA);
;       WAIT_V(8); WAIT_L(0); BAR; MMA(1, 0, At, B0); MMA(1, 1, At, B1); BAR; SCHED;
;     }
;     if (wr == 0) BAR;
	s_add_i32 s44, 0, 0x18000
	v_add_u32_e32 v177, s44, v148
	s_add_i32 s45, 0, 0x1c000
	ds_read_b128 v[144:147], v177
	ds_read_b128 v[152:155], v177 offset:1024
	ds_read_b128 v[178:181], v177 offset:2048
	ds_read_b128 v[182:185], v177 offset:3072
	v_add_u32_e32 v177, s45, v148
	ds_read_b128 v[186:189], v177
	ds_read_b128 v[190:193], v177 offset:1024
	ds_read_b128 v[194:197], v177 offset:2048
	ds_read_b128 v[198:201], v177 offset:3072
	s_add_u32 s26, s26, 0x40000
	s_addc_u32 s27, s27, 0
	s_mov_b32 m0, s31
	v_lshl_add_u64 v[242:243], s[26:27], 0, v[2:3]
	ds_read_b128 v[202:205], v151 offset:32768
	ds_read_b128 v[206:209], v151 offset:33792
	ds_read_b128 v[210:213], v151 offset:34816
	ds_read_b128 v[214:217], v151 offset:35840
	ds_read_b128 v[218:221], v151 offset:36864
	ds_read_b128 v[222:225], v151 offset:37888
	ds_read_b128 v[226:229], v151 offset:38912
	ds_read_b128 v[230:233], v151 offset:39936
	global_load_lds_dwordx4 v[242:243], off
	v_lshl_add_u64 v[242:243], s[26:27], 0, v[134:135]
	s_mov_b32 m0, s38
	s_nop 0
	global_load_lds_dwordx4 v[242:243], off
	s_waitcnt vmcnt(8) lgkmcnt(0)
	s_barrier
	v_mfma_f32_16x16x32_f16 v[130:133], v[144:147], v[202:205], v[130:133]
	v_mfma_f32_16x16x32_f16 v[126:129], v[178:181], v[202:205], v[126:129]
	v_mfma_f32_16x16x32_f16 v[114:117], v[144:147], v[210:213], v[114:117]
	v_mfma_f32_16x16x32_f16 v[110:113], v[178:181], v[210:213], v[110:113]
	v_mfma_f32_16x16x32_f16 v[98:101], v[144:147], v[218:221], v[98:101]
	v_mfma_f32_16x16x32_f16 v[94:97], v[178:181], v[218:221], v[94:97]
	v_mfma_f32_16x16x32_f16 v[82:85], v[144:147], v[226:229], v[82:85]
	v_mfma_f32_16x16x32_f16 v[78:81], v[178:181], v[226:229], v[78:81]
	v_mfma_f32_16x16x32_f16 v[130:133], v[152:155], v[206:209], v[130:133]
	v_mfma_f32_16x16x32_f16 v[126:129], v[182:185], v[206:209], v[126:129]
	v_mfma_f32_16x16x32_f16 v[114:117], v[152:155], v[214:217], v[114:117]
	v_mfma_f32_16x16x32_f16 v[110:113], v[182:185], v[214:217], v[110:113]
	v_mfma_f32_16x16x32_f16 v[98:101], v[152:155], v[222:225], v[98:101]
	v_mfma_f32_16x16x32_f16 v[94:97], v[182:185], v[222:225], v[94:97]
	v_mfma_f32_16x16x32_f16 v[82:85], v[152:155], v[230:233], v[82:85]
	v_mfma_f32_16x16x32_f16 v[78:81], v[182:185], v[230:233], v[78:81]
	v_mfma_f32_16x16x32_f16 v[122:125], v[186:189], v[202:205], v[122:125]
	v_mfma_f32_16x16x32_f16 v[118:121], v[194:197], v[202:205], v[118:121]
	v_mfma_f32_16x16x32_f16 v[106:109], v[186:189], v[210:213], v[106:109]
	v_mfma_f32_16x16x32_f16 v[102:105], v[194:197], v[210:213], v[102:105]
	v_mfma_f32_16x16x32_f16 v[90:93], v[186:189], v[218:221], v[90:93]
	v_mfma_f32_16x16x32_f16 v[86:89], v[194:197], v[218:221], v[86:89]
	v_mfma_f32_16x16x32_f16 v[74:77], v[186:189], v[226:229], v[74:77]
	v_mfma_f32_16x16x32_f16 v[70:73], v[194:197], v[226:229], v[70:73]
	v_mfma_f32_16x16x32_f16 v[122:125], v[190:193], v[206:209], v[122:125]
	v_mfma_f32_16x16x32_f16 v[118:121], v[198:201], v[206:209], v[118:121]
	v_mfma_f32_16x16x32_f16 v[106:109], v[190:193], v[214:217], v[106:109]
	v_mfma_f32_16x16x32_f16 v[102:105], v[198:201], v[214:217], v[102:105]
	v_mfma_f32_16x16x32_f16 v[90:93], v[190:193], v[222:225], v[90:93]
	v_mfma_f32_16x16x32_f16 v[86:89], v[198:201], v[222:225], v[86:89]
	v_mfma_f32_16x16x32_f16 v[74:77], v[190:193], v[230:233], v[74:77]
	v_mfma_f32_16x16x32_f16 v[70:73], v[198:201], v[230:233], v[70:73]
	s_barrier
	s_add_i32 s26, s44, s30
	v_lshl_add_u64 v[234:235], v[234:235], 0, s[36:37]
	s_mov_b32 m0, s26
	ds_read_b128 v[202:205], v151 offset:49152
	ds_read_b128 v[206:209], v151 offset:50176
	ds_read_b128 v[210:213], v151 offset:51200
	ds_read_b128 v[214:217], v151 offset:52224
	ds_read_b128 v[218:221], v151 offset:53248
	ds_read_b128 v[222:225], v151 offset:54272
	ds_read_b128 v[226:229], v151 offset:55296
	ds_read_b128 v[230:233], v151 offset:56320
	global_load_lds_dwordx4 v[234:235], off
	s_add_i32 m0, s26, 0x2000
	s_add_u32 s22, s22, 0x40080
	v_lshl_add_u64 v[234:235], v[236:237], 0, s[36:37]
	s_addc_u32 s23, s23, 0
	s_add_i32 s26, s45, s30
	global_load_lds_dwordx4 v[234:235], off
	v_lshl_add_u64 v[234:235], s[22:23], 0, v[0:1]
	s_mov_b32 m0, s26
	s_nop 0
	global_load_lds_dwordx4 v[234:235], off
	v_lshl_add_u64 v[234:235], s[22:23], 0, v[138:139]
	s_add_i32 m0, s26, 0x2000
	s_nop 0
	global_load_lds_dwordx4 v[234:235], off
	v_lshl_add_u64 v[234:235], v[238:239], 0, s[36:37]
	s_mov_b32 m0, s39
	s_nop 0
	global_load_lds_dwordx4 v[234:235], off
	v_lshl_add_u64 v[234:235], v[240:241], 0, s[36:37]
	s_mov_b32 m0, s40
	s_nop 0
	global_load_lds_dwordx4 v[234:235], off
	s_waitcnt vmcnt(8) lgkmcnt(0)
	s_barrier
	v_mfma_f32_16x16x32_f16 v[66:69], v[144:147], v[202:205], v[66:69]
	v_mfma_f32_16x16x32_f16 v[62:65], v[178:181], v[202:205], v[62:65]
	v_mfma_f32_16x16x32_f16 v[50:53], v[144:147], v[210:213], v[50:53]
	v_mfma_f32_16x16x32_f16 v[46:49], v[178:181], v[210:213], v[46:49]
	v_mfma_f32_16x16x32_f16 v[34:37], v[144:147], v[218:221], v[34:37]
	v_mfma_f32_16x16x32_f16 v[30:33], v[178:181], v[218:221], v[30:33]
	v_mfma_f32_16x16x32_f16 v[18:21], v[144:147], v[226:229], v[18:21]
	v_mfma_f32_16x16x32_f16 v[14:17], v[178:181], v[226:229], v[14:17]
	v_mfma_f32_16x16x32_f16 v[66:69], v[152:155], v[206:209], v[66:69]
	v_mfma_f32_16x16x32_f16 v[62:65], v[182:185], v[206:209], v[62:65]
	v_mfma_f32_16x16x32_f16 v[50:53], v[152:155], v[214:217], v[50:53]
	v_mfma_f32_16x16x32_f16 v[46:49], v[182:185], v[214:217], v[46:49]
	v_mfma_f32_16x16x32_f16 v[34:37], v[152:155], v[222:225], v[34:37]
	v_mfma_f32_16x16x32_f16 v[30:33], v[182:185], v[222:225], v[30:33]
	v_mfma_f32_16x16x32_f16 v[18:21], v[152:155], v[230:233], v[18:21]
	v_mfma_f32_16x16x32_f16 v[14:17], v[182:185], v[230:233], v[14:17]
	v_mfma_f32_16x16x32_f16 v[58:61], v[186:189], v[202:205], v[58:61]
	v_mfma_f32_16x16x32_f16 v[54:57], v[194:197], v[202:205], v[54:57]
	v_mfma_f32_16x16x32_f16 v[42:45], v[186:189], v[210:213], v[42:45]
	v_mfma_f32_16x16x32_f16 v[38:41], v[194:197], v[210:213], v[38:41]
	v_mfma_f32_16x16x32_f16 v[26:29], v[186:189], v[218:221], v[26:29]
	v_mfma_f32_16x16x32_f16 v[22:25], v[194:197], v[218:221], v[22:25]
	v_mfma_f32_16x16x32_f16 v[10:13], v[186:189], v[226:229], v[10:13]
	v_mfma_f32_16x16x32_f16 v[6:9], v[194:197], v[226:229], v[6:9]
	v_mfma_f32_16x16x32_f16 v[58:61], v[190:193], v[206:209], v[58:61]
	v_mfma_f32_16x16x32_f16 v[54:57], v[198:201], v[206:209], v[54:57]
	v_mfma_f32_16x16x32_f16 v[42:45], v[190:193], v[214:217], v[42:45]
	v_mfma_f32_16x16x32_f16 v[38:41], v[198:201], v[214:217], v[38:41]
	v_mfma_f32_16x16x32_f16 v[26:29], v[190:193], v[222:225], v[26:29]
	v_mfma_f32_16x16x32_f16 v[22:25], v[198:201], v[222:225], v[22:25]
	v_mfma_f32_16x16x32_f16 v[10:13], v[190:193], v[230:233], v[10:13]
	v_mfma_f32_16x16x32_f16 v[6:9], v[198:201], v[230:233], v[6:9]
	s_barrier
	s_add_i32 s43, s43, 2
	s_add_u32 s41, s41, 0x100
	s_addc_u32 s42, s42, 0
	s_add_u32 s20, s20, 0x100
	s_addc_u32 s21, s21, 0
	s_cmp_gt_u32 s43, 13
	s_cbranch_scc0 .LBB0_175
	s_and_b64 vcc, exec, s[4:5]
	s_cbranch_vccz .LBB0_178
	s_barrier

; #define STAGE(bufoff, gbase, voff) do { _Pragma("unroll") for (int _i = 0; _i < 2; ++_i) \
;     __builtin_amdgcn_global_load_lds((const unsigned*)((const char*)(gbase) + (voff)[_i]), (LAS unsigned*)(lds + (bufoff) + ldsw + _i * 8192), 16, 0, 0); } while (0)
; #define LDA(dst, b, h) do { _Pragma("unroll") for (int m = 0; m < 4; ++m) _Pragma("unroll") for (int k = 0; k < 2; ++k) dst[m][k] = *(const LAS half8*)(lds + SA(b, h) + aoff + m * 2048 + k * 1024); } while (0)
; #define LDB(dst, b, h) do { _Pragma("unroll") for (int n = 0; n < 2; ++n) _Pragma("unroll") for (int k = 0; k < 2; ++k) dst[n][k] = *(const LAS half8*)(lds + SB(b, h) + boff + n * 2048 + k * 1024); } while (0)
; #define MMA(ai, bj, At_, Bt_) do { __builtin_amdgcn_s_setprio(1); \
;     _Pragma("unroll") for (int m = 0; m < 4; ++m) _Pragma("unroll") for (int n = 0; n < 2; ++n) _Pragma("unroll") for (int k = 0; k < 2; ++k) \
;       acc[ai][bj][m][n] = MFMA16(Bt_[n][k], At_[m][k], acc[ai][bj][m][n]); \
;     __builtin_amdgcn_s_setprio(0); } while (0)
; #define WAIT_V(n) asm volatile("s_waitcnt vmcnt(" #n ")" ::: "memory")
; #define WAIT_L(n) asm volatile("s_waitcnt lgkmcnt(" #n ")" ::: "memory")
; #define BAR __builtin_amdgcn_s_barrier()
; #define SCHED __builtin_amdgcn_sched_barrier(0)
; template <int EPI>
; DI void gemm_phase(const int wid_s, const h16* __restrict__ A, const h16* __restrict__ Bt, const int N, const int K, const EpiArgs ea) {
;     ...
;     const char* nA = (const char*)A + (size_t)nbrow * K * 2;
;     const char* nB = (const char*)Bt + (size_t)nbcol * K * 2;
;     for (int t = 0; t < nt; t += 2) {
;       const bool last = (t == nt - 2);
;       const char* a1 = cA + (size_t)(t + 1) * kstep;
;       const char* a2 = last ? nA : cA + (size_t)(t + 2) * kstep; const char* b2 = last ? nB : cB + (size_t)(t + 2) * kstep;
;       const char* a3 = a2 + kstep; const char* b3 = b2 + kstep;
;       LDB(B0, 0, 0); LDB(B1, 0, 1); SCHED; LDA(At, 0, 0); STAGE(SA(1, 1), a1 + hstep, voffA);
;       WAIT_V(8); WAIT_L(0); BAR; MMA(0, 0, At, B0); MMA(0, 1, At, B1); BAR; SCHED;
;       LDA(At, 0, 1); STAGE(SB(0, 0), b2, voffB); STAGE(SB(0, 1), b2 + hstep, voffB); STAGE(SA(0, 0), a2, voffA);
.LBB0_385:
	s_ashr_i32 s9, s8, 31
	s_lshl_b64 s[16:17], s[8:9], 11
	s_add_u32 s9, s92, s16
	s_addc_u32 s41, s93, s17
	s_ashr_i32 s11, s10, 31
	s_lshl_b64 s[18:19], s[10:11], 11
	v_readlane_b32 s11, v249, 29
	s_add_u32 s11, s11, s18
	v_readlane_b32 s26, v249, 31
	s_addc_u32 s42, s26, s19
	v_readlane_b32 s26, v249, 30
	s_add_u32 s43, s26, s22
	v_readlane_b32 s22, v249, 32
	s_addc_u32 s44, s22, s23
	s_add_u32 s45, s86, s20
	v_mov_b32_e32 v6, 0
	v_lshl_add_u64 v[144:145], v[140:141], 0, s[20:21]
	v_lshl_add_u64 v[146:147], v[142:143], 0, s[20:21]
	s_addc_u32 s46, s87, s21
	s_mov_b32 s47, -2
	s_mov_b64 s[20:21], 0
	s_add_u32 s22, s45, s20
	s_addc_u32 s23, s46, s21
	s_add_u32 s22, s22, 0x520e100
	s_addc_u32 s23, s23, 0
	s_add_u32 s48, s43, s20
	s_addc_u32 s49, s44, s21
	s_add_i32 s50, 0, 0x10000
	s_cmpk_eq_i32 s20, 0x700
	s_cselect_b32 s27, s41, s23
	s_cselect_b32 s26, s9, s22
	v_add_u32_e32 v177, s50, v148
	s_cselect_b32 s23, s42, s49
	s_cselect_b32 s22, s11, s48
	s_add_i32 s51, 0, 0x14000
	ds_read_b128 v[152:155], v177
	ds_read_b128 v[178:181], v177 offset:1024
	ds_read_b128 v[182:185], v177 offset:2048
	ds_read_b128 v[186:189], v177 offset:3072
	v_add_u32_e32 v177, s51, v148
	ds_read_b128 v[190:193], v177
	ds_read_b128 v[194:197], v177 offset:1024
	ds_read_b128 v[198:201], v177 offset:2048
	ds_read_b128 v[202:205], v177 offset:3072
	v_lshl_add_u64 v[238:239], v[146:147], 0, s[20:21]
	s_add_i32 m0, s13, 0xc000
	ds_read_b128 v[206:209], v151
	ds_read_b128 v[210:213], v151 offset:1024
	ds_read_b128 v[214:217], v151 offset:2048
	ds_read_b128 v[218:221], v151 offset:3072
	ds_read_b128 v[222:225], v151 offset:4096
	ds_read_b128 v[226:229], v151 offset:5120
	ds_read_b128 v[230:233], v151 offset:6144
	ds_read_b128 v[234:237], v151 offset:7168
	global_load_lds_dwordx4 v[238:239], off
	v_lshl_add_u64 v[238:239], v[144:145], 0, s[20:21]
	s_add_i32 m0, s13, 0xe000
	s_nop 0
	global_load_lds_dwordx4 v[238:239], off
	s_waitcnt vmcnt(8) lgkmcnt(0)
	s_barrier
	v_mfma_f32_16x16x32_f16 v[130:133], v[152:155], v[206:209], 0
	v_mfma_f32_16x16x32_f16 v[126:129], v[182:185], v[206:209], 0
	v_mfma_f32_16x16x32_f16 v[122:125], v[152:155], v[214:217], 0
	v_mfma_f32_16x16x32_f16 v[118:121], v[182:185], v[214:217], 0
	v_mfma_f32_16x16x32_f16 v[106:109], v[152:155], v[222:225], 0
	v_mfma_f32_16x16x32_f16 v[102:105], v[182:185], v[222:225], 0
	v_mfma_f32_16x16x32_f16 v[90:93], v[152:155], v[230:233], 0
	v_mfma_f32_16x16x32_f16 v[86:89], v[182:185], v[230:233], 0
	v_mfma_f32_16x16x32_f16 v[130:133], v[178:181], v[210:213], v[130:133]
	v_mfma_f32_16x16x32_f16 v[126:129], v[186:189], v[210:213], v[126:129]
	v_mfma_f32_16x16x32_f16 v[122:125], v[178:181], v[218:221], v[122:125]
	v_mfma_f32_16x16x32_f16 v[118:121], v[186:189], v[218:221], v[118:121]
	v_mfma_f32_16x16x32_f16 v[106:109], v[178:181], v[226:229], v[106:109]
	v_mfma_f32_16x16x32_f16 v[102:105], v[186:189], v[226:229], v[102:105]
	v_mfma_f32_16x16x32_f16 v[90:93], v[178:181], v[234:237], v[90:93]
	v_mfma_f32_16x16x32_f16 v[86:89], v[186:189], v[234:237], v[86:89]
	v_mfma_f32_16x16x32_f16 v[114:117], v[190:193], v[206:209], 0
	v_mfma_f32_16x16x32_f16 v[110:113], v[198:201], v[206:209], 0
	v_mfma_f32_16x16x32_f16 v[98:101], v[190:193], v[214:217], 0
	v_mfma_f32_16x16x32_f16 v[94:97], v[198:201], v[214:217], 0
	v_mfma_f32_16x16x32_f16 v[82:85], v[190:193], v[222:225], 0
	v_mfma_f32_16x16x32_f16 v[78:81], v[198:201], v[222:225], 0
	v_mfma_f32_16x16x32_f16 v[74:77], v[190:193], v[230:233], 0
	v_mfma_f32_16x16x32_f16 v[70:73], v[198:201], v[230:233], 0
	v_mfma_f32_16x16x32_f16 v[114:117], v[194:197], v[210:213], v[114:117]
	v_mfma_f32_16x16x32_f16 v[110:113], v[202:205], v[210:213], v[110:113]
	v_mfma_f32_16x16x32_f16 v[98:101], v[194:197], v[218:221], v[98:101]
	v_mfma_f32_16x16x32_f16 v[94:97], v[202:205], v[218:221], v[94:97]
	v_mfma_f32_16x16x32_f16 v[82:85], v[194:197], v[226:229], v[82:85]
	v_mfma_f32_16x16x32_f16 v[78:81], v[202:205], v[226:229], v[78:81]
	v_mfma_f32_16x16x32_f16 v[74:77], v[194:197], v[234:237], v[74:77]
	v_mfma_f32_16x16x32_f16 v[70:73], v[202:205], v[234:237], v[70:73]
	s_barrier
	s_add_i32 s48, s50, s30
	v_lshl_add_u64 v[238:239], s[22:23], 0, v[0:1]
	s_mov_b32 m0, s48
	ds_read_b128 v[206:209], v151 offset:16384
	ds_read_b128 v[210:213], v151 offset:17408
	ds_read_b128 v[214:217], v151 offset:18432
	ds_read_b128 v[218:221], v151 offset:19456
	ds_read_b128 v[222:225], v151 offset:20480
	ds_read_b128 v[226:229], v151 offset:21504
	ds_read_b128 v[230:233], v151 offset:22528
	ds_read_b128 v[234:237], v151 offset:23552
	global_load_lds_dwordx4 v[238:239], off
	s_add_i32 m0, s48, 0x2000
	s_add_u32 s48, s22, 0x40000
	v_lshl_add_u64 v[240:241], s[22:23], 0, v[2:3]
	s_addc_u32 s49, s23, 0
	s_add_i32 s50, s51, s30
	global_load_lds_dwordx4 v[240:241], off
	v_lshl_add_u64 v[242:243], s[48:49], 0, v[0:1]
	s_mov_b32 m0, s50
	v_lshl_add_u64 v[244:245], s[26:27], 0, v[134:135]
	global_load_lds_dwordx4 v[242:243], off
	v_lshl_add_u64 v[242:243], s[48:49], 0, v[2:3]
	s_add_i32 m0, s50, 0x2000
	s_nop 0
	global_load_lds_dwordx4 v[242:243], off
	v_lshl_add_u64 v[242:243], s[26:27], 0, v[138:139]
	s_mov_b32 m0, s13
	s_nop 0
	global_load_lds_dwordx4 v[242:243], off
	s_mov_b32 m0, s15
	s_nop 0
	global_load_lds_dwordx4 v[244:245], off
	s_waitcnt vmcnt(8) lgkmcnt(0)
	s_barrier
; #define STAGE(bufoff, gbase, voff) do { _Pragma("unroll") for (int _i = 0; _i < 2; ++_i) \
;     __builtin_amdgcn_global_load_lds((const unsigned*)((const char*)(gbase) + (voff)[_i]), (LAS unsigned*)(lds + (bufoff) + ldsw + _i * 8192), 16, 0, 0); } while (0)
; #define LDA(dst, b, h) do { _Pragma("unroll") for (int m = 0; m < 4; ++m) _Pragma("unroll") for (int k = 0; k < 2; ++k) dst[m][k] = *(const LAS half8*)(lds + SA(b, h) + aoff + m * 2048 + k * 1024); } while (0)
; #define LDB(dst, b, h) do { _Pragma("unroll") for (int n = 0; n < 2; ++n) _Pragma("unroll") for (int k = 0; k < 2; ++k) dst[n][k] = *(const LAS half8*)(lds + SB(b, h) + boff + n * 2048 + k * 1024); } while (0)
; #define MMA(ai, bj, At_, Bt_) do { __builtin_amdgcn_s_setprio(1); \
;     _Pragma("unroll") for (int m = 0; m < 4; ++m) _Pragma("unroll") for (int n = 0; n < 2; ++n) _Pragma("unroll") for (int k = 0; k < 2; ++k) \
;       acc[ai][bj][m][n] = MFMA16(Bt_[n][k], At_[m][k], acc[ai][bj][m][n]); \
;     __builtin_amdgcn_s_setprio(0); } while (0)
; #define WAIT_V(n) asm volatile("s_waitcnt vmcnt(" #n ")" ::: "memory")
; #define WAIT_L(n) asm volatile("s_waitcnt lgkmcnt(" #n ")" ::: "memory")
; #define BAR __builtin_amdgcn_s_barrier()
; #define SCHED __builtin_amdgcn_sched_barrier(0)
; template <int EPI>
; DI void gemm_phase(const int wid_s, const h16* __restrict__ A, const h16* __restrict__ Bt, const int N, const int K, const EpiArgs ea) {
;     ...
;       LDA(At, 0, 1); STAGE(SB(0, 0), b2, voffB); STAGE(SB(0, 1), b2 + hstep, voffB); STAGE(SA(0, 0), a2, voffA);
;       WAIT_V(8); WAIT_L(0); BAR; MMA(1, 0, At, B0); MMA(1, 1, At, B1); BAR; SCHED;
;       LDB(B0, 1, 0); LDB(B1, 1, 1); SCHED; LDA(At, 1, 0); STAGE(SA(0, 1), a2 + hstep, voffA);
;       WAIT_V(8); WAIT_L(0); BAR; MMA(0, 0, At, B0); MMA(0, 1, At, B1); BAR; SCHED;
	v_mfma_f32_16x16x32_f16 v[66:69], v[152:155], v[206:209], 0
	v_mfma_f32_16x16x32_f16 v[62:65], v[182:185], v[206:209], 0
	v_mfma_f32_16x16x32_f16 v[58:61], v[152:155], v[214:217], 0
	v_mfma_f32_16x16x32_f16 v[54:57], v[182:185], v[214:217], 0
	v_mfma_f32_16x16x32_f16 v[42:45], v[152:155], v[222:225], 0
	v_mfma_f32_16x16x32_f16 v[38:41], v[182:185], v[222:225], 0
	v_mfma_f32_16x16x32_f16 v[26:29], v[152:155], v[230:233], 0
	v_mfma_f32_16x16x32_f16 v[22:25], v[182:185], v[230:233], 0
	v_mfma_f32_16x16x32_f16 v[66:69], v[178:181], v[210:213], v[66:69]
	v_mfma_f32_16x16x32_f16 v[62:65], v[186:189], v[210:213], v[62:65]
	v_mfma_f32_16x16x32_f16 v[58:61], v[178:181], v[218:221], v[58:61]
	v_mfma_f32_16x16x32_f16 v[54:57], v[186:189], v[218:221], v[54:57]
	v_mfma_f32_16x16x32_f16 v[42:45], v[178:181], v[226:229], v[42:45]
	v_mfma_f32_16x16x32_f16 v[38:41], v[186:189], v[226:229], v[38:41]
	v_mfma_f32_16x16x32_f16 v[26:29], v[178:181], v[234:237], v[26:29]
	v_mfma_f32_16x16x32_f16 v[22:25], v[186:189], v[234:237], v[22:25]
	v_mfma_f32_16x16x32_f16 v[50:53], v[190:193], v[206:209], 0
	v_mfma_f32_16x16x32_f16 v[46:49], v[198:201], v[206:209], 0
	v_mfma_f32_16x16x32_f16 v[34:37], v[190:193], v[214:217], 0
	v_mfma_f32_16x16x32_f16 v[30:33], v[198:201], v[214:217], 0
	v_mfma_f32_16x16x32_f16 v[18:21], v[190:193], v[222:225], 0
	v_mfma_f32_16x16x32_f16 v[14:17], v[198:201], v[222:225], 0
	v_mfma_f32_16x16x32_f16 v[10:13], v[190:193], v[230:233], 0
	v_mfma_f32_16x16x32_f16 v[6:9], v[198:201], v[230:233], 0
	v_mfma_f32_16x16x32_f16 v[50:53], v[194:197], v[210:213], v[50:53]
	v_mfma_f32_16x16x32_f16 v[46:49], v[202:205], v[210:213], v[46:49]
	v_mfma_f32_16x16x32_f16 v[34:37], v[194:197], v[218:221], v[34:37]
	v_mfma_f32_16x16x32_f16 v[30:33], v[202:205], v[218:221], v[30:33]
	v_mfma_f32_16x16x32_f16 v[18:21], v[194:197], v[226:229], v[18:21]
	v_mfma_f32_16x16x32_f16 v[14:17], v[202:205], v[226:229], v[14:17]
	v_mfma_f32_16x16x32_f16 v[10:13], v[194:197], v[234:237], v[10:13]
	v_mfma_f32_16x16x32_f16 v[6:9], v[202:205], v[234:237], v[6:9]
	s_barrier
	s_add_i32 s48, 0, 0x18000
	v_add_u32_e32 v177, s48, v148
	s_add_i32 s49, 0, 0x1c000
	ds_read_b128 v[152:155], v177
	ds_read_b128 v[178:181], v177 offset:1024
	ds_read_b128 v[182:185], v177 offset:2048
	ds_read_b128 v[186:189], v177 offset:3072
	v_add_u32_e32 v177, s49, v148
	ds_read_b128 v[190:193], v177
	ds_read_b128 v[194:197], v177 offset:1024
	ds_read_b128 v[198:201], v177 offset:2048
	ds_read_b128 v[202:205], v177 offset:3072
	s_add_u32 s26, s26, 0x40000
	s_addc_u32 s27, s27, 0
	s_mov_b32 m0, s31
	v_lshl_add_u64 v[246:247], s[26:27], 0, v[138:139]
	ds_read_b128 v[206:209], v151 offset:32768
	ds_read_b128 v[210:213], v151 offset:33792
	ds_read_b128 v[214:217], v151 offset:34816
	ds_read_b128 v[218:221], v151 offset:35840
	ds_read_b128 v[222:225], v151 offset:36864
	ds_read_b128 v[226:229], v151 offset:37888
	ds_read_b128 v[230:233], v151 offset:38912
	ds_read_b128 v[234:237], v151 offset:39936
	global_load_lds_dwordx4 v[246:247], off
	v_lshl_add_u64 v[246:247], s[26:27], 0, v[134:135]
	s_mov_b32 m0, s38
	s_nop 0
	global_load_lds_dwordx4 v[246:247], off
	s_waitcnt vmcnt(8) lgkmcnt(0)
	s_barrier
	v_mfma_f32_16x16x32_f16 v[130:133], v[152:155], v[206:209], v[130:133]
	v_mfma_f32_16x16x32_f16 v[126:129], v[182:185], v[206:209], v[126:129]
	v_mfma_f32_16x16x32_f16 v[122:125], v[152:155], v[214:217], v[122:125]
	v_mfma_f32_16x16x32_f16 v[118:121], v[182:185], v[214:217], v[118:121]
	v_mfma_f32_16x16x32_f16 v[106:109], v[152:155], v[222:225], v[106:109]
	v_mfma_f32_16x16x32_f16 v[102:105], v[182:185], v[222:225], v[102:105]
	v_mfma_f32_16x16x32_f16 v[90:93], v[152:155], v[230:233], v[90:93]
	v_mfma_f32_16x16x32_f16 v[86:89], v[182:185], v[230:233], v[86:89]
	v_mfma_f32_16x16x32_f16 v[130:133], v[178:181], v[210:213], v[130:133]
	v_mfma_f32_16x16x32_f16 v[126:129], v[186:189], v[210:213], v[126:129]
	v_mfma_f32_16x16x32_f16 v[122:125], v[178:181], v[218:221], v[122:125]
	v_mfma_f32_16x16x32_f16 v[118:121], v[186:189], v[218:221], v[118:121]
	v_mfma_f32_16x16x32_f16 v[106:109], v[178:181], v[226:229], v[106:109]
	v_mfma_f32_16x16x32_f16 v[102:105], v[186:189], v[226:229], v[102:105]
	v_mfma_f32_16x16x32_f16 v[90:93], v[178:181], v[234:237], v[90:93]
	v_mfma_f32_16x16x32_f16 v[86:89], v[186:189], v[234:237], v[86:89]
	v_mfma_f32_16x16x32_f16 v[114:117], v[190:193], v[206:209], v[114:117]
	v_mfma_f32_16x16x32_f16 v[110:113], v[198:201], v[206:209], v[110:113]
	v_mfma_f32_16x16x32_f16 v[98:101], v[190:193], v[214:217], v[98:101]
	v_mfma_f32_16x16x32_f16 v[94:97], v[198:201], v[214:217], v[94:97]
	v_mfma_f32_16x16x32_f16 v[82:85], v[190:193], v[222:225], v[82:85]
	v_mfma_f32_16x16x32_f16 v[78:81], v[198:201], v[222:225], v[78:81]
	v_mfma_f32_16x16x32_f16 v[74:77], v[190:193], v[230:233], v[74:77]
	v_mfma_f32_16x16x32_f16 v[70:73], v[198:201], v[230:233], v[70:73]
	v_mfma_f32_16x16x32_f16 v[114:117], v[194:197], v[210:213], v[114:117]
	v_mfma_f32_16x16x32_f16 v[110:113], v[202:205], v[210:213], v[110:113]
	v_mfma_f32_16x16x32_f16 v[98:101], v[194:197], v[218:221], v[98:101]
	v_mfma_f32_16x16x32_f16 v[94:97], v[202:205], v[218:221], v[94:97]
	v_mfma_f32_16x16x32_f16 v[82:85], v[194:197], v[226:229], v[82:85]
	v_mfma_f32_16x16x32_f16 v[78:81], v[202:205], v[226:229], v[78:81]
	v_mfma_f32_16x16x32_f16 v[74:77], v[194:197], v[234:237], v[74:77]
	v_mfma_f32_16x16x32_f16 v[70:73], v[202:205], v[234:237], v[70:73]
	s_barrier
; #define STAGE(bufoff, gbase, voff) do { _Pragma("unroll") for (int _i = 0; _i < 2; ++_i) \
;     __builtin_amdgcn_global_load_lds((const unsigned*)((const char*)(gbase) + (voff)[_i]), (LAS unsigned*)(lds + (bufoff) + ldsw + _i * 8192), 16, 0, 0); } while (0)
; #define LDA(dst, b, h) do { _Pragma("unroll") for (int m = 0; m < 4; ++m) _Pragma("unroll") for (int k = 0; k < 2; ++k) dst[m][k] = *(const LAS half8*)(lds + SA(b, h) + aoff + m * 2048 + k * 1024); } while (0)
; #define LDB(dst, b, h) do { _Pragma("unroll") for (int n = 0; n < 2; ++n) _Pragma("unroll") for (int k = 0; k < 2; ++k) dst[n][k] = *(const LAS half8*)(lds + SB(b, h) + boff + n * 2048 + k * 1024); } while (0)
; #define MMA(ai, bj, At_, Bt_) do { __builtin_amdgcn_s_setprio(1); \
;     _Pragma("unroll") for (int m = 0; m < 4; ++m) _Pragma("unroll") for (int n = 0; n < 2; ++n) _Pragma("unroll") for (int k = 0; k < 2; ++k) \
;       acc[ai][bj][m][n] = MFMA16(Bt_[n][k], At_[m][k], acc[ai][bj][m][n]); \
;     __builtin_amdgcn_s_setprio(0); } while (0)
; #define WAIT_V(n) asm volatile("s_waitcnt vmcnt(" #n ")" ::: "memory")
; #define WAIT_L(n) asm volatile("s_waitcnt lgkmcnt(" #n ")" ::: "memory")
; #define BAR __builtin_amdgcn_s_barrier()
; #define SCHED __builtin_amdgcn_sched_barrier(0)
; template <int EPI>
; DI void gemm_phase(const int wid_s, const h16* __restrict__ A, const h16* __restrict__ Bt, const int N, const int K, const EpiArgs ea) {
;     ...
;     for (int t = 0; t < nt; t += 2) {
;       const bool last = (t == nt - 2);
;       const char* a1 = cA + (size_t)(t + 1) * kstep;
;       const char* a2 = last ? nA : cA + (size_t)(t + 2) * kstep; const char* b2 = last ? nB : cB + (size_t)(t + 2) * kstep;
;       const char* a3 = a2 + kstep; const char* b3 = b2 + kstep;
;       LDB(B0, 0, 0); LDB(B1, 0, 1); SCHED; LDA(At, 0, 0); STAGE(SA(1, 1), a1 + hstep, voffA);
;       WAIT_V(8); WAIT_L(0); BAR; MMA(0, 0, At, B0); MMA(0, 1, At, B1); BAR; SCHED;
;     ...
;       LDA(At, 1, 1); STAGE(SB(1, 0), b3, voffB); STAGE(SB(1, 1), b3 + hstep, voffB); STAGE(SA(1, 0), a3, voffA);
;       WAIT_V(8); WAIT_L(0); BAR; MMA(1, 0, At, B0); MMA(1, 1, At, B1); BAR; SCHED;
	s_add_i32 s26, s48, s30
	v_lshl_add_u64 v[238:239], v[238:239], 0, s[36:37]
	s_mov_b32 m0, s26
	ds_read_b128 v[206:209], v151 offset:49152
	ds_read_b128 v[210:213], v151 offset:50176
	ds_read_b128 v[214:217], v151 offset:51200
	ds_read_b128 v[218:221], v151 offset:52224
	ds_read_b128 v[222:225], v151 offset:53248
	ds_read_b128 v[226:229], v151 offset:54272
	ds_read_b128 v[230:233], v151 offset:55296
	ds_read_b128 v[234:237], v151 offset:56320
	global_load_lds_dwordx4 v[238:239], off
	s_add_i32 m0, s26, 0x2000
	s_add_u32 s22, s22, 0x40080
	v_lshl_add_u64 v[238:239], v[240:241], 0, s[36:37]
	s_addc_u32 s23, s23, 0
	s_add_i32 s26, s49, s30
	global_load_lds_dwordx4 v[238:239], off
	v_lshl_add_u64 v[238:239], s[22:23], 0, v[0:1]
	s_mov_b32 m0, s26
	s_nop 0
	global_load_lds_dwordx4 v[238:239], off
	v_lshl_add_u64 v[238:239], s[22:23], 0, v[2:3]
	s_add_i32 m0, s26, 0x2000
	s_nop 0
	global_load_lds_dwordx4 v[238:239], off
	v_lshl_add_u64 v[238:239], v[242:243], 0, s[36:37]
	s_mov_b32 m0, s39
	s_nop 0
	global_load_lds_dwordx4 v[238:239], off
	v_lshl_add_u64 v[238:239], v[244:245], 0, s[36:37]
	s_mov_b32 m0, s40
	s_nop 0
	global_load_lds_dwordx4 v[238:239], off
	s_waitcnt vmcnt(8) lgkmcnt(0)
	s_barrier
	v_mfma_f32_16x16x32_f16 v[66:69], v[152:155], v[206:209], v[66:69]
	v_mfma_f32_16x16x32_f16 v[62:65], v[182:185], v[206:209], v[62:65]
	v_mfma_f32_16x16x32_f16 v[58:61], v[152:155], v[214:217], v[58:61]
	v_mfma_f32_16x16x32_f16 v[54:57], v[182:185], v[214:217], v[54:57]
	v_mfma_f32_16x16x32_f16 v[42:45], v[152:155], v[222:225], v[42:45]
	v_mfma_f32_16x16x32_f16 v[38:41], v[182:185], v[222:225], v[38:41]
	v_mfma_f32_16x16x32_f16 v[26:29], v[152:155], v[230:233], v[26:29]
	v_mfma_f32_16x16x32_f16 v[22:25], v[182:185], v[230:233], v[22:25]
	v_mfma_f32_16x16x32_f16 v[66:69], v[178:181], v[210:213], v[66:69]
	v_mfma_f32_16x16x32_f16 v[62:65], v[186:189], v[210:213], v[62:65]
	v_mfma_f32_16x16x32_f16 v[58:61], v[178:181], v[218:221], v[58:61]
	v_mfma_f32_16x16x32_f16 v[54:57], v[186:189], v[218:221], v[54:57]
	v_mfma_f32_16x16x32_f16 v[42:45], v[178:181], v[226:229], v[42:45]
	v_mfma_f32_16x16x32_f16 v[38:41], v[186:189], v[226:229], v[38:41]
	v_mfma_f32_16x16x32_f16 v[26:29], v[178:181], v[234:237], v[26:29]
	v_mfma_f32_16x16x32_f16 v[22:25], v[186:189], v[234:237], v[22:25]
	v_mfma_f32_16x16x32_f16 v[50:53], v[190:193], v[206:209], v[50:53]
	v_mfma_f32_16x16x32_f16 v[46:49], v[198:201], v[206:209], v[46:49]
	v_mfma_f32_16x16x32_f16 v[34:37], v[190:193], v[214:217], v[34:37]
	v_mfma_f32_16x16x32_f16 v[30:33], v[198:201], v[214:217], v[30:33]
	v_mfma_f32_16x16x32_f16 v[18:21], v[190:193], v[222:225], v[18:21]
	v_mfma_f32_16x16x32_f16 v[14:17], v[198:201], v[222:225], v[14:17]
	v_mfma_f32_16x16x32_f16 v[10:13], v[190:193], v[230:233], v[10:13]
	v_mfma_f32_16x16x32_f16 v[6:9], v[198:201], v[230:233], v[6:9]
	v_mfma_f32_16x16x32_f16 v[50:53], v[194:197], v[210:213], v[50:53]
	v_mfma_f32_16x16x32_f16 v[46:49], v[202:205], v[210:213], v[46:49]
	v_mfma_f32_16x16x32_f16 v[34:37], v[194:197], v[218:221], v[34:37]
	v_mfma_f32_16x16x32_f16 v[30:33], v[202:205], v[218:221], v[30:33]
	v_mfma_f32_16x16x32_f16 v[18:21], v[194:197], v[226:229], v[18:21]
	v_mfma_f32_16x16x32_f16 v[14:17], v[202:205], v[226:229], v[14:17]
	v_mfma_f32_16x16x32_f16 v[10:13], v[194:197], v[234:237], v[10:13]
	v_mfma_f32_16x16x32_f16 v[6:9], v[202:205], v[234:237], v[6:9]
	s_barrier
	s_add_i32 s47, s47, 2
	s_add_u32 s20, s20, 0x100
	s_addc_u32 s21, s21, 0
	s_cmp_gt_u32 s47, 13
.LBB0_386:
	s_add_u32 s22, s45, s20
	s_addc_u32 s23, s46, s21
	s_add_u32 s22, s22, 0x520e100
	s_addc_u32 s23, s23, 0
	s_add_u32 s48, s43, s20
	s_addc_u32 s49, s44, s21
	s_add_i32 s50, 0, 0x10000
	s_cmpk_eq_i32 s20, 0x700
	s_cselect_b32 s27, s41, s23
	s_cselect_b32 s26, s9, s22
	v_add_u32_e32 v177, s50, v148
	s_cselect_b32 s23, s42, s49
	s_cselect_b32 s22, s11, s48
	s_add_i32 s51, 0, 0x14000
	ds_read_b128 v[152:155], v177
	ds_read_b128 v[178:181], v177 offset:1024
	ds_read_b128 v[182:185], v177 offset:2048
	ds_read_b128 v[186:189], v177 offset:3072
	v_add_u32_e32 v177, s51, v148
	ds_read_b128 v[190:193], v177
	ds_read_b128 v[194:197], v177 offset:1024
	ds_read_b128 v[198:201], v177 offset:2048
	ds_read_b128 v[202:205], v177 offset:3072
	v_lshl_add_u64 v[238:239], v[146:147], 0, s[20:21]
	s_add_i32 m0, s13, 0xc000
	ds_read_b128 v[206:209], v151
	ds_read_b128 v[210:213], v151 offset:1024
	ds_read_b128 v[214:217], v151 offset:2048
	ds_read_b128 v[218:221], v151 offset:3072
	ds_read_b128 v[222:225], v151 offset:4096
	ds_read_b128 v[226:229], v151 offset:5120
	ds_read_b128 v[230:233], v151 offset:6144
	ds_read_b128 v[234:237], v151 offset:7168
	global_load_lds_dwordx4 v[238:239], off
	v_lshl_add_u64 v[238:239], v[144:145], 0, s[20:21]
	s_add_i32 m0, s13, 0xe000
	s_nop 0
	global_load_lds_dwordx4 v[238:239], off
	s_waitcnt vmcnt(8) lgkmcnt(0)
	s_barrier
; #define STAGE(bufoff, gbase, voff) do { _Pragma("unroll") for (int _i = 0; _i < 2; ++_i) \
;     __builtin_amdgcn_global_load_lds((const unsigned*)((const char*)(gbase) + (voff)[_i]), (LAS unsigned*)(lds + (bufoff) + ldsw + _i * 8192), 16, 0, 0); } while (0)
; #define LDA(dst, b, h) do { _Pragma("unroll") for (int m = 0; m < 4; ++m) _Pragma("unroll") for (int k = 0; k < 2; ++k) dst[m][k] = *(const LAS half8*)(lds + SA(b, h) + aoff + m * 2048 + k * 1024); } while (0)
; #define LDB(dst, b, h) do { _Pragma("unroll") for (int n = 0; n < 2; ++n) _Pragma("unroll") for (int k = 0; k < 2; ++k) dst[n][k] = *(const LAS half8*)(lds + SB(b, h) + boff + n * 2048 + k * 1024); } while (0)
; #define MMA(ai, bj, At_, Bt_) do { __builtin_amdgcn_s_setprio(1); \
;     _Pragma("unroll") for (int m = 0; m < 4; ++m) _Pragma("unroll") for (int n = 0; n < 2; ++n) _Pragma("unroll") for (int k = 0; k < 2; ++k) \
;       acc[ai][bj][m][n] = MFMA16(Bt_[n][k], At_[m][k], acc[ai][bj][m][n]); \
;     __builtin_amdgcn_s_setprio(0); } while (0)
; #define WAIT_V(n) asm volatile("s_waitcnt vmcnt(" #n ")" ::: "memory")
; #define WAIT_L(n) asm volatile("s_waitcnt lgkmcnt(" #n ")" ::: "memory")
; #define BAR __builtin_amdgcn_s_barrier()
; #define SCHED __builtin_amdgcn_sched_barrier(0)
; template <int EPI>
; DI void gemm_phase(const int wid_s, const h16* __restrict__ A, const h16* __restrict__ Bt, const int N, const int K, const EpiArgs ea) {
;     ...
;       LDB(B0, 0, 0); LDB(B1, 0, 1); SCHED; LDA(At, 0, 0); STAGE(SA(1, 1), a1 + hstep, voffA);
;       WAIT_V(8); WAIT_L(0); BAR; MMA(0, 0, At, B0); MMA(0, 1, At, B1); BAR; SCHED;
;       LDA(At, 0, 1); STAGE(SB(0, 0), b2, voffB); STAGE(SB(0, 1), b2 + hstep, voffB); STAGE(SA(0, 0), a2, voffA);
;       WAIT_V(8); WAIT_L(0); BAR; MMA(1, 0, At, B0); MMA(1, 1, At, B1); BAR; SCHED;
	v_mfma_f32_16x16x32_f16 v[130:133], v[152:155], v[206:209], v[130:133]
	v_mfma_f32_16x16x32_f16 v[126:129], v[182:185], v[206:209], v[126:129]
	v_mfma_f32_16x16x32_f16 v[122:125], v[152:155], v[214:217], v[122:125]
	v_mfma_f32_16x16x32_f16 v[118:121], v[182:185], v[214:217], v[118:121]
	v_mfma_f32_16x16x32_f16 v[106:109], v[152:155], v[222:225], v[106:109]
	v_mfma_f32_16x16x32_f16 v[102:105], v[182:185], v[222:225], v[102:105]
	v_mfma_f32_16x16x32_f16 v[90:93], v[152:155], v[230:233], v[90:93]
	v_mfma_f32_16x16x32_f16 v[86:89], v[182:185], v[230:233], v[86:89]
	v_mfma_f32_16x16x32_f16 v[130:133], v[178:181], v[210:213], v[130:133]
	v_mfma_f32_16x16x32_f16 v[126:129], v[186:189], v[210:213], v[126:129]
	v_mfma_f32_16x16x32_f16 v[122:125], v[178:181], v[218:221], v[122:125]
	v_mfma_f32_16x16x32_f16 v[118:121], v[186:189], v[218:221], v[118:121]
	v_mfma_f32_16x16x32_f16 v[106:109], v[178:181], v[226:229], v[106:109]
	v_mfma_f32_16x16x32_f16 v[102:105], v[186:189], v[226:229], v[102:105]
	v_mfma_f32_16x16x32_f16 v[90:93], v[178:181], v[234:237], v[90:93]
	v_mfma_f32_16x16x32_f16 v[86:89], v[186:189], v[234:237], v[86:89]
	v_mfma_f32_16x16x32_f16 v[114:117], v[190:193], v[206:209], v[114:117]
	v_mfma_f32_16x16x32_f16 v[110:113], v[198:201], v[206:209], v[110:113]
	v_mfma_f32_16x16x32_f16 v[98:101], v[190:193], v[214:217], v[98:101]
	v_mfma_f32_16x16x32_f16 v[94:97], v[198:201], v[214:217], v[94:97]
	v_mfma_f32_16x16x32_f16 v[82:85], v[190:193], v[222:225], v[82:85]
	v_mfma_f32_16x16x32_f16 v[78:81], v[198:201], v[222:225], v[78:81]
	v_mfma_f32_16x16x32_f16 v[74:77], v[190:193], v[230:233], v[74:77]
	v_mfma_f32_16x16x32_f16 v[70:73], v[198:201], v[230:233], v[70:73]
	v_mfma_f32_16x16x32_f16 v[114:117], v[194:197], v[210:213], v[114:117]
	v_mfma_f32_16x16x32_f16 v[110:113], v[202:205], v[210:213], v[110:113]
	v_mfma_f32_16x16x32_f16 v[98:101], v[194:197], v[218:221], v[98:101]
	v_mfma_f32_16x16x32_f16 v[94:97], v[202:205], v[218:221], v[94:97]
	v_mfma_f32_16x16x32_f16 v[82:85], v[194:197], v[226:229], v[82:85]
	v_mfma_f32_16x16x32_f16 v[78:81], v[202:205], v[226:229], v[78:81]
	v_mfma_f32_16x16x32_f16 v[74:77], v[194:197], v[234:237], v[74:77]
	v_mfma_f32_16x16x32_f16 v[70:73], v[202:205], v[234:237], v[70:73]
	s_barrier
	s_add_i32 s48, s50, s30
	v_lshl_add_u64 v[238:239], s[22:23], 0, v[0:1]
	s_mov_b32 m0, s48
	ds_read_b128 v[206:209], v151 offset:16384
	ds_read_b128 v[210:213], v151 offset:17408
	ds_read_b128 v[214:217], v151 offset:18432
	ds_read_b128 v[218:221], v151 offset:19456
	ds_read_b128 v[222:225], v151 offset:20480
	ds_read_b128 v[226:229], v151 offset:21504
	ds_read_b128 v[230:233], v151 offset:22528
	ds_read_b128 v[234:237], v151 offset:23552
	global_load_lds_dwordx4 v[238:239], off
	s_add_i32 m0, s48, 0x2000
	s_add_u32 s48, s22, 0x40000
	v_lshl_add_u64 v[240:241], s[22:23], 0, v[2:3]
	s_addc_u32 s49, s23, 0
	s_add_i32 s50, s51, s30
	global_load_lds_dwordx4 v[240:241], off
	v_lshl_add_u64 v[242:243], s[48:49], 0, v[0:1]
	s_mov_b32 m0, s50
	v_lshl_add_u64 v[244:245], s[26:27], 0, v[134:135]
	global_load_lds_dwordx4 v[242:243], off
	v_lshl_add_u64 v[242:243], s[48:49], 0, v[2:3]
	s_add_i32 m0, s50, 0x2000
	s_nop 0
	global_load_lds_dwordx4 v[242:243], off
	v_lshl_add_u64 v[242:243], s[26:27], 0, v[138:139]
	s_mov_b32 m0, s13
	s_nop 0
	global_load_lds_dwordx4 v[242:243], off
	s_mov_b32 m0, s15
	s_nop 0
	global_load_lds_dwordx4 v[244:245], off
	s_waitcnt vmcnt(8) lgkmcnt(0)
	s_barrier
	v_mfma_f32_16x16x32_f16 v[66:69], v[152:155], v[206:209], v[66:69]
	v_mfma_f32_16x16x32_f16 v[62:65], v[182:185], v[206:209], v[62:65]
	v_mfma_f32_16x16x32_f16 v[58:61], v[152:155], v[214:217], v[58:61]
	v_mfma_f32_16x16x32_f16 v[54:57], v[182:185], v[214:217], v[54:57]
	v_mfma_f32_16x16x32_f16 v[42:45], v[152:155], v[222:225], v[42:45]
	v_mfma_f32_16x16x32_f16 v[38:41], v[182:185], v[222:225], v[38:41]
	v_mfma_f32_16x16x32_f16 v[26:29], v[152:155], v[230:233], v[26:29]
	v_mfma_f32_16x16x32_f16 v[22:25], v[182:185], v[230:233], v[22:25]
	v_mfma_f32_16x16x32_f16 v[66:69], v[178:181], v[210:213], v[66:69]
	v_mfma_f32_16x16x32_f16 v[62:65], v[186:189], v[210:213], v[62:65]
	v_mfma_f32_16x16x32_f16 v[58:61], v[178:181], v[218:221], v[58:61]
	v_mfma_f32_16x16x32_f16 v[54:57], v[186:189], v[218:221], v[54:57]
	v_mfma_f32_16x16x32_f16 v[42:45], v[178:181], v[226:229], v[42:45]
	v_mfma_f32_16x16x32_f16 v[38:41], v[186:189], v[226:229], v[38:41]
	v_mfma_f32_16x16x32_f16 v[26:29], v[178:181], v[234:237], v[26:29]
	v_mfma_f32_16x16x32_f16 v[22:25], v[186:189], v[234:237], v[22:25]
	v_mfma_f32_16x16x32_f16 v[50:53], v[190:193], v[206:209], v[50:53]
	v_mfma_f32_16x16x32_f16 v[46:49], v[198:201], v[206:209], v[46:49]
	v_mfma_f32_16x16x32_f16 v[34:37], v[190:193], v[214:217], v[34:37]
	v_mfma_f32_16x16x32_f16 v[30:33], v[198:201], v[214:217], v[30:33]
	v_mfma_f32_16x16x32_f16 v[18:21], v[190:193], v[222:225], v[18:21]
	v_mfma_f32_16x16x32_f16 v[14:17], v[198:201], v[222:225], v[14:17]
	v_mfma_f32_16x16x32_f16 v[10:13], v[190:193], v[230:233], v[10:13]
	v_mfma_f32_16x16x32_f16 v[6:9], v[198:201], v[230:233], v[6:9]
	v_mfma_f32_16x16x32_f16 v[50:53], v[194:197], v[210:213], v[50:53]
	v_mfma_f32_16x16x32_f16 v[46:49], v[202:205], v[210:213], v[46:49]
	v_mfma_f32_16x16x32_f16 v[34:37], v[194:197], v[218:221], v[34:37]
	v_mfma_f32_16x16x32_f16 v[30:33], v[202:205], v[218:221], v[30:33]
	v_mfma_f32_16x16x32_f16 v[18:21], v[194:197], v[226:229], v[18:21]
	v_mfma_f32_16x16x32_f16 v[14:17], v[202:205], v[226:229], v[14:17]
	v_mfma_f32_16x16x32_f16 v[10:13], v[194:197], v[234:237], v[10:13]
	v_mfma_f32_16x16x32_f16 v[6:9], v[202:205], v[234:237], v[6:9]
	s_barrier
; #define STAGE(bufoff, gbase, voff) do { _Pragma("unroll") for (int _i = 0; _i < 2; ++_i) \
;     __builtin_amdgcn_global_load_lds((const unsigned*)((const char*)(gbase) + (voff)[_i]), (LAS unsigned*)(lds + (bufoff) + ldsw + _i * 8192), 16, 0, 0); } while (0)
; #define LDA(dst, b, h) do { _Pragma("unroll") for (int m = 0; m < 4; ++m) _Pragma("unroll") for (int k = 0; k < 2; ++k) dst[m][k] = *(const LAS half8*)(lds + SA(b, h) + aoff + m * 2048 + k * 1024); } while (0)
; #define LDB(dst, b, h) do { _Pragma("unroll") for (int n = 0; n < 2; ++n) _Pragma("unroll") for (int k = 0; k < 2; ++k) dst[n][k] = *(const LAS half8*)(lds + SB(b, h) + boff + n * 2048 + k * 1024); } while (0)
; #define MMA(ai, bj, At_, Bt_) do { __builtin_amdgcn_s_setprio(1); \
;     _Pragma("unroll") for (int m = 0; m < 4; ++m) _Pragma("unroll") for (int n = 0; n < 2; ++n) _Pragma("unroll") for (int k = 0; k < 2; ++k) \
;       acc[ai][bj][m][n] = MFMA16(Bt_[n][k], At_[m][k], acc[ai][bj][m][n]); \
;     __builtin_amdgcn_s_setprio(0); } while (0)
; #define WAIT_V(n) asm volatile("s_waitcnt vmcnt(" #n ")" ::: "memory")
; #define WAIT_L(n) asm volatile("s_waitcnt lgkmcnt(" #n ")" ::: "memory")
; #define BAR __builtin_amdgcn_s_barrier()
; #define SCHED __builtin_amdgcn_sched_barrier(0)
; template <int EPI>
; DI void gemm_phase(const int wid_s, const h16* __restrict__ A, const h16* __restrict__ Bt, const int N, const int K, const EpiArgs ea) {
;     ...
;       LDB(B0, 1, 0); LDB(B1, 1, 1); SCHED; LDA(At, 1, 0); STAGE(SA(0, 1), a2 + hstep, voffA);
;       WAIT_V(8); WAIT_L(0); BAR; MMA(0, 0, At, B0); MMA(0, 1, At, B1); BAR; SCHED;
;       LDA(At, 1, 1); STAGE(SB(1, 0), b3, voffB); STAGE(SB(1, 1), b3 + hstep, voffB); STAGE(SA(1, 0), a3, voffA);
;       WAIT_V(8); WAIT_L(0); BAR; MMA(1, 0, At, B0); MMA(1, 1, At, B1); BAR; SCHED;
;     }
;     if (wr == 0) BAR;
	s_add_i32 s48, 0, 0x18000
	v_add_u32_e32 v177, s48, v148
	s_add_i32 s49, 0, 0x1c000
	ds_read_b128 v[152:155], v177
	ds_read_b128 v[178:181], v177 offset:1024
	ds_read_b128 v[182:185], v177 offset:2048
	ds_read_b128 v[186:189], v177 offset:3072
	v_add_u32_e32 v177, s49, v148
	ds_read_b128 v[190:193], v177
	ds_read_b128 v[194:197], v177 offset:1024
	ds_read_b128 v[198:201], v177 offset:2048
	ds_read_b128 v[202:205], v177 offset:3072
	s_add_u32 s26, s26, 0x40000
	s_addc_u32 s27, s27, 0
	s_mov_b32 m0, s31
	v_lshl_add_u64 v[246:247], s[26:27], 0, v[138:139]
	ds_read_b128 v[206:209], v151 offset:32768
	ds_read_b128 v[210:213], v151 offset:33792
	ds_read_b128 v[214:217], v151 offset:34816
	ds_read_b128 v[218:221], v151 offset:35840
	ds_read_b128 v[222:225], v151 offset:36864
	ds_read_b128 v[226:229], v151 offset:37888
	ds_read_b128 v[230:233], v151 offset:38912
	ds_read_b128 v[234:237], v151 offset:39936
	global_load_lds_dwordx4 v[246:247], off
	v_lshl_add_u64 v[246:247], s[26:27], 0, v[134:135]
	s_mov_b32 m0, s38
	s_nop 0
	global_load_lds_dwordx4 v[246:247], off
	s_waitcnt vmcnt(8) lgkmcnt(0)
	s_barrier
	v_mfma_f32_16x16x32_f16 v[130:133], v[152:155], v[206:209], v[130:133]
	v_mfma_f32_16x16x32_f16 v[126:129], v[182:185], v[206:209], v[126:129]
	v_mfma_f32_16x16x32_f16 v[122:125], v[152:155], v[214:217], v[122:125]
	v_mfma_f32_16x16x32_f16 v[118:121], v[182:185], v[214:217], v[118:121]
	v_mfma_f32_16x16x32_f16 v[106:109], v[152:155], v[222:225], v[106:109]
	v_mfma_f32_16x16x32_f16 v[102:105], v[182:185], v[222:225], v[102:105]
	v_mfma_f32_16x16x32_f16 v[90:93], v[152:155], v[230:233], v[90:93]
	v_mfma_f32_16x16x32_f16 v[86:89], v[182:185], v[230:233], v[86:89]
	v_mfma_f32_16x16x32_f16 v[130:133], v[178:181], v[210:213], v[130:133]
	v_mfma_f32_16x16x32_f16 v[126:129], v[186:189], v[210:213], v[126:129]
	v_mfma_f32_16x16x32_f16 v[122:125], v[178:181], v[218:221], v[122:125]
	v_mfma_f32_16x16x32_f16 v[118:121], v[186:189], v[218:221], v[118:121]
	v_mfma_f32_16x16x32_f16 v[106:109], v[178:181], v[226:229], v[106:109]
	v_mfma_f32_16x16x32_f16 v[102:105], v[186:189], v[226:229], v[102:105]
	v_mfma_f32_16x16x32_f16 v[90:93], v[178:181], v[234:237], v[90:93]
	v_mfma_f32_16x16x32_f16 v[86:89], v[186:189], v[234:237], v[86:89]
	v_mfma_f32_16x16x32_f16 v[114:117], v[190:193], v[206:209], v[114:117]
	v_mfma_f32_16x16x32_f16 v[110:113], v[198:201], v[206:209], v[110:113]
	v_mfma_f32_16x16x32_f16 v[98:101], v[190:193], v[214:217], v[98:101]
	v_mfma_f32_16x16x32_f16 v[94:97], v[198:201], v[214:217], v[94:97]
	v_mfma_f32_16x16x32_f16 v[82:85], v[190:193], v[222:225], v[82:85]
	v_mfma_f32_16x16x32_f16 v[78:81], v[198:201], v[222:225], v[78:81]
	v_mfma_f32_16x16x32_f16 v[74:77], v[190:193], v[230:233], v[74:77]
	v_mfma_f32_16x16x32_f16 v[70:73], v[198:201], v[230:233], v[70:73]
	v_mfma_f32_16x16x32_f16 v[114:117], v[194:197], v[210:213], v[114:117]
	v_mfma_f32_16x16x32_f16 v[110:113], v[202:205], v[210:213], v[110:113]
	v_mfma_f32_16x16x32_f16 v[98:101], v[194:197], v[218:221], v[98:101]
	v_mfma_f32_16x16x32_f16 v[94:97], v[202:205], v[218:221], v[94:97]
	v_mfma_f32_16x16x32_f16 v[82:85], v[194:197], v[226:229], v[82:85]
	v_mfma_f32_16x16x32_f16 v[78:81], v[202:205], v[226:229], v[78:81]
	v_mfma_f32_16x16x32_f16 v[74:77], v[194:197], v[234:237], v[74:77]
	v_mfma_f32_16x16x32_f16 v[70:73], v[202:205], v[234:237], v[70:73]
	s_barrier
	s_add_i32 s26, s48, s30
	v_lshl_add_u64 v[238:239], v[238:239], 0, s[36:37]
	s_mov_b32 m0, s26
	ds_read_b128 v[206:209], v151 offset:49152
	ds_read_b128 v[210:213], v151 offset:50176
	ds_read_b128 v[214:217], v151 offset:51200
	ds_read_b128 v[218:221], v151 offset:52224
	ds_read_b128 v[222:225], v151 offset:53248
	ds_read_b128 v[226:229], v151 offset:54272
	ds_read_b128 v[230:233], v151 offset:55296
	ds_read_b128 v[234:237], v151 offset:56320
	global_load_lds_dwordx4 v[238:239], off
	s_add_i32 m0, s26, 0x2000
	s_add_u32 s22, s22, 0x40080
	v_lshl_add_u64 v[238:239], v[240:241], 0, s[36:37]
	s_addc_u32 s23, s23, 0
	s_add_i32 s26, s49, s30
	global_load_lds_dwordx4 v[238:239], off
	v_lshl_add_u64 v[238:239], s[22:23], 0, v[0:1]
	s_mov_b32 m0, s26
	s_nop 0
	global_load_lds_dwordx4 v[238:239], off
	v_lshl_add_u64 v[238:239], s[22:23], 0, v[2:3]
	s_add_i32 m0, s26, 0x2000
	s_nop 0
	global_load_lds_dwordx4 v[238:239], off
	v_lshl_add_u64 v[238:239], v[242:243], 0, s[36:37]
	s_mov_b32 m0, s39
	s_nop 0
	global_load_lds_dwordx4 v[238:239], off
	v_lshl_add_u64 v[238:239], v[244:245], 0, s[36:37]
	s_mov_b32 m0, s40
	s_nop 0
	global_load_lds_dwordx4 v[238:239], off
	s_waitcnt vmcnt(8) lgkmcnt(0)
	s_barrier
	v_mfma_f32_16x16x32_f16 v[66:69], v[152:155], v[206:209], v[66:69]
	v_mfma_f32_16x16x32_f16 v[62:65], v[182:185], v[206:209], v[62:65]
	v_mfma_f32_16x16x32_f16 v[58:61], v[152:155], v[214:217], v[58:61]
	v_mfma_f32_16x16x32_f16 v[54:57], v[182:185], v[214:217], v[54:57]
	v_mfma_f32_16x16x32_f16 v[42:45], v[152:155], v[222:225], v[42:45]
	v_mfma_f32_16x16x32_f16 v[38:41], v[182:185], v[222:225], v[38:41]
	v_mfma_f32_16x16x32_f16 v[26:29], v[152:155], v[230:233], v[26:29]
	v_mfma_f32_16x16x32_f16 v[22:25], v[182:185], v[230:233], v[22:25]
	v_mfma_f32_16x16x32_f16 v[66:69], v[178:181], v[210:213], v[66:69]
	v_mfma_f32_16x16x32_f16 v[62:65], v[186:189], v[210:213], v[62:65]
	v_mfma_f32_16x16x32_f16 v[58:61], v[178:181], v[218:221], v[58:61]
	v_mfma_f32_16x16x32_f16 v[54:57], v[186:189], v[218:221], v[54:57]
	v_mfma_f32_16x16x32_f16 v[42:45], v[178:181], v[226:229], v[42:45]
	v_mfma_f32_16x16x32_f16 v[38:41], v[186:189], v[226:229], v[38:41]
	v_mfma_f32_16x16x32_f16 v[26:29], v[178:181], v[234:237], v[26:29]
	v_mfma_f32_16x16x32_f16 v[22:25], v[186:189], v[234:237], v[22:25]
	v_mfma_f32_16x16x32_f16 v[50:53], v[190:193], v[206:209], v[50:53]
	v_mfma_f32_16x16x32_f16 v[46:49], v[198:201], v[206:209], v[46:49]
	v_mfma_f32_16x16x32_f16 v[34:37], v[190:193], v[214:217], v[34:37]
	v_mfma_f32_16x16x32_f16 v[30:33], v[198:201], v[214:217], v[30:33]
	v_mfma_f32_16x16x32_f16 v[18:21], v[190:193], v[222:225], v[18:21]
	v_mfma_f32_16x16x32_f16 v[14:17], v[198:201], v[222:225], v[14:17]
	v_mfma_f32_16x16x32_f16 v[10:13], v[190:193], v[230:233], v[10:13]
	v_mfma_f32_16x16x32_f16 v[6:9], v[198:201], v[230:233], v[6:9]
	v_mfma_f32_16x16x32_f16 v[50:53], v[194:197], v[210:213], v[50:53]
	v_mfma_f32_16x16x32_f16 v[46:49], v[202:205], v[210:213], v[46:49]
	v_mfma_f32_16x16x32_f16 v[34:37], v[194:197], v[218:221], v[34:37]
	v_mfma_f32_16x16x32_f16 v[30:33], v[202:205], v[218:221], v[30:33]
	v_mfma_f32_16x16x32_f16 v[18:21], v[194:197], v[226:229], v[18:21]
	v_mfma_f32_16x16x32_f16 v[14:17], v[202:205], v[226:229], v[14:17]
	v_mfma_f32_16x16x32_f16 v[10:13], v[194:197], v[234:237], v[10:13]
	v_mfma_f32_16x16x32_f16 v[6:9], v[202:205], v[234:237], v[6:9]
	s_barrier
	s_add_i32 s47, s47, 2
	s_add_u32 s20, s20, 0x100
	s_addc_u32 s21, s21, 0
	s_cmp_gt_u32 s47, 13
	s_cbranch_scc0 .LBB0_386
	s_and_b64 vcc, exec, s[4:5]
	s_cbranch_vccz .LBB0_389
	s_barrier
